# K-loop LDS-DMA uses SGPR base + 32-bit VGPR offset (saddr form), drops 146 v_lshl_add_u64
# speedup vs baseline: 1.0055x; 1.0055x over previous
; #define PG8_STAGE(bufoff, gbase, voff) do { _Pragma("unroll") for (int _i = 0; _i < 2; ++_i) \
;         __builtin_amdgcn_global_load_lds((const unsigned*)((const char*)(gbase) + (voff)[_i]), (LAS unsigned*)(lds + (bufoff) + ldsw + _i * 8192), 16, 0, 0); } while (0)
; #define PG8_LDA(dst, b, h) do { _Pragma("unroll") for (int m = 0; m < 4; ++m) _Pragma("unroll") for (int k = 0; k < 2; ++k) dst[m][k] = *(const LAS bf16x8*)(lds + PG8_SA(b, h) + aoff + m * 2048 + k * 1024); } while (0)
; #define PG8_LDB(dst, b, h) do { _Pragma("unroll") for (int n = 0; n < 2; ++n) _Pragma("unroll") for (int k = 0; k < 2; ++k) dst[n][k] = *(const LAS bf16x8*)(lds + PG8_SB(b, h) + boff + n * 2048 + k * 1024); } while (0)
; #define PG8_MMA(ai, bj, At, Bt) do { __builtin_amdgcn_s_setprio(1); _Pragma("unroll") for (int m = 0; m < 4; ++m) _Pragma("unroll") for (int n = 0; n < 2; ++n) _Pragma("unroll") for (int k = 0; k < 2; ++k) \
;         acc[ai][bj][m][n] = __builtin_amdgcn_mfma_f32_16x16x32_bf16(Bt[n][k], At[m][k], acc[ai][bj][m][n], 0, 0, 0); __builtin_amdgcn_s_setprio(0); } while (0)
; #define PG8_WAIT_V(n) asm volatile("s_waitcnt vmcnt(" #n ")" ::: "memory")
; #define PG8_WAIT_L(n) asm volatile("s_waitcnt lgkmcnt(" #n ")" ::: "memory")
; #define PG8_BAR __builtin_amdgcn_s_barrier()
; #define PG8_SCHED __builtin_amdgcn_sched_barrier(0)
; template <class Epi, class Sched, bool ALIGN_EPI>
; __device__ __forceinline__ void gemm_phase(LAS unsigned char* lds, const Gemm g, const Sched& S, const Epi& E, const int wid) {
;     ...
;             PG8_LDB(B0, 0, 0); PG8_LDB(B1, 0, 1); PG8_SCHED; PG8_LDA(At, 0, 0); PG8_STAGE(PG8_SA(1, 1), a1 + hstepA, voffA);
;             PG8_WAIT_V(8); PG8_WAIT_L(0); PG8_BAR; PG8_MMA(0, 0, At, B0); PG8_MMA(0, 1, At, B1); PG8_BAR; PG8_SCHED;
;             PG8_LDA(At, 0, 1); PG8_STAGE(PG8_SB(0, 0), b2, voffB); PG8_STAGE(PG8_SB(0, 1), b2 + hstepB, voffB); PG8_STAGE(PG8_SA(0, 0), a2, voffA);
;             PG8_WAIT_V(8); PG8_WAIT_L(0); PG8_BAR; PG8_MMA(1, 0, At, B0); PG8_MMA(1, 1, At, B1); PG8_BAR; PG8_SCHED;
.LBB0_166:
	ds_read_b128 v[152:155], v149
	ds_read_b128 v[156:159], v149 offset:1024
	ds_read_b128 v[160:163], v149 offset:2048
	ds_read_b128 v[164:167], v149 offset:3072
	ds_read_b128 v[168:171], v150
	ds_read_b128 v[172:175], v150 offset:1024
	ds_read_b128 v[176:179], v150 offset:2048
	ds_read_b128 v[180:183], v150 offset:3072
	s_add_u32 s26, s24, 0x4000
	s_addc_u32 s27, s25, 0
	s_cmp_eq_u32 s66, 60
	s_cselect_b32 s50, s35, s26
	s_cselect_b32 s51, s17, s27
	s_cselect_b32 s48, s63, s64
	s_cselect_b32 s49, s15, s65
	s_add_u32 s26, s50, 0x8000
	s_addc_u32 s27, s51, 0
	s_add_i32 m0, s47, 0xc000
	ds_read_b128 v[184:187], v151
	ds_read_b128 v[188:191], v151 offset:1024
	ds_read_b128 v[192:195], v151 offset:2048
	ds_read_b128 v[196:199], v151 offset:3072
	ds_read_b128 v[200:203], v151 offset:4096
	ds_read_b128 v[204:207], v151 offset:5120
	ds_read_b128 v[208:211], v151 offset:6144
	ds_read_b128 v[212:215], v151 offset:7168
	global_load_lds_dwordx4 v138, s[24:25]
	s_add_i32 m0, s47, 0xe000
	s_nop 0
	global_load_lds_dwordx4 v140, s[24:25]
	s_waitcnt vmcnt(8)
	s_waitcnt lgkmcnt(0)
	s_barrier
	s_setprio 1
	s_waitcnt lgkmcnt(0)
	v_mfma_f32_16x16x32_bf16 v[124:127], v[152:155], v[184:187], v[124:127]
	v_mfma_f32_16x16x32_bf16 v[120:123], v[160:163], v[184:187], v[120:123]
	v_mfma_f32_16x16x32_bf16 v[108:111], v[152:155], v[192:195], v[108:111]
	v_mfma_f32_16x16x32_bf16 v[104:107], v[160:163], v[192:195], v[104:107]
	v_mfma_f32_16x16x32_bf16 v[92:95], v[152:155], v[200:203], v[92:95]
	v_mfma_f32_16x16x32_bf16 v[88:91], v[160:163], v[200:203], v[88:91]
	v_mfma_f32_16x16x32_bf16 v[76:79], v[152:155], v[208:211], v[76:79]
	v_mfma_f32_16x16x32_bf16 v[72:75], v[160:163], v[208:211], v[72:75]
	v_mfma_f32_16x16x32_bf16 v[124:127], v[156:159], v[188:191], v[124:127]
	v_mfma_f32_16x16x32_bf16 v[120:123], v[164:167], v[188:191], v[120:123]
	v_mfma_f32_16x16x32_bf16 v[108:111], v[156:159], v[196:199], v[108:111]
	v_mfma_f32_16x16x32_bf16 v[104:107], v[164:167], v[196:199], v[104:107]
	v_mfma_f32_16x16x32_bf16 v[92:95], v[156:159], v[204:207], v[92:95]
	v_mfma_f32_16x16x32_bf16 v[88:91], v[164:167], v[204:207], v[88:91]
	v_mfma_f32_16x16x32_bf16 v[76:79], v[156:159], v[212:215], v[76:79]
	v_mfma_f32_16x16x32_bf16 v[72:75], v[164:167], v[212:215], v[72:75]
	s_setprio 0
	s_setprio 1
	v_mfma_f32_16x16x32_bf16 v[116:119], v[168:171], v[184:187], v[116:119]
	v_mfma_f32_16x16x32_bf16 v[112:115], v[176:179], v[184:187], v[112:115]
	v_mfma_f32_16x16x32_bf16 v[100:103], v[168:171], v[192:195], v[100:103]
	v_mfma_f32_16x16x32_bf16 v[96:99], v[176:179], v[192:195], v[96:99]
	v_mfma_f32_16x16x32_bf16 v[84:87], v[168:171], v[200:203], v[84:87]
	v_mfma_f32_16x16x32_bf16 v[80:83], v[176:179], v[200:203], v[80:83]
	v_mfma_f32_16x16x32_bf16 v[68:71], v[168:171], v[208:211], v[68:71]
	v_mfma_f32_16x16x32_bf16 v[64:67], v[176:179], v[208:211], v[64:67]
	v_mfma_f32_16x16x32_bf16 v[116:119], v[172:175], v[188:191], v[116:119]
	v_mfma_f32_16x16x32_bf16 v[112:115], v[180:183], v[188:191], v[112:115]
	v_mfma_f32_16x16x32_bf16 v[100:103], v[172:175], v[196:199], v[100:103]
	v_mfma_f32_16x16x32_bf16 v[96:99], v[180:183], v[196:199], v[96:99]
	v_mfma_f32_16x16x32_bf16 v[84:87], v[172:175], v[204:207], v[84:87]
	v_mfma_f32_16x16x32_bf16 v[80:83], v[180:183], v[204:207], v[80:83]
	v_mfma_f32_16x16x32_bf16 v[68:71], v[172:175], v[212:215], v[68:71]
	v_mfma_f32_16x16x32_bf16 v[64:67], v[180:183], v[212:215], v[64:67]
	s_setprio 0
	s_barrier
	s_add_i32 s38, s61, s3
	s_mov_b32 m0, s38
	ds_read_b128 v[184:187], v151 offset:16384
	ds_read_b128 v[188:191], v151 offset:17408
	ds_read_b128 v[192:195], v151 offset:18432
	ds_read_b128 v[196:199], v151 offset:19456
	ds_read_b128 v[200:203], v151 offset:20480
	ds_read_b128 v[204:207], v151 offset:21504
	ds_read_b128 v[208:211], v151 offset:22528
	ds_read_b128 v[212:215], v151 offset:23552
	global_load_lds_dwordx4 v132, s[48:49]
	s_add_i32 m0, s38, 0x2000
	s_add_u32 s68, s48, 0x1000
	s_addc_u32 s69, s49, 0
	s_add_i32 s38, s62, s3
	global_load_lds_dwordx4 v128, s[48:49]
	s_mov_b32 m0, s38
	s_nop 0
	global_load_lds_dwordx4 v132, s[68:69]
	s_add_i32 m0, s38, 0x2000
	s_nop 0
	global_load_lds_dwordx4 v128, s[68:69]
	s_mov_b32 m0, s47
	s_nop 0
	global_load_lds_dwordx4 v134, s[50:51]
	s_mov_b32 m0, s52
	s_nop 0
	global_load_lds_dwordx4 v130, s[50:51]
	s_waitcnt vmcnt(8)
	s_waitcnt lgkmcnt(0)
	s_barrier
	s_setprio 1
	s_waitcnt lgkmcnt(0)
	v_mfma_f32_16x16x32_bf16 v[60:63], v[152:155], v[184:187], v[60:63]
	v_mfma_f32_16x16x32_bf16 v[56:59], v[160:163], v[184:187], v[56:59]
	v_mfma_f32_16x16x32_bf16 v[44:47], v[152:155], v[192:195], v[44:47]
	v_mfma_f32_16x16x32_bf16 v[40:43], v[160:163], v[192:195], v[40:43]
	v_mfma_f32_16x16x32_bf16 v[28:31], v[152:155], v[200:203], v[28:31]
	v_mfma_f32_16x16x32_bf16 v[24:27], v[160:163], v[200:203], v[24:27]
	v_mfma_f32_16x16x32_bf16 v[12:15], v[152:155], v[208:211], v[12:15]
	v_mfma_f32_16x16x32_bf16 v[8:11], v[160:163], v[208:211], v[8:11]
	v_mfma_f32_16x16x32_bf16 v[60:63], v[156:159], v[188:191], v[60:63]
	v_mfma_f32_16x16x32_bf16 v[56:59], v[164:167], v[188:191], v[56:59]
	v_mfma_f32_16x16x32_bf16 v[44:47], v[156:159], v[196:199], v[44:47]
	v_mfma_f32_16x16x32_bf16 v[40:43], v[164:167], v[196:199], v[40:43]
	v_mfma_f32_16x16x32_bf16 v[28:31], v[156:159], v[204:207], v[28:31]
	v_mfma_f32_16x16x32_bf16 v[24:27], v[164:167], v[204:207], v[24:27]
	v_mfma_f32_16x16x32_bf16 v[12:15], v[156:159], v[212:215], v[12:15]
	v_mfma_f32_16x16x32_bf16 v[8:11], v[164:167], v[212:215], v[8:11]
	s_setprio 0
	s_setprio 1
	v_mfma_f32_16x16x32_bf16 v[52:55], v[168:171], v[184:187], v[52:55]
	v_mfma_f32_16x16x32_bf16 v[48:51], v[176:179], v[184:187], v[48:51]
	v_mfma_f32_16x16x32_bf16 v[36:39], v[168:171], v[192:195], v[36:39]
	v_mfma_f32_16x16x32_bf16 v[32:35], v[176:179], v[192:195], v[32:35]
	v_mfma_f32_16x16x32_bf16 v[20:23], v[168:171], v[200:203], v[20:23]
	v_mfma_f32_16x16x32_bf16 v[16:19], v[176:179], v[200:203], v[16:19]
	v_mfma_f32_16x16x32_bf16 v[4:7], v[168:171], v[208:211], v[4:7]
	v_mfma_f32_16x16x32_bf16 v[0:3], v[176:179], v[208:211], v[0:3]
	v_mfma_f32_16x16x32_bf16 v[52:55], v[172:175], v[188:191], v[52:55]
	v_mfma_f32_16x16x32_bf16 v[48:51], v[180:183], v[188:191], v[48:51]
	v_mfma_f32_16x16x32_bf16 v[36:39], v[172:175], v[196:199], v[36:39]
	v_mfma_f32_16x16x32_bf16 v[32:35], v[180:183], v[196:199], v[32:35]
	v_mfma_f32_16x16x32_bf16 v[20:23], v[172:175], v[204:207], v[20:23]
	v_mfma_f32_16x16x32_bf16 v[16:19], v[180:183], v[204:207], v[16:19]
	v_mfma_f32_16x16x32_bf16 v[4:7], v[172:175], v[212:215], v[4:7]
	v_mfma_f32_16x16x32_bf16 v[0:3], v[180:183], v[212:215], v[0:3]
	s_setprio 0
	s_barrier
; #define PG8_STAGE(bufoff, gbase, voff) do { _Pragma("unroll") for (int _i = 0; _i < 2; ++_i) \
;         __builtin_amdgcn_global_load_lds((const unsigned*)((const char*)(gbase) + (voff)[_i]), (LAS unsigned*)(lds + (bufoff) + ldsw + _i * 8192), 16, 0, 0); } while (0)
; #define PG8_LDA(dst, b, h) do { _Pragma("unroll") for (int m = 0; m < 4; ++m) _Pragma("unroll") for (int k = 0; k < 2; ++k) dst[m][k] = *(const LAS bf16x8*)(lds + PG8_SA(b, h) + aoff + m * 2048 + k * 1024); } while (0)
; #define PG8_LDB(dst, b, h) do { _Pragma("unroll") for (int n = 0; n < 2; ++n) _Pragma("unroll") for (int k = 0; k < 2; ++k) dst[n][k] = *(const LAS bf16x8*)(lds + PG8_SB(b, h) + boff + n * 2048 + k * 1024); } while (0)
; #define PG8_MMA(ai, bj, At, Bt) do { __builtin_amdgcn_s_setprio(1); _Pragma("unroll") for (int m = 0; m < 4; ++m) _Pragma("unroll") for (int n = 0; n < 2; ++n) _Pragma("unroll") for (int k = 0; k < 2; ++k) \
;         acc[ai][bj][m][n] = __builtin_amdgcn_mfma_f32_16x16x32_bf16(Bt[n][k], At[m][k], acc[ai][bj][m][n], 0, 0, 0); __builtin_amdgcn_s_setprio(0); } while (0)
; #define PG8_WAIT_V(n) asm volatile("s_waitcnt vmcnt(" #n ")" ::: "memory")
; #define PG8_WAIT_L(n) asm volatile("s_waitcnt lgkmcnt(" #n ")" ::: "memory")
; #define PG8_BAR __builtin_amdgcn_s_barrier()
; #define PG8_SCHED __builtin_amdgcn_sched_barrier(0)
; template <class Epi, class Sched, bool ALIGN_EPI>
; __device__ __forceinline__ void gemm_phase(LAS unsigned char* lds, const Gemm g, const Sched& S, const Epi& E, const int wid) {
;     ...
;             PG8_LDB(B0, 1, 0); PG8_LDB(B1, 1, 1); PG8_SCHED; PG8_LDA(At, 1, 0); PG8_STAGE(PG8_SA(0, 1), a2 + hstepA, voffA);
;             PG8_WAIT_V(8); PG8_WAIT_L(0); PG8_BAR; PG8_MMA(0, 0, At, B0); PG8_MMA(0, 1, At, B1); PG8_BAR; PG8_SCHED;
;             PG8_LDA(At, 1, 1); PG8_STAGE(PG8_SB(1, 0), b3, voffB); PG8_STAGE(PG8_SB(1, 1), b3 + hstepB, voffB); PG8_STAGE(PG8_SA(1, 0), a3, voffA);
;             PG8_WAIT_V(8); PG8_WAIT_L(0); PG8_BAR; PG8_MMA(1, 0, At, B0); PG8_MMA(1, 1, At, B1); PG8_BAR; PG8_SCHED;
;         }
;         if constexpr (ALIGN_EPI) { if (wr == 0) PG8_BAR; }
	s_add_i32 s38, 0, 0x18000
	v_add_u32_e32 v136, s38, v146
	s_add_i32 s39, 0, 0x1c000
	ds_read_b128 v[152:155], v136
	ds_read_b128 v[156:159], v136 offset:1024
	ds_read_b128 v[160:163], v136 offset:2048
	ds_read_b128 v[164:167], v136 offset:3072
	v_add_u32_e32 v136, s39, v146
	ds_read_b128 v[168:171], v136
	ds_read_b128 v[172:175], v136 offset:1024
	ds_read_b128 v[176:179], v136 offset:2048
	ds_read_b128 v[180:183], v136 offset:3072
	s_add_u32 s50, s50, 0x4000
	s_addc_u32 s51, s51, 0
	s_mov_b32 m0, s53
	ds_read_b128 v[184:187], v151 offset:32768
	ds_read_b128 v[188:191], v151 offset:33792
	ds_read_b128 v[192:195], v151 offset:34816
	ds_read_b128 v[196:199], v151 offset:35840
	ds_read_b128 v[200:203], v151 offset:36864
	ds_read_b128 v[204:207], v151 offset:37888
	ds_read_b128 v[208:211], v151 offset:38912
	ds_read_b128 v[212:215], v151 offset:39936
	global_load_lds_dwordx4 v134, s[50:51]
	s_mov_b32 m0, s54
	s_nop 0
	global_load_lds_dwordx4 v130, s[50:51]
	s_waitcnt vmcnt(8)
	s_waitcnt lgkmcnt(0)
	s_barrier
	s_setprio 1
	s_waitcnt lgkmcnt(0)
	v_mfma_f32_16x16x32_bf16 v[124:127], v[152:155], v[184:187], v[124:127]
	v_mfma_f32_16x16x32_bf16 v[120:123], v[160:163], v[184:187], v[120:123]
	v_mfma_f32_16x16x32_bf16 v[108:111], v[152:155], v[192:195], v[108:111]
	v_mfma_f32_16x16x32_bf16 v[104:107], v[160:163], v[192:195], v[104:107]
	v_mfma_f32_16x16x32_bf16 v[92:95], v[152:155], v[200:203], v[92:95]
	v_mfma_f32_16x16x32_bf16 v[88:91], v[160:163], v[200:203], v[88:91]
	v_mfma_f32_16x16x32_bf16 v[76:79], v[152:155], v[208:211], v[76:79]
	v_mfma_f32_16x16x32_bf16 v[72:75], v[160:163], v[208:211], v[72:75]
	v_mfma_f32_16x16x32_bf16 v[124:127], v[156:159], v[188:191], v[124:127]
	v_mfma_f32_16x16x32_bf16 v[120:123], v[164:167], v[188:191], v[120:123]
	v_mfma_f32_16x16x32_bf16 v[108:111], v[156:159], v[196:199], v[108:111]
	v_mfma_f32_16x16x32_bf16 v[104:107], v[164:167], v[196:199], v[104:107]
	v_mfma_f32_16x16x32_bf16 v[92:95], v[156:159], v[204:207], v[92:95]
	v_mfma_f32_16x16x32_bf16 v[88:91], v[164:167], v[204:207], v[88:91]
	v_mfma_f32_16x16x32_bf16 v[76:79], v[156:159], v[212:215], v[76:79]
	v_mfma_f32_16x16x32_bf16 v[72:75], v[164:167], v[212:215], v[72:75]
	s_setprio 0
	s_setprio 1
	v_mfma_f32_16x16x32_bf16 v[116:119], v[168:171], v[184:187], v[116:119]
	v_mfma_f32_16x16x32_bf16 v[112:115], v[176:179], v[184:187], v[112:115]
	v_mfma_f32_16x16x32_bf16 v[100:103], v[168:171], v[192:195], v[100:103]
	v_mfma_f32_16x16x32_bf16 v[96:99], v[176:179], v[192:195], v[96:99]
	v_mfma_f32_16x16x32_bf16 v[84:87], v[168:171], v[200:203], v[84:87]
	v_mfma_f32_16x16x32_bf16 v[80:83], v[176:179], v[200:203], v[80:83]
	v_mfma_f32_16x16x32_bf16 v[68:71], v[168:171], v[208:211], v[68:71]
	v_mfma_f32_16x16x32_bf16 v[64:67], v[176:179], v[208:211], v[64:67]
	v_mfma_f32_16x16x32_bf16 v[116:119], v[172:175], v[188:191], v[116:119]
	v_mfma_f32_16x16x32_bf16 v[112:115], v[180:183], v[188:191], v[112:115]
	v_mfma_f32_16x16x32_bf16 v[100:103], v[172:175], v[196:199], v[100:103]
	v_mfma_f32_16x16x32_bf16 v[96:99], v[180:183], v[196:199], v[96:99]
	v_mfma_f32_16x16x32_bf16 v[84:87], v[172:175], v[204:207], v[84:87]
	v_mfma_f32_16x16x32_bf16 v[80:83], v[180:183], v[204:207], v[80:83]
	v_mfma_f32_16x16x32_bf16 v[68:71], v[172:175], v[212:215], v[68:71]
	v_mfma_f32_16x16x32_bf16 v[64:67], v[180:183], v[212:215], v[64:67]
	s_setprio 0
	s_barrier
	s_add_u32 s50, s48, 0x8000
	s_addc_u32 s51, s49, 0
	s_add_i32 s38, s38, s3
	s_mov_b32 m0, s38
	ds_read_b128 v[184:187], v151 offset:49152
	ds_read_b128 v[188:191], v151 offset:50176
	ds_read_b128 v[192:195], v151 offset:51200
	ds_read_b128 v[196:199], v151 offset:52224
	ds_read_b128 v[200:203], v151 offset:53248
	ds_read_b128 v[204:207], v151 offset:54272
	ds_read_b128 v[208:211], v151 offset:55296
	ds_read_b128 v[212:215], v151 offset:56320
	global_load_lds_dwordx4 v132, s[50:51]
	s_add_i32 m0, s38, 0x2000
	s_add_u32 s48, s48, 0x9000
	s_addc_u32 s49, s49, 0
	s_add_i32 s38, s39, s3
	global_load_lds_dwordx4 v128, s[50:51]
	s_mov_b32 m0, s38
	s_nop 0
	global_load_lds_dwordx4 v132, s[48:49]
	s_add_i32 m0, s38, 0x2000
	s_nop 0
	global_load_lds_dwordx4 v128, s[48:49]
	s_mov_b32 m0, s58
	s_nop 0
	global_load_lds_dwordx4 v134, s[26:27]
	s_mov_b32 m0, s59
	s_nop 0
	global_load_lds_dwordx4 v130, s[26:27]
	s_waitcnt vmcnt(8)
	s_waitcnt lgkmcnt(0)
	s_barrier
	s_setprio 1
	s_waitcnt lgkmcnt(0)
	v_mfma_f32_16x16x32_bf16 v[60:63], v[152:155], v[184:187], v[60:63]
	v_mfma_f32_16x16x32_bf16 v[56:59], v[160:163], v[184:187], v[56:59]
	v_mfma_f32_16x16x32_bf16 v[44:47], v[152:155], v[192:195], v[44:47]
	v_mfma_f32_16x16x32_bf16 v[40:43], v[160:163], v[192:195], v[40:43]
	v_mfma_f32_16x16x32_bf16 v[28:31], v[152:155], v[200:203], v[28:31]
	v_mfma_f32_16x16x32_bf16 v[24:27], v[160:163], v[200:203], v[24:27]
	v_mfma_f32_16x16x32_bf16 v[12:15], v[152:155], v[208:211], v[12:15]
	v_mfma_f32_16x16x32_bf16 v[8:11], v[160:163], v[208:211], v[8:11]
	v_mfma_f32_16x16x32_bf16 v[60:63], v[156:159], v[188:191], v[60:63]
	v_mfma_f32_16x16x32_bf16 v[56:59], v[164:167], v[188:191], v[56:59]
	v_mfma_f32_16x16x32_bf16 v[44:47], v[156:159], v[196:199], v[44:47]
	v_mfma_f32_16x16x32_bf16 v[40:43], v[164:167], v[196:199], v[40:43]
	v_mfma_f32_16x16x32_bf16 v[28:31], v[156:159], v[204:207], v[28:31]
	v_mfma_f32_16x16x32_bf16 v[24:27], v[164:167], v[204:207], v[24:27]
	v_mfma_f32_16x16x32_bf16 v[12:15], v[156:159], v[212:215], v[12:15]
	v_mfma_f32_16x16x32_bf16 v[8:11], v[164:167], v[212:215], v[8:11]
	s_setprio 0
	s_setprio 1
	v_mfma_f32_16x16x32_bf16 v[52:55], v[168:171], v[184:187], v[52:55]
	v_mfma_f32_16x16x32_bf16 v[48:51], v[176:179], v[184:187], v[48:51]
	v_mfma_f32_16x16x32_bf16 v[36:39], v[168:171], v[192:195], v[36:39]
	v_mfma_f32_16x16x32_bf16 v[32:35], v[176:179], v[192:195], v[32:35]
	v_mfma_f32_16x16x32_bf16 v[20:23], v[168:171], v[200:203], v[20:23]
	v_mfma_f32_16x16x32_bf16 v[16:19], v[176:179], v[200:203], v[16:19]
	v_mfma_f32_16x16x32_bf16 v[4:7], v[168:171], v[208:211], v[4:7]
	v_mfma_f32_16x16x32_bf16 v[0:3], v[176:179], v[208:211], v[0:3]
	v_mfma_f32_16x16x32_bf16 v[52:55], v[172:175], v[188:191], v[52:55]
	v_mfma_f32_16x16x32_bf16 v[48:51], v[180:183], v[188:191], v[48:51]
	v_mfma_f32_16x16x32_bf16 v[36:39], v[172:175], v[196:199], v[36:39]
	v_mfma_f32_16x16x32_bf16 v[32:35], v[180:183], v[196:199], v[32:35]
	v_mfma_f32_16x16x32_bf16 v[20:23], v[172:175], v[204:207], v[20:23]
	v_mfma_f32_16x16x32_bf16 v[16:19], v[180:183], v[204:207], v[16:19]
	v_mfma_f32_16x16x32_bf16 v[4:7], v[172:175], v[212:215], v[4:7]
	v_mfma_f32_16x16x32_bf16 v[0:3], v[180:183], v[212:215], v[0:3]
	s_setprio 0
	s_barrier
	s_add_i32 s66, s66, 2
	s_add_u32 s24, s24, 0x10000
	s_addc_u32 s25, s25, 0
	s_add_u32 s64, s64, 0x10000
	s_addc_u32 s65, s65, 0
	s_cmp_gt_u32 s66, 61
	s_cbranch_scc0 .LBB0_166
	s_and_b64 vcc, exec, s[28:29]
	s_cbranch_vccz .LBB0_169
	s_barrier

; #define PG8_STAGE(bufoff, gbase, voff) do { _Pragma("unroll") for (int _i = 0; _i < 2; ++_i) \
;         __builtin_amdgcn_global_load_lds((const unsigned*)((const char*)(gbase) + (voff)[_i]), (LAS unsigned*)(lds + (bufoff) + ldsw + _i * 8192), 16, 0, 0); } while (0)
; #define PG8_LDA(dst, b, h) do { _Pragma("unroll") for (int m = 0; m < 4; ++m) _Pragma("unroll") for (int k = 0; k < 2; ++k) dst[m][k] = *(const LAS bf16x8*)(lds + PG8_SA(b, h) + aoff + m * 2048 + k * 1024); } while (0)
; #define PG8_LDB(dst, b, h) do { _Pragma("unroll") for (int n = 0; n < 2; ++n) _Pragma("unroll") for (int k = 0; k < 2; ++k) dst[n][k] = *(const LAS bf16x8*)(lds + PG8_SB(b, h) + boff + n * 2048 + k * 1024); } while (0)
; #define PG8_MMA(ai, bj, At, Bt) do { __builtin_amdgcn_s_setprio(1); _Pragma("unroll") for (int m = 0; m < 4; ++m) _Pragma("unroll") for (int n = 0; n < 2; ++n) _Pragma("unroll") for (int k = 0; k < 2; ++k) \
;         acc[ai][bj][m][n] = __builtin_amdgcn_mfma_f32_16x16x32_bf16(Bt[n][k], At[m][k], acc[ai][bj][m][n], 0, 0, 0); __builtin_amdgcn_s_setprio(0); } while (0)
; #define PG8_WAIT_V(n) asm volatile("s_waitcnt vmcnt(" #n ")" ::: "memory")
; #define PG8_WAIT_L(n) asm volatile("s_waitcnt lgkmcnt(" #n ")" ::: "memory")
; #define PG8_BAR __builtin_amdgcn_s_barrier()
; #define PG8_SCHED __builtin_amdgcn_sched_barrier(0)
; template <class Epi, class Sched, bool ALIGN_EPI>
; __device__ __forceinline__ void gemm_phase(LAS unsigned char* lds, const Gemm g, const Sched& S, const Epi& E, const int wid) {
;     ...
;             const char* a2 = last ? nA : cA + (size_t)(t + 2) * kstepA; const char* b2 = last ? nB : cB + (size_t)(t + 2) * kstep;
;             const char* a3 = a2 + kstepA; const char* b3 = b2 + kstep;
;             PG8_LDB(B0, 0, 0); PG8_LDB(B1, 0, 1); PG8_SCHED; PG8_LDA(At, 0, 0); PG8_STAGE(PG8_SA(1, 1), a1 + hstepA, voffA);
;             PG8_WAIT_V(8); PG8_WAIT_L(0); PG8_BAR; PG8_MMA(0, 0, At, B0); PG8_MMA(0, 1, At, B1); PG8_BAR; PG8_SCHED;
;             PG8_LDA(At, 0, 1); PG8_STAGE(PG8_SB(0, 0), b2, voffB); PG8_STAGE(PG8_SB(0, 1), b2 + hstepB, voffB); PG8_STAGE(PG8_SA(0, 0), a2, voffA);
;             PG8_WAIT_V(8); PG8_WAIT_L(0); PG8_BAR; PG8_MMA(1, 0, At, B0); PG8_MMA(1, 1, At, B1); PG8_BAR; PG8_SCHED;
.LBB0_243:
	s_add_u32 s38, s26, s60
	s_addc_u32 s39, s27, s61
	s_add_u32 s64, s38, 0x100
	s_addc_u32 s65, s39, 0
	s_and_b64 s[62:63], s[58:59], exec
	s_cselect_b32 s63, s21, s65
	s_cselect_b32 s62, s20, s64
	s_add_u32 s60, s10, s60
	s_addc_u32 s61, s11, s61
	s_add_u32 s60, s60, 0x100
	ds_read_b128 v[142:145], v137
	ds_read_b128 v[146:149], v137 offset:1024
	ds_read_b128 v[150:153], v137 offset:2048
	ds_read_b128 v[154:157], v137 offset:3072
	ds_read_b128 v[158:161], v138
	ds_read_b128 v[162:165], v138 offset:1024
	ds_read_b128 v[166:169], v138 offset:2048
	ds_read_b128 v[170:173], v138 offset:3072
	s_addc_u32 s61, s61, 0
	s_and_b64 s[58:59], s[58:59], exec
	s_cselect_b32 s65, s35, s61
	s_cselect_b32 s64, s55, s60
	s_add_u32 s68, s38, 0x18080
	s_addc_u32 s69, s39, 0
	s_add_u32 s66, s64, 0x4000
	s_addc_u32 s67, s65, 0
	s_add_u32 s60, s62, 0x18000
	s_addc_u32 s61, s63, 0
	s_add_u32 s58, s64, 0x4080
	s_addc_u32 s59, s65, 0
	s_mov_b32 m0, s30
	ds_read_b128 v[174:177], v139
	ds_read_b128 v[178:181], v139 offset:1024
	ds_read_b128 v[182:185], v139 offset:2048
	ds_read_b128 v[186:189], v139 offset:3072
	ds_read_b128 v[190:193], v139 offset:4096
	ds_read_b128 v[194:197], v139 offset:5120
	ds_read_b128 v[198:201], v139 offset:6144
	ds_read_b128 v[202:205], v139 offset:7168
	global_load_lds_dwordx4 v134, s[68:69]
	s_mov_b32 m0, s77
	s_nop 0
	global_load_lds_dwordx4 v130, s[68:69]
	s_waitcnt vmcnt(8)
	s_waitcnt lgkmcnt(0)
	s_barrier
	s_setprio 1
	s_waitcnt lgkmcnt(0)
	v_mfma_f32_16x16x32_bf16 v[124:127], v[142:145], v[174:177], v[124:127]
	v_mfma_f32_16x16x32_bf16 v[120:123], v[150:153], v[174:177], v[120:123]
	v_mfma_f32_16x16x32_bf16 v[108:111], v[142:145], v[182:185], v[108:111]
	v_mfma_f32_16x16x32_bf16 v[104:107], v[150:153], v[182:185], v[104:107]
	v_mfma_f32_16x16x32_bf16 v[92:95], v[142:145], v[190:193], v[92:95]
	v_mfma_f32_16x16x32_bf16 v[88:91], v[150:153], v[190:193], v[88:91]
	v_mfma_f32_16x16x32_bf16 v[76:79], v[142:145], v[198:201], v[76:79]
	v_mfma_f32_16x16x32_bf16 v[72:75], v[150:153], v[198:201], v[72:75]
	v_mfma_f32_16x16x32_bf16 v[124:127], v[146:149], v[178:181], v[124:127]
	v_mfma_f32_16x16x32_bf16 v[120:123], v[154:157], v[178:181], v[120:123]
	v_mfma_f32_16x16x32_bf16 v[108:111], v[146:149], v[186:189], v[108:111]
	v_mfma_f32_16x16x32_bf16 v[104:107], v[154:157], v[186:189], v[104:107]
	v_mfma_f32_16x16x32_bf16 v[92:95], v[146:149], v[194:197], v[92:95]
	v_mfma_f32_16x16x32_bf16 v[88:91], v[154:157], v[194:197], v[88:91]
	v_mfma_f32_16x16x32_bf16 v[76:79], v[146:149], v[202:205], v[76:79]
	v_mfma_f32_16x16x32_bf16 v[72:75], v[154:157], v[202:205], v[72:75]
	s_setprio 0
	s_setprio 1
	v_mfma_f32_16x16x32_bf16 v[116:119], v[158:161], v[174:177], v[116:119]
	v_mfma_f32_16x16x32_bf16 v[112:115], v[166:169], v[174:177], v[112:115]
	v_mfma_f32_16x16x32_bf16 v[100:103], v[158:161], v[182:185], v[100:103]
	v_mfma_f32_16x16x32_bf16 v[96:99], v[166:169], v[182:185], v[96:99]
	v_mfma_f32_16x16x32_bf16 v[84:87], v[158:161], v[190:193], v[84:87]
	v_mfma_f32_16x16x32_bf16 v[80:83], v[166:169], v[190:193], v[80:83]
	v_mfma_f32_16x16x32_bf16 v[68:71], v[158:161], v[198:201], v[68:71]
	v_mfma_f32_16x16x32_bf16 v[64:67], v[166:169], v[198:201], v[64:67]
	v_mfma_f32_16x16x32_bf16 v[116:119], v[162:165], v[178:181], v[116:119]
	v_mfma_f32_16x16x32_bf16 v[112:115], v[170:173], v[178:181], v[112:115]
	v_mfma_f32_16x16x32_bf16 v[100:103], v[162:165], v[186:189], v[100:103]
	v_mfma_f32_16x16x32_bf16 v[96:99], v[170:173], v[186:189], v[96:99]
	v_mfma_f32_16x16x32_bf16 v[84:87], v[162:165], v[194:197], v[84:87]
	v_mfma_f32_16x16x32_bf16 v[80:83], v[170:173], v[194:197], v[80:83]
	v_mfma_f32_16x16x32_bf16 v[68:71], v[162:165], v[202:205], v[68:71]
	v_mfma_f32_16x16x32_bf16 v[64:67], v[170:173], v[202:205], v[64:67]
	s_setprio 0
	s_barrier
	s_mov_b32 m0, s79
	v_lshl_add_u64 v[206:207], s[64:65], 0, v[132:133]
	ds_read_b128 v[174:177], v139 offset:16384
	ds_read_b128 v[178:181], v139 offset:17408
	ds_read_b128 v[182:185], v139 offset:18432
	ds_read_b128 v[186:189], v139 offset:19456
	ds_read_b128 v[190:193], v139 offset:20480
	ds_read_b128 v[194:197], v139 offset:21504
	ds_read_b128 v[198:201], v139 offset:22528
	ds_read_b128 v[202:205], v139 offset:23552
	global_load_lds_dwordx4 v[206:207], off
	v_lshl_add_u64 v[208:209], s[64:65], 0, v[128:129]
	s_mov_b32 m0, s80
	s_nop 0
	global_load_lds_dwordx4 v[208:209], off
	s_mov_b32 m0, s81
	v_lshl_add_u64 v[212:213], s[62:63], 0, v[130:131]
	global_load_lds_dwordx4 v132, s[66:67]
	s_mov_b32 m0, s84
	s_nop 0
	global_load_lds_dwordx4 v128, s[66:67]
	v_lshl_add_u64 v[210:211], s[62:63], 0, v[134:135]
	s_mov_b32 m0, s13
	s_nop 0
	global_load_lds_dwordx4 v[210:211], off
	s_mov_b32 m0, s52
	s_nop 0
	global_load_lds_dwordx4 v[212:213], off
	s_waitcnt vmcnt(8)
	s_waitcnt lgkmcnt(0)
	s_barrier
; #define PG8_STAGE(bufoff, gbase, voff) do { _Pragma("unroll") for (int _i = 0; _i < 2; ++_i) \
;         __builtin_amdgcn_global_load_lds((const unsigned*)((const char*)(gbase) + (voff)[_i]), (LAS unsigned*)(lds + (bufoff) + ldsw + _i * 8192), 16, 0, 0); } while (0)
; #define PG8_LDA(dst, b, h) do { _Pragma("unroll") for (int m = 0; m < 4; ++m) _Pragma("unroll") for (int k = 0; k < 2; ++k) dst[m][k] = *(const LAS bf16x8*)(lds + PG8_SA(b, h) + aoff + m * 2048 + k * 1024); } while (0)
; #define PG8_LDB(dst, b, h) do { _Pragma("unroll") for (int n = 0; n < 2; ++n) _Pragma("unroll") for (int k = 0; k < 2; ++k) dst[n][k] = *(const LAS bf16x8*)(lds + PG8_SB(b, h) + boff + n * 2048 + k * 1024); } while (0)
; #define PG8_MMA(ai, bj, At, Bt) do { __builtin_amdgcn_s_setprio(1); _Pragma("unroll") for (int m = 0; m < 4; ++m) _Pragma("unroll") for (int n = 0; n < 2; ++n) _Pragma("unroll") for (int k = 0; k < 2; ++k) \
;         acc[ai][bj][m][n] = __builtin_amdgcn_mfma_f32_16x16x32_bf16(Bt[n][k], At[m][k], acc[ai][bj][m][n], 0, 0, 0); __builtin_amdgcn_s_setprio(0); } while (0)
; #define PG8_WAIT_V(n) asm volatile("s_waitcnt vmcnt(" #n ")" ::: "memory")
; #define PG8_WAIT_L(n) asm volatile("s_waitcnt lgkmcnt(" #n ")" ::: "memory")
; #define PG8_BAR __builtin_amdgcn_s_barrier()
; #define PG8_SCHED __builtin_amdgcn_sched_barrier(0)
; template <class Epi, class Sched, bool ALIGN_EPI>
; __device__ __forceinline__ void gemm_phase(LAS unsigned char* lds, const Gemm g, const Sched& S, const Epi& E, const int wid) {
;     ...
;             PG8_WAIT_V(8); PG8_WAIT_L(0); PG8_BAR; PG8_MMA(1, 0, At, B0); PG8_MMA(1, 1, At, B1); PG8_BAR; PG8_SCHED;
;             PG8_LDB(B0, 1, 0); PG8_LDB(B1, 1, 1); PG8_SCHED; PG8_LDA(At, 1, 0); PG8_STAGE(PG8_SA(0, 1), a2 + hstepA, voffA);
;             PG8_WAIT_V(8); PG8_WAIT_L(0); PG8_BAR; PG8_MMA(0, 0, At, B0); PG8_MMA(0, 1, At, B1); PG8_BAR; PG8_SCHED;
	s_setprio 1
	s_waitcnt lgkmcnt(0)
	v_mfma_f32_16x16x32_bf16 v[60:63], v[142:145], v[174:177], v[60:63]
	v_mfma_f32_16x16x32_bf16 v[56:59], v[150:153], v[174:177], v[56:59]
	v_mfma_f32_16x16x32_bf16 v[44:47], v[142:145], v[182:185], v[44:47]
	v_mfma_f32_16x16x32_bf16 v[40:43], v[150:153], v[182:185], v[40:43]
	v_mfma_f32_16x16x32_bf16 v[28:31], v[142:145], v[190:193], v[28:31]
	v_mfma_f32_16x16x32_bf16 v[24:27], v[150:153], v[190:193], v[24:27]
	v_mfma_f32_16x16x32_bf16 v[12:15], v[142:145], v[198:201], v[12:15]
	v_mfma_f32_16x16x32_bf16 v[8:11], v[150:153], v[198:201], v[8:11]
	v_mfma_f32_16x16x32_bf16 v[60:63], v[146:149], v[178:181], v[60:63]
	v_mfma_f32_16x16x32_bf16 v[56:59], v[154:157], v[178:181], v[56:59]
	v_mfma_f32_16x16x32_bf16 v[44:47], v[146:149], v[186:189], v[44:47]
	v_mfma_f32_16x16x32_bf16 v[40:43], v[154:157], v[186:189], v[40:43]
	v_mfma_f32_16x16x32_bf16 v[28:31], v[146:149], v[194:197], v[28:31]
	v_mfma_f32_16x16x32_bf16 v[24:27], v[154:157], v[194:197], v[24:27]
	v_mfma_f32_16x16x32_bf16 v[12:15], v[146:149], v[202:205], v[12:15]
	v_mfma_f32_16x16x32_bf16 v[8:11], v[154:157], v[202:205], v[8:11]
	s_setprio 0
	s_setprio 1
	v_mfma_f32_16x16x32_bf16 v[52:55], v[158:161], v[174:177], v[52:55]
	v_mfma_f32_16x16x32_bf16 v[48:51], v[166:169], v[174:177], v[48:51]
	v_mfma_f32_16x16x32_bf16 v[36:39], v[158:161], v[182:185], v[36:39]
	v_mfma_f32_16x16x32_bf16 v[32:35], v[166:169], v[182:185], v[32:35]
	v_mfma_f32_16x16x32_bf16 v[20:23], v[158:161], v[190:193], v[20:23]
	v_mfma_f32_16x16x32_bf16 v[16:19], v[166:169], v[190:193], v[16:19]
	v_mfma_f32_16x16x32_bf16 v[4:7], v[158:161], v[198:201], v[4:7]
	v_mfma_f32_16x16x32_bf16 v[0:3], v[166:169], v[198:201], v[0:3]
	v_mfma_f32_16x16x32_bf16 v[52:55], v[162:165], v[178:181], v[52:55]
	v_mfma_f32_16x16x32_bf16 v[48:51], v[170:173], v[178:181], v[48:51]
	v_mfma_f32_16x16x32_bf16 v[36:39], v[162:165], v[186:189], v[36:39]
	v_mfma_f32_16x16x32_bf16 v[32:35], v[170:173], v[186:189], v[32:35]
	v_mfma_f32_16x16x32_bf16 v[20:23], v[162:165], v[194:197], v[20:23]
	v_mfma_f32_16x16x32_bf16 v[16:19], v[170:173], v[194:197], v[16:19]
	v_mfma_f32_16x16x32_bf16 v[4:7], v[162:165], v[202:205], v[4:7]
	v_mfma_f32_16x16x32_bf16 v[0:3], v[170:173], v[202:205], v[0:3]
	s_setprio 0
	s_barrier
	ds_read_b128 v[142:145], v140
	ds_read_b128 v[146:149], v140 offset:1024
	ds_read_b128 v[150:153], v140 offset:2048
	ds_read_b128 v[154:157], v140 offset:3072
	ds_read_b128 v[158:161], v141
	ds_read_b128 v[162:165], v141 offset:1024
	ds_read_b128 v[166:169], v141 offset:2048
	ds_read_b128 v[170:173], v141 offset:3072
	s_mov_b32 m0, s70
	ds_read_b128 v[174:177], v139 offset:32768
	ds_read_b128 v[178:181], v139 offset:33792
	ds_read_b128 v[182:185], v139 offset:34816
	ds_read_b128 v[186:189], v139 offset:35840
	ds_read_b128 v[190:193], v139 offset:36864
	ds_read_b128 v[194:197], v139 offset:37888
	ds_read_b128 v[198:201], v139 offset:38912
	ds_read_b128 v[202:205], v139 offset:39936
	global_load_lds_dwordx4 v134, s[60:61]
	s_mov_b32 m0, s71
	s_nop 0
	global_load_lds_dwordx4 v130, s[60:61]
	s_waitcnt vmcnt(8)
	s_waitcnt lgkmcnt(0)
	s_barrier
	s_setprio 1
	s_waitcnt lgkmcnt(0)
	v_mfma_f32_16x16x32_bf16 v[124:127], v[142:145], v[174:177], v[124:127]
	v_mfma_f32_16x16x32_bf16 v[120:123], v[150:153], v[174:177], v[120:123]
	v_mfma_f32_16x16x32_bf16 v[108:111], v[142:145], v[182:185], v[108:111]
	v_mfma_f32_16x16x32_bf16 v[104:107], v[150:153], v[182:185], v[104:107]
	v_mfma_f32_16x16x32_bf16 v[92:95], v[142:145], v[190:193], v[92:95]
	v_mfma_f32_16x16x32_bf16 v[88:91], v[150:153], v[190:193], v[88:91]
	v_mfma_f32_16x16x32_bf16 v[76:79], v[142:145], v[198:201], v[76:79]
	v_mfma_f32_16x16x32_bf16 v[72:75], v[150:153], v[198:201], v[72:75]
	v_mfma_f32_16x16x32_bf16 v[124:127], v[146:149], v[178:181], v[124:127]
	v_mfma_f32_16x16x32_bf16 v[120:123], v[154:157], v[178:181], v[120:123]
	v_mfma_f32_16x16x32_bf16 v[108:111], v[146:149], v[186:189], v[108:111]
	v_mfma_f32_16x16x32_bf16 v[104:107], v[154:157], v[186:189], v[104:107]
	v_mfma_f32_16x16x32_bf16 v[92:95], v[146:149], v[194:197], v[92:95]
	v_mfma_f32_16x16x32_bf16 v[88:91], v[154:157], v[194:197], v[88:91]
	v_mfma_f32_16x16x32_bf16 v[76:79], v[146:149], v[202:205], v[76:79]
	v_mfma_f32_16x16x32_bf16 v[72:75], v[154:157], v[202:205], v[72:75]
	s_setprio 0
	s_setprio 1
	v_mfma_f32_16x16x32_bf16 v[116:119], v[158:161], v[174:177], v[116:119]
	v_mfma_f32_16x16x32_bf16 v[112:115], v[166:169], v[174:177], v[112:115]
	v_mfma_f32_16x16x32_bf16 v[100:103], v[158:161], v[182:185], v[100:103]
	v_mfma_f32_16x16x32_bf16 v[96:99], v[166:169], v[182:185], v[96:99]
	v_mfma_f32_16x16x32_bf16 v[84:87], v[158:161], v[190:193], v[84:87]
	v_mfma_f32_16x16x32_bf16 v[80:83], v[166:169], v[190:193], v[80:83]
	v_mfma_f32_16x16x32_bf16 v[68:71], v[158:161], v[198:201], v[68:71]
	v_mfma_f32_16x16x32_bf16 v[64:67], v[166:169], v[198:201], v[64:67]
	v_mfma_f32_16x16x32_bf16 v[116:119], v[162:165], v[178:181], v[116:119]
	v_mfma_f32_16x16x32_bf16 v[112:115], v[170:173], v[178:181], v[112:115]
	v_mfma_f32_16x16x32_bf16 v[100:103], v[162:165], v[186:189], v[100:103]
	v_mfma_f32_16x16x32_bf16 v[96:99], v[170:173], v[186:189], v[96:99]
	v_mfma_f32_16x16x32_bf16 v[84:87], v[162:165], v[194:197], v[84:87]
	v_mfma_f32_16x16x32_bf16 v[80:83], v[170:173], v[194:197], v[80:83]
	v_mfma_f32_16x16x32_bf16 v[68:71], v[162:165], v[202:205], v[68:71]
	v_mfma_f32_16x16x32_bf16 v[64:67], v[170:173], v[202:205], v[64:67]
	s_setprio 0
	s_barrier
; #define PG8_STAGE(bufoff, gbase, voff) do { _Pragma("unroll") for (int _i = 0; _i < 2; ++_i) \
;         __builtin_amdgcn_global_load_lds((const unsigned*)((const char*)(gbase) + (voff)[_i]), (LAS unsigned*)(lds + (bufoff) + ldsw + _i * 8192), 16, 0, 0); } while (0)
; #define PG8_LDA(dst, b, h) do { _Pragma("unroll") for (int m = 0; m < 4; ++m) _Pragma("unroll") for (int k = 0; k < 2; ++k) dst[m][k] = *(const LAS bf16x8*)(lds + PG8_SA(b, h) + aoff + m * 2048 + k * 1024); } while (0)
; #define PG8_MMA(ai, bj, At, Bt) do { __builtin_amdgcn_s_setprio(1); _Pragma("unroll") for (int m = 0; m < 4; ++m) _Pragma("unroll") for (int n = 0; n < 2; ++n) _Pragma("unroll") for (int k = 0; k < 2; ++k) \
;         acc[ai][bj][m][n] = __builtin_amdgcn_mfma_f32_16x16x32_bf16(Bt[n][k], At[m][k], acc[ai][bj][m][n], 0, 0, 0); __builtin_amdgcn_s_setprio(0); } while (0)
; #define PG8_WAIT_V(n) asm volatile("s_waitcnt vmcnt(" #n ")" ::: "memory")
; #define PG8_WAIT_L(n) asm volatile("s_waitcnt lgkmcnt(" #n ")" ::: "memory")
; #define PG8_BAR __builtin_amdgcn_s_barrier()
; #define PG8_SCHED __builtin_amdgcn_sched_barrier(0)
; template <class Epi, class Sched, bool ALIGN_EPI>
; __device__ __forceinline__ void gemm_phase(LAS unsigned char* lds, const Gemm g, const Sched& S, const Epi& E, const int wid) {
;     ...
;             PG8_LDA(At, 1, 1); PG8_STAGE(PG8_SB(1, 0), b3, voffB); PG8_STAGE(PG8_SB(1, 1), b3 + hstepB, voffB); PG8_STAGE(PG8_SA(1, 0), a3, voffA);
;             PG8_WAIT_V(8); PG8_WAIT_L(0); PG8_BAR; PG8_MMA(1, 0, At, B0); PG8_MMA(1, 1, At, B1); PG8_BAR; PG8_SCHED;
;         }
;         if constexpr (ALIGN_EPI) { if (wr == 0) PG8_BAR; }
	s_mov_b32 m0, s85
	v_lshl_add_u64 v[206:207], v[206:207], 0, s[18:19]
	ds_read_b128 v[174:177], v139 offset:49152
	ds_read_b128 v[178:181], v139 offset:50176
	ds_read_b128 v[182:185], v139 offset:51200
	ds_read_b128 v[186:189], v139 offset:52224
	ds_read_b128 v[190:193], v139 offset:53248
	ds_read_b128 v[194:197], v139 offset:54272
	ds_read_b128 v[198:201], v139 offset:55296
	ds_read_b128 v[202:205], v139 offset:56320
	global_load_lds_dwordx4 v[206:207], off
	v_lshl_add_u64 v[206:207], v[208:209], 0, s[18:19]
	s_mov_b32 m0, s86
	s_nop 0
	global_load_lds_dwordx4 v[206:207], off
	s_mov_b32 m0, s87
	s_nop 0
	global_load_lds_dwordx4 v132, s[58:59]
	s_mov_b32 m0, s89
	s_nop 0
	global_load_lds_dwordx4 v128, s[58:59]
	v_lshl_add_u64 v[206:207], v[210:211], 0, s[18:19]
	s_mov_b32 m0, s75
	s_nop 0
	global_load_lds_dwordx4 v[206:207], off
	v_lshl_add_u64 v[206:207], v[212:213], 0, s[18:19]
	s_mov_b32 m0, s76
	s_nop 0
	global_load_lds_dwordx4 v[206:207], off
	s_waitcnt vmcnt(8)
	s_waitcnt lgkmcnt(0)
	s_barrier
	s_setprio 1
	s_waitcnt lgkmcnt(0)
	v_mfma_f32_16x16x32_bf16 v[60:63], v[142:145], v[174:177], v[60:63]
	v_mfma_f32_16x16x32_bf16 v[56:59], v[150:153], v[174:177], v[56:59]
	v_mfma_f32_16x16x32_bf16 v[44:47], v[142:145], v[182:185], v[44:47]
	v_mfma_f32_16x16x32_bf16 v[40:43], v[150:153], v[182:185], v[40:43]
	v_mfma_f32_16x16x32_bf16 v[28:31], v[142:145], v[190:193], v[28:31]
	v_mfma_f32_16x16x32_bf16 v[24:27], v[150:153], v[190:193], v[24:27]
	v_mfma_f32_16x16x32_bf16 v[12:15], v[142:145], v[198:201], v[12:15]
	v_mfma_f32_16x16x32_bf16 v[8:11], v[150:153], v[198:201], v[8:11]
	v_mfma_f32_16x16x32_bf16 v[60:63], v[146:149], v[178:181], v[60:63]
	v_mfma_f32_16x16x32_bf16 v[56:59], v[154:157], v[178:181], v[56:59]
	v_mfma_f32_16x16x32_bf16 v[44:47], v[146:149], v[186:189], v[44:47]
	v_mfma_f32_16x16x32_bf16 v[40:43], v[154:157], v[186:189], v[40:43]
	v_mfma_f32_16x16x32_bf16 v[28:31], v[146:149], v[194:197], v[28:31]
	v_mfma_f32_16x16x32_bf16 v[24:27], v[154:157], v[194:197], v[24:27]
	v_mfma_f32_16x16x32_bf16 v[12:15], v[146:149], v[202:205], v[12:15]
	v_mfma_f32_16x16x32_bf16 v[8:11], v[154:157], v[202:205], v[8:11]
	s_setprio 0
	s_setprio 1
	v_mfma_f32_16x16x32_bf16 v[52:55], v[158:161], v[174:177], v[52:55]
	v_mfma_f32_16x16x32_bf16 v[48:51], v[166:169], v[174:177], v[48:51]
	v_mfma_f32_16x16x32_bf16 v[36:39], v[158:161], v[182:185], v[36:39]
	v_mfma_f32_16x16x32_bf16 v[32:35], v[166:169], v[182:185], v[32:35]
	v_mfma_f32_16x16x32_bf16 v[20:23], v[158:161], v[190:193], v[20:23]
	v_mfma_f32_16x16x32_bf16 v[16:19], v[166:169], v[190:193], v[16:19]
	v_mfma_f32_16x16x32_bf16 v[4:7], v[158:161], v[198:201], v[4:7]
	v_mfma_f32_16x16x32_bf16 v[0:3], v[166:169], v[198:201], v[0:3]
	v_mfma_f32_16x16x32_bf16 v[52:55], v[162:165], v[178:181], v[52:55]
	v_mfma_f32_16x16x32_bf16 v[48:51], v[170:173], v[178:181], v[48:51]
	v_mfma_f32_16x16x32_bf16 v[36:39], v[162:165], v[186:189], v[36:39]
	v_mfma_f32_16x16x32_bf16 v[32:35], v[170:173], v[186:189], v[32:35]
	v_mfma_f32_16x16x32_bf16 v[20:23], v[162:165], v[194:197], v[20:23]
	v_mfma_f32_16x16x32_bf16 v[16:19], v[170:173], v[194:197], v[16:19]
	v_mfma_f32_16x16x32_bf16 v[4:7], v[162:165], v[202:205], v[4:7]
	v_mfma_f32_16x16x32_bf16 v[0:3], v[170:173], v[202:205], v[0:3]
	s_setprio 0
	s_barrier
	s_andn2_b64 vcc, exec, s[56:57]
	s_mov_b64 s[58:59], -1
	s_mov_b64 s[56:57], 0
	s_mov_b64 s[60:61], 0x100
	s_cbranch_vccz .LBB0_243
	s_and_b64 vcc, exec, s[28:29]
	s_cbranch_vccz .LBB0_246
	s_barrier

; #define PG8_STAGE(bufoff, gbase, voff) do { _Pragma("unroll") for (int _i = 0; _i < 2; ++_i) \
;         __builtin_amdgcn_global_load_lds((const unsigned*)((const char*)(gbase) + (voff)[_i]), (LAS unsigned*)(lds + (bufoff) + ldsw + _i * 8192), 16, 0, 0); } while (0)
; #define PG8_LDA(dst, b, h) do { _Pragma("unroll") for (int m = 0; m < 4; ++m) _Pragma("unroll") for (int k = 0; k < 2; ++k) dst[m][k] = *(const LAS bf16x8*)(lds + PG8_SA(b, h) + aoff + m * 2048 + k * 1024); } while (0)
; #define PG8_LDB(dst, b, h) do { _Pragma("unroll") for (int n = 0; n < 2; ++n) _Pragma("unroll") for (int k = 0; k < 2; ++k) dst[n][k] = *(const LAS bf16x8*)(lds + PG8_SB(b, h) + boff + n * 2048 + k * 1024); } while (0)
; #define PG8_MMA(ai, bj, At, Bt) do { __builtin_amdgcn_s_setprio(1); _Pragma("unroll") for (int m = 0; m < 4; ++m) _Pragma("unroll") for (int n = 0; n < 2; ++n) _Pragma("unroll") for (int k = 0; k < 2; ++k) \
;         acc[ai][bj][m][n] = __builtin_amdgcn_mfma_f32_16x16x32_bf16(Bt[n][k], At[m][k], acc[ai][bj][m][n], 0, 0, 0); __builtin_amdgcn_s_setprio(0); } while (0)
; #define PG8_WAIT_V(n) asm volatile("s_waitcnt vmcnt(" #n ")" ::: "memory")
; #define PG8_WAIT_L(n) asm volatile("s_waitcnt lgkmcnt(" #n ")" ::: "memory")
; #define PG8_BAR __builtin_amdgcn_s_barrier()
; #define PG8_SCHED __builtin_amdgcn_sched_barrier(0)
; template <class Epi, class Sched, bool ALIGN_EPI>
; __device__ __forceinline__ void gemm_phase(LAS unsigned char* lds, const Gemm g, const Sched& S, const Epi& E, const int wid) {
;     ...
;             const char* a1 = cA + (size_t)(t + 1) * kstepA;
;             const char* a2 = last ? nA : cA + (size_t)(t + 2) * kstepA; const char* b2 = last ? nB : cB + (size_t)(t + 2) * kstep;
;             const char* a3 = a2 + kstepA; const char* b3 = b2 + kstep;
;             PG8_LDB(B0, 0, 0); PG8_LDB(B1, 0, 1); PG8_SCHED; PG8_LDA(At, 0, 0); PG8_STAGE(PG8_SA(1, 1), a1 + hstepA, voffA);
;             PG8_WAIT_V(8); PG8_WAIT_L(0); PG8_BAR; PG8_MMA(0, 0, At, B0); PG8_MMA(0, 1, At, B1); PG8_BAR; PG8_SCHED;
;             PG8_LDA(At, 0, 1); PG8_STAGE(PG8_SB(0, 0), b2, voffB); PG8_STAGE(PG8_SB(0, 1), b2 + hstepB, voffB); PG8_STAGE(PG8_SA(0, 0), a2, voffA);
;             PG8_WAIT_V(8); PG8_WAIT_L(0); PG8_BAR; PG8_MMA(1, 0, At, B0); PG8_MMA(1, 1, At, B1); PG8_BAR; PG8_SCHED;
.LBB0_282:
	ds_read_b128 v[40:43], v153
	ds_read_b128 v[44:47], v153 offset:1024
	ds_read_b128 v[156:159], v153 offset:2048
	ds_read_b128 v[160:163], v153 offset:3072
	ds_read_b128 v[164:167], v154
	ds_read_b128 v[168:171], v154 offset:1024
	ds_read_b128 v[172:175], v154 offset:2048
	ds_read_b128 v[176:179], v154 offset:3072
	s_add_u32 s24, s22, 0x100
	s_addc_u32 s25, s23, 0
	s_cmp_eq_u32 s68, 2
	s_cselect_b32 s55, s19, s25
	s_cselect_b32 s54, s18, s24
	s_cselect_b32 s27, s21, s67
	s_cselect_b32 s26, s20, s13
	s_mov_b32 m0, s63
	v_lshl_add_u64 v[212:213], s[22:23], 0, v[146:147]
	ds_read_b128 v[180:183], v155
	ds_read_b128 v[184:187], v155 offset:1024
	ds_read_b128 v[188:191], v155 offset:2048
	ds_read_b128 v[192:195], v155 offset:3072
	ds_read_b128 v[196:199], v155 offset:4096
	ds_read_b128 v[200:203], v155 offset:5120
	ds_read_b128 v[204:207], v155 offset:6144
	ds_read_b128 v[208:211], v155 offset:7168
	global_load_lds_dwordx4 v[212:213], off
	v_lshl_add_u64 v[212:213], s[22:23], 0, v[148:149]
	s_mov_b32 m0, s64
	s_nop 0
	global_load_lds_dwordx4 v[212:213], off
	s_waitcnt vmcnt(8)
	s_waitcnt lgkmcnt(0)
	s_barrier
	s_setprio 1
	s_waitcnt lgkmcnt(0)
	v_mfma_f32_16x16x32_bf16 v[132:135], v[40:43], v[180:183], v[132:135]
	v_mfma_f32_16x16x32_bf16 v[128:131], v[156:159], v[180:183], v[128:131]
	v_mfma_f32_16x16x32_bf16 v[116:119], v[40:43], v[188:191], v[116:119]
	v_mfma_f32_16x16x32_bf16 v[112:115], v[156:159], v[188:191], v[112:115]
	v_mfma_f32_16x16x32_bf16 v[100:103], v[40:43], v[196:199], v[100:103]
	v_mfma_f32_16x16x32_bf16 v[96:99], v[156:159], v[196:199], v[96:99]
	v_mfma_f32_16x16x32_bf16 v[84:87], v[40:43], v[204:207], v[84:87]
	v_mfma_f32_16x16x32_bf16 v[80:83], v[156:159], v[204:207], v[80:83]
	v_mfma_f32_16x16x32_bf16 v[132:135], v[44:47], v[184:187], v[132:135]
	v_mfma_f32_16x16x32_bf16 v[128:131], v[160:163], v[184:187], v[128:131]
	v_mfma_f32_16x16x32_bf16 v[116:119], v[44:47], v[192:195], v[116:119]
	v_mfma_f32_16x16x32_bf16 v[112:115], v[160:163], v[192:195], v[112:115]
	v_mfma_f32_16x16x32_bf16 v[100:103], v[44:47], v[200:203], v[100:103]
	v_mfma_f32_16x16x32_bf16 v[96:99], v[160:163], v[200:203], v[96:99]
	v_mfma_f32_16x16x32_bf16 v[84:87], v[44:47], v[208:211], v[84:87]
	v_mfma_f32_16x16x32_bf16 v[80:83], v[160:163], v[208:211], v[80:83]
	s_setprio 0
	s_setprio 1
	v_mfma_f32_16x16x32_bf16 v[124:127], v[164:167], v[180:183], v[124:127]
	v_mfma_f32_16x16x32_bf16 v[120:123], v[172:175], v[180:183], v[120:123]
	v_mfma_f32_16x16x32_bf16 v[108:111], v[164:167], v[188:191], v[108:111]
	v_mfma_f32_16x16x32_bf16 v[104:107], v[172:175], v[188:191], v[104:107]
	v_mfma_f32_16x16x32_bf16 v[92:95], v[164:167], v[196:199], v[92:95]
	v_mfma_f32_16x16x32_bf16 v[88:91], v[172:175], v[196:199], v[88:91]
	v_mfma_f32_16x16x32_bf16 v[76:79], v[164:167], v[204:207], v[76:79]
	v_mfma_f32_16x16x32_bf16 v[72:75], v[172:175], v[204:207], v[72:75]
	v_mfma_f32_16x16x32_bf16 v[124:127], v[168:171], v[184:187], v[124:127]
	v_mfma_f32_16x16x32_bf16 v[120:123], v[176:179], v[184:187], v[120:123]
	v_mfma_f32_16x16x32_bf16 v[108:111], v[168:171], v[192:195], v[108:111]
	v_mfma_f32_16x16x32_bf16 v[104:107], v[176:179], v[192:195], v[104:107]
	v_mfma_f32_16x16x32_bf16 v[92:95], v[168:171], v[200:203], v[92:95]
	v_mfma_f32_16x16x32_bf16 v[88:91], v[176:179], v[200:203], v[88:91]
	v_mfma_f32_16x16x32_bf16 v[76:79], v[168:171], v[208:211], v[76:79]
	v_mfma_f32_16x16x32_bf16 v[72:75], v[176:179], v[208:211], v[72:75]
	s_setprio 0
	s_barrier
	s_add_i32 s22, s61, s3
	v_lshl_add_u64 v[212:213], s[26:27], 0, v[140:141]
	s_mov_b32 m0, s22
	ds_read_b128 v[180:183], v155 offset:16384
	ds_read_b128 v[184:187], v155 offset:17408
	ds_read_b128 v[188:191], v155 offset:18432
	ds_read_b128 v[192:195], v155 offset:19456
	ds_read_b128 v[196:199], v155 offset:20480
	ds_read_b128 v[200:203], v155 offset:21504
	ds_read_b128 v[204:207], v155 offset:22528
	ds_read_b128 v[208:211], v155 offset:23552
	global_load_lds_dwordx4 v[212:213], off
	s_add_i32 m0, s22, 0x2000
	s_add_u32 s22, s26, 0x6000
	v_lshl_add_u64 v[214:215], s[26:27], 0, v[136:137]
	s_addc_u32 s23, s27, 0
	s_add_i32 s38, s62, s3
	global_load_lds_dwordx4 v[214:215], off
	s_mov_b32 m0, s38
	v_lshl_add_u64 v[218:219], s[54:55], 0, v[138:139]
	global_load_lds_dwordx4 v140, s[22:23]
	s_add_i32 m0, s38, 0x2000
	s_nop 0
	global_load_lds_dwordx4 v136, s[22:23]
	v_lshl_add_u64 v[216:217], s[54:55], 0, v[142:143]
	s_mov_b32 m0, s52
	s_nop 0
	global_load_lds_dwordx4 v[216:217], off
	s_mov_b32 m0, s53
	s_nop 0
	global_load_lds_dwordx4 v[218:219], off
	s_waitcnt vmcnt(8)
	s_waitcnt lgkmcnt(0)
	s_barrier
; #define PG8_STAGE(bufoff, gbase, voff) do { _Pragma("unroll") for (int _i = 0; _i < 2; ++_i) \
;         __builtin_amdgcn_global_load_lds((const unsigned*)((const char*)(gbase) + (voff)[_i]), (LAS unsigned*)(lds + (bufoff) + ldsw + _i * 8192), 16, 0, 0); } while (0)
; #define PG8_LDA(dst, b, h) do { _Pragma("unroll") for (int m = 0; m < 4; ++m) _Pragma("unroll") for (int k = 0; k < 2; ++k) dst[m][k] = *(const LAS bf16x8*)(lds + PG8_SA(b, h) + aoff + m * 2048 + k * 1024); } while (0)
; #define PG8_LDB(dst, b, h) do { _Pragma("unroll") for (int n = 0; n < 2; ++n) _Pragma("unroll") for (int k = 0; k < 2; ++k) dst[n][k] = *(const LAS bf16x8*)(lds + PG8_SB(b, h) + boff + n * 2048 + k * 1024); } while (0)
; #define PG8_MMA(ai, bj, At, Bt) do { __builtin_amdgcn_s_setprio(1); _Pragma("unroll") for (int m = 0; m < 4; ++m) _Pragma("unroll") for (int n = 0; n < 2; ++n) _Pragma("unroll") for (int k = 0; k < 2; ++k) \
;         acc[ai][bj][m][n] = __builtin_amdgcn_mfma_f32_16x16x32_bf16(Bt[n][k], At[m][k], acc[ai][bj][m][n], 0, 0, 0); __builtin_amdgcn_s_setprio(0); } while (0)
; #define PG8_WAIT_V(n) asm volatile("s_waitcnt vmcnt(" #n ")" ::: "memory")
; #define PG8_WAIT_L(n) asm volatile("s_waitcnt lgkmcnt(" #n ")" ::: "memory")
; #define PG8_BAR __builtin_amdgcn_s_barrier()
; #define PG8_SCHED __builtin_amdgcn_sched_barrier(0)
; template <class Epi, class Sched, bool ALIGN_EPI>
; __device__ __forceinline__ void gemm_phase(LAS unsigned char* lds, const Gemm g, const Sched& S, const Epi& E, const int wid) {
;     ...
;             PG8_WAIT_V(8); PG8_WAIT_L(0); PG8_BAR; PG8_MMA(1, 0, At, B0); PG8_MMA(1, 1, At, B1); PG8_BAR; PG8_SCHED;
;             PG8_LDB(B0, 1, 0); PG8_LDB(B1, 1, 1); PG8_SCHED; PG8_LDA(At, 1, 0); PG8_STAGE(PG8_SA(0, 1), a2 + hstepA, voffA);
;             PG8_WAIT_V(8); PG8_WAIT_L(0); PG8_BAR; PG8_MMA(0, 0, At, B0); PG8_MMA(0, 1, At, B1); PG8_BAR; PG8_SCHED;
	s_setprio 1
	s_waitcnt lgkmcnt(0)
	v_mfma_f32_16x16x32_bf16 v[68:71], v[40:43], v[180:183], v[68:71]
	v_mfma_f32_16x16x32_bf16 v[64:67], v[156:159], v[180:183], v[64:67]
	v_mfma_f32_16x16x32_bf16 v[52:55], v[40:43], v[188:191], v[52:55]
	v_mfma_f32_16x16x32_bf16 v[48:51], v[156:159], v[188:191], v[48:51]
	v_mfma_f32_16x16x32_bf16 v[28:31], v[40:43], v[196:199], v[28:31]
	v_mfma_f32_16x16x32_bf16 v[24:27], v[156:159], v[196:199], v[24:27]
	v_mfma_f32_16x16x32_bf16 v[12:15], v[40:43], v[204:207], v[12:15]
	v_mfma_f32_16x16x32_bf16 v[8:11], v[156:159], v[204:207], v[8:11]
	v_mfma_f32_16x16x32_bf16 v[68:71], v[44:47], v[184:187], v[68:71]
	v_mfma_f32_16x16x32_bf16 v[64:67], v[160:163], v[184:187], v[64:67]
	v_mfma_f32_16x16x32_bf16 v[52:55], v[44:47], v[192:195], v[52:55]
	v_mfma_f32_16x16x32_bf16 v[48:51], v[160:163], v[192:195], v[48:51]
	v_mfma_f32_16x16x32_bf16 v[28:31], v[44:47], v[200:203], v[28:31]
	v_mfma_f32_16x16x32_bf16 v[24:27], v[160:163], v[200:203], v[24:27]
	v_mfma_f32_16x16x32_bf16 v[12:15], v[44:47], v[208:211], v[12:15]
	v_mfma_f32_16x16x32_bf16 v[8:11], v[160:163], v[208:211], v[8:11]
	s_setprio 0
	s_setprio 1
	v_mfma_f32_16x16x32_bf16 v[36:39], v[164:167], v[188:191], v[36:39]
	v_mfma_f32_16x16x32_bf16 v[32:35], v[172:175], v[188:191], v[32:35]
	v_mfma_f32_16x16x32_bf16 v[20:23], v[164:167], v[196:199], v[20:23]
	v_mfma_f32_16x16x32_bf16 v[16:19], v[172:175], v[196:199], v[16:19]
	v_mfma_f32_16x16x32_bf16 v[4:7], v[164:167], v[204:207], v[4:7]
	v_mfma_f32_16x16x32_bf16 v[0:3], v[172:175], v[204:207], v[0:3]
	v_mfma_f32_16x16x32_bf16 v[40:43], v[164:167], v[180:183], v[60:63]
	v_mfma_f32_16x16x32_bf16 v[44:47], v[172:175], v[180:183], v[56:59]
	v_mfma_f32_16x16x32_bf16 v[36:39], v[168:171], v[192:195], v[36:39]
	v_mfma_f32_16x16x32_bf16 v[32:35], v[176:179], v[192:195], v[32:35]
	v_mfma_f32_16x16x32_bf16 v[20:23], v[168:171], v[200:203], v[20:23]
	v_mfma_f32_16x16x32_bf16 v[16:19], v[176:179], v[200:203], v[16:19]
	v_mfma_f32_16x16x32_bf16 v[4:7], v[168:171], v[208:211], v[4:7]
	v_mfma_f32_16x16x32_bf16 v[0:3], v[176:179], v[208:211], v[0:3]
	v_mfma_f32_16x16x32_bf16 v[40:43], v[168:171], v[184:187], v[40:43]
	v_mfma_f32_16x16x32_bf16 v[44:47], v[176:179], v[184:187], v[44:47]
	s_setprio 0
	s_barrier
	s_add_i32 s38, 0, 0x18000
	s_add_i32 s39, 0, 0x1c000
	v_add_u32_e32 v160, s38, v150
	v_add_u32_e32 v176, s39, v150
	ds_read_b128 v[56:59], v160
	ds_read_b128 v[60:63], v160 offset:1024
	ds_read_b128 v[156:159], v160 offset:2048
	ds_read_b128 v[160:163], v160 offset:3072
	ds_read_b128 v[164:167], v176
	ds_read_b128 v[168:171], v176 offset:1024
	ds_read_b128 v[172:175], v176 offset:2048
	ds_read_b128 v[176:179], v176 offset:3072
	s_add_u32 s22, s54, 0x18000
	s_addc_u32 s23, s55, 0
	s_mov_b32 m0, s56
	ds_read_b128 v[180:183], v155 offset:32768
	ds_read_b128 v[184:187], v155 offset:33792
	ds_read_b128 v[188:191], v155 offset:34816
	ds_read_b128 v[192:195], v155 offset:35840
	ds_read_b128 v[196:199], v155 offset:36864
	ds_read_b128 v[200:203], v155 offset:37888
	ds_read_b128 v[204:207], v155 offset:38912
	ds_read_b128 v[208:211], v155 offset:39936
	global_load_lds_dwordx4 v142, s[22:23]
	s_mov_b32 m0, s57
	s_nop 0
	global_load_lds_dwordx4 v138, s[22:23]
	s_waitcnt vmcnt(8)
	s_waitcnt lgkmcnt(0)
	s_barrier
	s_setprio 1
	s_waitcnt lgkmcnt(0)
	v_mfma_f32_16x16x32_bf16 v[132:135], v[56:59], v[180:183], v[132:135]
	v_mfma_f32_16x16x32_bf16 v[128:131], v[156:159], v[180:183], v[128:131]
	v_mfma_f32_16x16x32_bf16 v[116:119], v[56:59], v[188:191], v[116:119]
	v_mfma_f32_16x16x32_bf16 v[112:115], v[156:159], v[188:191], v[112:115]
	v_mfma_f32_16x16x32_bf16 v[100:103], v[56:59], v[196:199], v[100:103]
	v_mfma_f32_16x16x32_bf16 v[96:99], v[156:159], v[196:199], v[96:99]
	v_mfma_f32_16x16x32_bf16 v[84:87], v[56:59], v[204:207], v[84:87]
	v_mfma_f32_16x16x32_bf16 v[80:83], v[156:159], v[204:207], v[80:83]
	v_mfma_f32_16x16x32_bf16 v[132:135], v[60:63], v[184:187], v[132:135]
	v_mfma_f32_16x16x32_bf16 v[128:131], v[160:163], v[184:187], v[128:131]
	v_mfma_f32_16x16x32_bf16 v[116:119], v[60:63], v[192:195], v[116:119]
	v_mfma_f32_16x16x32_bf16 v[112:115], v[160:163], v[192:195], v[112:115]
	v_mfma_f32_16x16x32_bf16 v[100:103], v[60:63], v[200:203], v[100:103]
	v_mfma_f32_16x16x32_bf16 v[96:99], v[160:163], v[200:203], v[96:99]
	v_mfma_f32_16x16x32_bf16 v[84:87], v[60:63], v[208:211], v[84:87]
	v_mfma_f32_16x16x32_bf16 v[80:83], v[160:163], v[208:211], v[80:83]
	s_setprio 0
	s_setprio 1
	v_mfma_f32_16x16x32_bf16 v[124:127], v[164:167], v[180:183], v[124:127]
	v_mfma_f32_16x16x32_bf16 v[120:123], v[172:175], v[180:183], v[120:123]
	v_mfma_f32_16x16x32_bf16 v[108:111], v[164:167], v[188:191], v[108:111]
	v_mfma_f32_16x16x32_bf16 v[104:107], v[172:175], v[188:191], v[104:107]
	v_mfma_f32_16x16x32_bf16 v[92:95], v[164:167], v[196:199], v[92:95]
	v_mfma_f32_16x16x32_bf16 v[88:91], v[172:175], v[196:199], v[88:91]
	v_mfma_f32_16x16x32_bf16 v[76:79], v[164:167], v[204:207], v[76:79]
	v_mfma_f32_16x16x32_bf16 v[72:75], v[172:175], v[204:207], v[72:75]
	v_mfma_f32_16x16x32_bf16 v[124:127], v[168:171], v[184:187], v[124:127]
	v_mfma_f32_16x16x32_bf16 v[120:123], v[176:179], v[184:187], v[120:123]
	v_mfma_f32_16x16x32_bf16 v[108:111], v[168:171], v[192:195], v[108:111]
	v_mfma_f32_16x16x32_bf16 v[104:107], v[176:179], v[192:195], v[104:107]
	v_mfma_f32_16x16x32_bf16 v[92:95], v[168:171], v[200:203], v[92:95]
	v_mfma_f32_16x16x32_bf16 v[88:91], v[176:179], v[200:203], v[88:91]
	v_mfma_f32_16x16x32_bf16 v[76:79], v[168:171], v[208:211], v[76:79]
	v_mfma_f32_16x16x32_bf16 v[72:75], v[176:179], v[208:211], v[72:75]
	s_setprio 0
	s_barrier
; #define PG8_STAGE(bufoff, gbase, voff) do { _Pragma("unroll") for (int _i = 0; _i < 2; ++_i) \
;         __builtin_amdgcn_global_load_lds((const unsigned*)((const char*)(gbase) + (voff)[_i]), (LAS unsigned*)(lds + (bufoff) + ldsw + _i * 8192), 16, 0, 0); } while (0)
; #define PG8_LDA(dst, b, h) do { _Pragma("unroll") for (int m = 0; m < 4; ++m) _Pragma("unroll") for (int k = 0; k < 2; ++k) dst[m][k] = *(const LAS bf16x8*)(lds + PG8_SA(b, h) + aoff + m * 2048 + k * 1024); } while (0)
; #define PG8_MMA(ai, bj, At, Bt) do { __builtin_amdgcn_s_setprio(1); _Pragma("unroll") for (int m = 0; m < 4; ++m) _Pragma("unroll") for (int n = 0; n < 2; ++n) _Pragma("unroll") for (int k = 0; k < 2; ++k) \
;         acc[ai][bj][m][n] = __builtin_amdgcn_mfma_f32_16x16x32_bf16(Bt[n][k], At[m][k], acc[ai][bj][m][n], 0, 0, 0); __builtin_amdgcn_s_setprio(0); } while (0)
; #define PG8_WAIT_V(n) asm volatile("s_waitcnt vmcnt(" #n ")" ::: "memory")
; #define PG8_WAIT_L(n) asm volatile("s_waitcnt lgkmcnt(" #n ")" ::: "memory")
; #define PG8_BAR __builtin_amdgcn_s_barrier()
; #define PG8_SCHED __builtin_amdgcn_sched_barrier(0)
; template <class Epi, class Sched, bool ALIGN_EPI>
; __device__ __forceinline__ void gemm_phase(LAS unsigned char* lds, const Gemm g, const Sched& S, const Epi& E, const int wid) {
;     ...
;             PG8_LDA(At, 1, 1); PG8_STAGE(PG8_SB(1, 0), b3, voffB); PG8_STAGE(PG8_SB(1, 1), b3 + hstepB, voffB); PG8_STAGE(PG8_SA(1, 0), a3, voffA);
;             PG8_WAIT_V(8); PG8_WAIT_L(0); PG8_BAR; PG8_MMA(1, 0, At, B0); PG8_MMA(1, 1, At, B1); PG8_BAR; PG8_SCHED;
;         }
;         if constexpr (ALIGN_EPI) { if (wr == 0) PG8_BAR; }
	s_add_i32 s22, s38, s3
	v_lshl_add_u64 v[212:213], v[212:213], 0, s[16:17]
	s_mov_b32 m0, s22
	ds_read_b128 v[180:183], v155 offset:49152
	ds_read_b128 v[184:187], v155 offset:50176
	ds_read_b128 v[188:191], v155 offset:51200
	ds_read_b128 v[192:195], v155 offset:52224
	ds_read_b128 v[196:199], v155 offset:53248
	ds_read_b128 v[200:203], v155 offset:54272
	ds_read_b128 v[204:207], v155 offset:55296
	ds_read_b128 v[208:211], v155 offset:56320
	global_load_lds_dwordx4 v[212:213], off
	s_add_i32 m0, s22, 0x2000
	s_add_u32 s22, s26, 0x6080
	v_lshl_add_u64 v[212:213], v[214:215], 0, s[16:17]
	s_addc_u32 s23, s27, 0
	s_add_i32 s26, s39, s3
	global_load_lds_dwordx4 v[212:213], off
	s_mov_b32 m0, s26
	s_nop 0
	global_load_lds_dwordx4 v140, s[22:23]
	s_add_i32 m0, s26, 0x2000
	s_nop 0
	global_load_lds_dwordx4 v136, s[22:23]
	v_lshl_add_u64 v[212:213], v[216:217], 0, s[16:17]
	s_mov_b32 m0, s30
	s_nop 0
	global_load_lds_dwordx4 v[212:213], off
	v_lshl_add_u64 v[212:213], v[218:219], 0, s[16:17]
	s_mov_b32 m0, s31
	s_nop 0
	global_load_lds_dwordx4 v[212:213], off
	s_waitcnt vmcnt(8)
	s_waitcnt lgkmcnt(0)
	s_barrier
	s_setprio 1
	s_waitcnt lgkmcnt(0)
	v_mfma_f32_16x16x32_bf16 v[68:71], v[56:59], v[180:183], v[68:71]
	v_mfma_f32_16x16x32_bf16 v[64:67], v[156:159], v[180:183], v[64:67]
	v_mfma_f32_16x16x32_bf16 v[52:55], v[56:59], v[188:191], v[52:55]
	v_mfma_f32_16x16x32_bf16 v[48:51], v[156:159], v[188:191], v[48:51]
	v_mfma_f32_16x16x32_bf16 v[28:31], v[56:59], v[196:199], v[28:31]
	v_mfma_f32_16x16x32_bf16 v[24:27], v[156:159], v[196:199], v[24:27]
	v_mfma_f32_16x16x32_bf16 v[12:15], v[56:59], v[204:207], v[12:15]
	v_mfma_f32_16x16x32_bf16 v[8:11], v[156:159], v[204:207], v[8:11]
	v_mfma_f32_16x16x32_bf16 v[68:71], v[60:63], v[184:187], v[68:71]
	v_mfma_f32_16x16x32_bf16 v[64:67], v[160:163], v[184:187], v[64:67]
	v_mfma_f32_16x16x32_bf16 v[52:55], v[60:63], v[192:195], v[52:55]
	v_mfma_f32_16x16x32_bf16 v[48:51], v[160:163], v[192:195], v[48:51]
	v_mfma_f32_16x16x32_bf16 v[28:31], v[60:63], v[200:203], v[28:31]
	v_mfma_f32_16x16x32_bf16 v[24:27], v[160:163], v[200:203], v[24:27]
	v_mfma_f32_16x16x32_bf16 v[12:15], v[60:63], v[208:211], v[12:15]
	v_mfma_f32_16x16x32_bf16 v[8:11], v[160:163], v[208:211], v[8:11]
	s_setprio 0
	s_setprio 1
	v_mfma_f32_16x16x32_bf16 v[40:43], v[164:167], v[180:183], v[40:43]
	v_mfma_f32_16x16x32_bf16 v[60:63], v[168:171], v[184:187], v[40:43]
	v_mfma_f32_16x16x32_bf16 v[40:43], v[172:175], v[180:183], v[44:47]
	v_mfma_f32_16x16x32_bf16 v[36:39], v[164:167], v[188:191], v[36:39]
	v_mfma_f32_16x16x32_bf16 v[32:35], v[172:175], v[188:191], v[32:35]
	v_mfma_f32_16x16x32_bf16 v[20:23], v[164:167], v[196:199], v[20:23]
	v_mfma_f32_16x16x32_bf16 v[16:19], v[172:175], v[196:199], v[16:19]
	v_mfma_f32_16x16x32_bf16 v[4:7], v[164:167], v[204:207], v[4:7]
	v_mfma_f32_16x16x32_bf16 v[0:3], v[172:175], v[204:207], v[0:3]
	v_mfma_f32_16x16x32_bf16 v[56:59], v[176:179], v[184:187], v[40:43]
	v_mfma_f32_16x16x32_bf16 v[36:39], v[168:171], v[192:195], v[36:39]
	v_mfma_f32_16x16x32_bf16 v[32:35], v[176:179], v[192:195], v[32:35]
	v_mfma_f32_16x16x32_bf16 v[20:23], v[168:171], v[200:203], v[20:23]
	v_mfma_f32_16x16x32_bf16 v[16:19], v[176:179], v[200:203], v[16:19]
	v_mfma_f32_16x16x32_bf16 v[4:7], v[168:171], v[208:211], v[4:7]
	v_mfma_f32_16x16x32_bf16 v[0:3], v[176:179], v[208:211], v[0:3]
	s_setprio 0
	s_barrier
	s_add_i32 s68, s68, 2
	s_add_u32 s13, s13, 0x100
	s_addc_u32 s67, s67, 0
	s_cmp_gt_u32 s68, 3
	s_mov_b64 s[22:23], s[24:25]
	s_cbranch_scc0 .LBB0_282
	s_and_b64 vcc, exec, s[28:29]
	s_cbranch_vccz .LBB0_285
	s_barrier

; #define PG8_STAGE(bufoff, gbase, voff) do { _Pragma("unroll") for (int _i = 0; _i < 2; ++_i) \
;         __builtin_amdgcn_global_load_lds((const unsigned*)((const char*)(gbase) + (voff)[_i]), (LAS unsigned*)(lds + (bufoff) + ldsw + _i * 8192), 16, 0, 0); } while (0)
; #define PG8_LDA(dst, b, h) do { _Pragma("unroll") for (int m = 0; m < 4; ++m) _Pragma("unroll") for (int k = 0; k < 2; ++k) dst[m][k] = *(const LAS bf16x8*)(lds + PG8_SA(b, h) + aoff + m * 2048 + k * 1024); } while (0)
; #define PG8_LDB(dst, b, h) do { _Pragma("unroll") for (int n = 0; n < 2; ++n) _Pragma("unroll") for (int k = 0; k < 2; ++k) dst[n][k] = *(const LAS bf16x8*)(lds + PG8_SB(b, h) + boff + n * 2048 + k * 1024); } while (0)
; #define PG8_MMA(ai, bj, At, Bt) do { __builtin_amdgcn_s_setprio(1); _Pragma("unroll") for (int m = 0; m < 4; ++m) _Pragma("unroll") for (int n = 0; n < 2; ++n) _Pragma("unroll") for (int k = 0; k < 2; ++k) \
;         acc[ai][bj][m][n] = __builtin_amdgcn_mfma_f32_16x16x32_bf16(Bt[n][k], At[m][k], acc[ai][bj][m][n], 0, 0, 0); __builtin_amdgcn_s_setprio(0); } while (0)
; #define PG8_WAIT_V(n) asm volatile("s_waitcnt vmcnt(" #n ")" ::: "memory")
; #define PG8_WAIT_L(n) asm volatile("s_waitcnt lgkmcnt(" #n ")" ::: "memory")
; #define PG8_BAR __builtin_amdgcn_s_barrier()
; #define PG8_SCHED __builtin_amdgcn_sched_barrier(0)
; template <class Epi, class Sched, bool ALIGN_EPI>
; __device__ __forceinline__ void gemm_phase(LAS unsigned char* lds, const Gemm g, const Sched& S, const Epi& E, const int wid) {
;     ...
;             const char* a1 = cA + (size_t)(t + 1) * kstepA;
;             const char* a2 = last ? nA : cA + (size_t)(t + 2) * kstepA; const char* b2 = last ? nB : cB + (size_t)(t + 2) * kstep;
;             const char* a3 = a2 + kstepA; const char* b3 = b2 + kstep;
;             PG8_LDB(B0, 0, 0); PG8_LDB(B1, 0, 1); PG8_SCHED; PG8_LDA(At, 0, 0); PG8_STAGE(PG8_SA(1, 1), a1 + hstepA, voffA);
;             PG8_WAIT_V(8); PG8_WAIT_L(0); PG8_BAR; PG8_MMA(0, 0, At, B0); PG8_MMA(0, 1, At, B1); PG8_BAR; PG8_SCHED;
;             PG8_LDA(At, 0, 1); PG8_STAGE(PG8_SB(0, 0), b2, voffB); PG8_STAGE(PG8_SB(0, 1), b2 + hstepB, voffB); PG8_STAGE(PG8_SA(0, 0), a2, voffA);
;             PG8_WAIT_V(8); PG8_WAIT_L(0); PG8_BAR; PG8_MMA(1, 0, At, B0); PG8_MMA(1, 1, At, B1); PG8_BAR; PG8_SCHED;
.LBB0_499:
	ds_read_b128 v[150:153], v147
	ds_read_b128 v[154:157], v147 offset:1024
	ds_read_b128 v[158:161], v147 offset:2048
	ds_read_b128 v[162:165], v147 offset:3072
	ds_read_b128 v[166:169], v148
	ds_read_b128 v[170:173], v148 offset:1024
	ds_read_b128 v[174:177], v148 offset:2048
	ds_read_b128 v[178:181], v148 offset:3072
	s_add_u32 s38, s24, 0xfff80080
	s_addc_u32 s39, s25, -1
	s_cmp_eq_u32 s67, 28
	s_cselect_b32 s57, s19, s39
	s_cselect_b32 s56, s27, s38
	s_cselect_b32 s55, s17, s66
	s_cselect_b32 s54, s64, s65
	s_add_i32 m0, s46, 0xc000
	ds_read_b128 v[182:185], v149
	ds_read_b128 v[186:189], v149 offset:1024
	ds_read_b128 v[190:193], v149 offset:2048
	ds_read_b128 v[194:197], v149 offset:3072
	ds_read_b128 v[198:201], v149 offset:4096
	ds_read_b128 v[202:205], v149 offset:5120
	ds_read_b128 v[206:209], v149 offset:6144
	ds_read_b128 v[210:213], v149 offset:7168
	global_load_lds_dwordx4 v136, s[24:25]
	s_add_i32 m0, s46, 0xe000
	s_nop 0
	global_load_lds_dwordx4 v138, s[24:25]
	s_waitcnt vmcnt(8)
	s_waitcnt lgkmcnt(0)
	s_barrier
	s_setprio 1
	s_waitcnt lgkmcnt(0)
	v_mfma_f32_16x16x32_bf16 v[124:127], v[150:153], v[182:185], v[124:127]
	v_mfma_f32_16x16x32_bf16 v[120:123], v[158:161], v[182:185], v[120:123]
	v_mfma_f32_16x16x32_bf16 v[108:111], v[150:153], v[190:193], v[108:111]
	v_mfma_f32_16x16x32_bf16 v[104:107], v[158:161], v[190:193], v[104:107]
	v_mfma_f32_16x16x32_bf16 v[92:95], v[150:153], v[198:201], v[92:95]
	v_mfma_f32_16x16x32_bf16 v[88:91], v[158:161], v[198:201], v[88:91]
	v_mfma_f32_16x16x32_bf16 v[76:79], v[150:153], v[206:209], v[76:79]
	v_mfma_f32_16x16x32_bf16 v[72:75], v[158:161], v[206:209], v[72:75]
	v_mfma_f32_16x16x32_bf16 v[124:127], v[154:157], v[186:189], v[124:127]
	v_mfma_f32_16x16x32_bf16 v[120:123], v[162:165], v[186:189], v[120:123]
	v_mfma_f32_16x16x32_bf16 v[108:111], v[154:157], v[194:197], v[108:111]
	v_mfma_f32_16x16x32_bf16 v[104:107], v[162:165], v[194:197], v[104:107]
	v_mfma_f32_16x16x32_bf16 v[92:95], v[154:157], v[202:205], v[92:95]
	v_mfma_f32_16x16x32_bf16 v[88:91], v[162:165], v[202:205], v[88:91]
	v_mfma_f32_16x16x32_bf16 v[76:79], v[154:157], v[210:213], v[76:79]
	v_mfma_f32_16x16x32_bf16 v[72:75], v[162:165], v[210:213], v[72:75]
	s_setprio 0
	s_setprio 1
	v_mfma_f32_16x16x32_bf16 v[116:119], v[166:169], v[182:185], v[116:119]
	v_mfma_f32_16x16x32_bf16 v[112:115], v[174:177], v[182:185], v[112:115]
	v_mfma_f32_16x16x32_bf16 v[100:103], v[166:169], v[190:193], v[100:103]
	v_mfma_f32_16x16x32_bf16 v[96:99], v[174:177], v[190:193], v[96:99]
	v_mfma_f32_16x16x32_bf16 v[84:87], v[166:169], v[198:201], v[84:87]
	v_mfma_f32_16x16x32_bf16 v[80:83], v[174:177], v[198:201], v[80:83]
	v_mfma_f32_16x16x32_bf16 v[68:71], v[166:169], v[206:209], v[68:71]
	v_mfma_f32_16x16x32_bf16 v[64:67], v[174:177], v[206:209], v[64:67]
	v_mfma_f32_16x16x32_bf16 v[116:119], v[170:173], v[186:189], v[116:119]
	v_mfma_f32_16x16x32_bf16 v[112:115], v[178:181], v[186:189], v[112:115]
	v_mfma_f32_16x16x32_bf16 v[100:103], v[170:173], v[194:197], v[100:103]
	v_mfma_f32_16x16x32_bf16 v[96:99], v[178:181], v[194:197], v[96:99]
	v_mfma_f32_16x16x32_bf16 v[84:87], v[170:173], v[202:205], v[84:87]
	v_mfma_f32_16x16x32_bf16 v[80:83], v[178:181], v[202:205], v[80:83]
	v_mfma_f32_16x16x32_bf16 v[68:71], v[170:173], v[210:213], v[68:71]
	v_mfma_f32_16x16x32_bf16 v[64:67], v[178:181], v[210:213], v[64:67]
	s_setprio 0
	s_barrier
	s_add_i32 s38, s43, s3
	s_mov_b32 m0, s38
	ds_read_b128 v[182:185], v149 offset:16384
	ds_read_b128 v[186:189], v149 offset:17408
	ds_read_b128 v[190:193], v149 offset:18432
	ds_read_b128 v[194:197], v149 offset:19456
	ds_read_b128 v[198:201], v149 offset:20480
	ds_read_b128 v[202:205], v149 offset:21504
	ds_read_b128 v[206:209], v149 offset:22528
	ds_read_b128 v[210:213], v149 offset:23552
	global_load_lds_dwordx4 v132, s[54:55]
	s_add_i32 m0, s38, 0x2000
	s_add_u32 s68, s54, 0x1000
	s_addc_u32 s69, s55, 0
	s_add_i32 s38, s63, s3
	global_load_lds_dwordx4 v128, s[54:55]
	s_mov_b32 m0, s38
	v_lshl_add_u64 v[216:217], s[56:57], 0, v[130:131]
	global_load_lds_dwordx4 v132, s[68:69]
	s_add_i32 m0, s38, 0x2000
	s_nop 0
	global_load_lds_dwordx4 v128, s[68:69]
	v_lshl_add_u64 v[214:215], s[56:57], 0, v[134:135]
	s_mov_b32 m0, s46
	s_nop 0
	global_load_lds_dwordx4 v[214:215], off
	s_mov_b32 m0, s47
	s_nop 0
	global_load_lds_dwordx4 v[216:217], off
	s_waitcnt vmcnt(8)
	s_waitcnt lgkmcnt(0)
	s_barrier
	s_setprio 1
	s_waitcnt lgkmcnt(0)
	v_mfma_f32_16x16x32_bf16 v[60:63], v[150:153], v[182:185], v[60:63]
	v_mfma_f32_16x16x32_bf16 v[56:59], v[158:161], v[182:185], v[56:59]
	v_mfma_f32_16x16x32_bf16 v[44:47], v[150:153], v[190:193], v[44:47]
	v_mfma_f32_16x16x32_bf16 v[40:43], v[158:161], v[190:193], v[40:43]
	v_mfma_f32_16x16x32_bf16 v[28:31], v[150:153], v[198:201], v[28:31]
	v_mfma_f32_16x16x32_bf16 v[24:27], v[158:161], v[198:201], v[24:27]
	v_mfma_f32_16x16x32_bf16 v[12:15], v[150:153], v[206:209], v[12:15]
	v_mfma_f32_16x16x32_bf16 v[8:11], v[158:161], v[206:209], v[8:11]
	v_mfma_f32_16x16x32_bf16 v[60:63], v[154:157], v[186:189], v[60:63]
	v_mfma_f32_16x16x32_bf16 v[56:59], v[162:165], v[186:189], v[56:59]
	v_mfma_f32_16x16x32_bf16 v[44:47], v[154:157], v[194:197], v[44:47]
	v_mfma_f32_16x16x32_bf16 v[40:43], v[162:165], v[194:197], v[40:43]
	v_mfma_f32_16x16x32_bf16 v[28:31], v[154:157], v[202:205], v[28:31]
	v_mfma_f32_16x16x32_bf16 v[24:27], v[162:165], v[202:205], v[24:27]
	v_mfma_f32_16x16x32_bf16 v[12:15], v[154:157], v[210:213], v[12:15]
	v_mfma_f32_16x16x32_bf16 v[8:11], v[162:165], v[210:213], v[8:11]
	s_setprio 0
	s_setprio 1
	v_mfma_f32_16x16x32_bf16 v[52:55], v[166:169], v[182:185], v[52:55]
	v_mfma_f32_16x16x32_bf16 v[48:51], v[174:177], v[182:185], v[48:51]
	v_mfma_f32_16x16x32_bf16 v[36:39], v[166:169], v[190:193], v[36:39]
	v_mfma_f32_16x16x32_bf16 v[32:35], v[174:177], v[190:193], v[32:35]
	v_mfma_f32_16x16x32_bf16 v[20:23], v[166:169], v[198:201], v[20:23]
	v_mfma_f32_16x16x32_bf16 v[16:19], v[174:177], v[198:201], v[16:19]
	v_mfma_f32_16x16x32_bf16 v[4:7], v[166:169], v[206:209], v[4:7]
	v_mfma_f32_16x16x32_bf16 v[0:3], v[174:177], v[206:209], v[0:3]
	v_mfma_f32_16x16x32_bf16 v[52:55], v[170:173], v[186:189], v[52:55]
	v_mfma_f32_16x16x32_bf16 v[48:51], v[178:181], v[186:189], v[48:51]
	v_mfma_f32_16x16x32_bf16 v[36:39], v[170:173], v[194:197], v[36:39]
	v_mfma_f32_16x16x32_bf16 v[32:35], v[178:181], v[194:197], v[32:35]
	v_mfma_f32_16x16x32_bf16 v[20:23], v[170:173], v[202:205], v[20:23]
	v_mfma_f32_16x16x32_bf16 v[16:19], v[178:181], v[202:205], v[16:19]
	v_mfma_f32_16x16x32_bf16 v[4:7], v[170:173], v[210:213], v[4:7]
	v_mfma_f32_16x16x32_bf16 v[0:3], v[178:181], v[210:213], v[0:3]
	s_setprio 0
	s_barrier
; #define PG8_STAGE(bufoff, gbase, voff) do { _Pragma("unroll") for (int _i = 0; _i < 2; ++_i) \
;         __builtin_amdgcn_global_load_lds((const unsigned*)((const char*)(gbase) + (voff)[_i]), (LAS unsigned*)(lds + (bufoff) + ldsw + _i * 8192), 16, 0, 0); } while (0)
; #define PG8_LDA(dst, b, h) do { _Pragma("unroll") for (int m = 0; m < 4; ++m) _Pragma("unroll") for (int k = 0; k < 2; ++k) dst[m][k] = *(const LAS bf16x8*)(lds + PG8_SA(b, h) + aoff + m * 2048 + k * 1024); } while (0)
; #define PG8_LDB(dst, b, h) do { _Pragma("unroll") for (int n = 0; n < 2; ++n) _Pragma("unroll") for (int k = 0; k < 2; ++k) dst[n][k] = *(const LAS bf16x8*)(lds + PG8_SB(b, h) + boff + n * 2048 + k * 1024); } while (0)
; #define PG8_MMA(ai, bj, At, Bt) do { __builtin_amdgcn_s_setprio(1); _Pragma("unroll") for (int m = 0; m < 4; ++m) _Pragma("unroll") for (int n = 0; n < 2; ++n) _Pragma("unroll") for (int k = 0; k < 2; ++k) \
;         acc[ai][bj][m][n] = __builtin_amdgcn_mfma_f32_16x16x32_bf16(Bt[n][k], At[m][k], acc[ai][bj][m][n], 0, 0, 0); __builtin_amdgcn_s_setprio(0); } while (0)
; #define PG8_WAIT_V(n) asm volatile("s_waitcnt vmcnt(" #n ")" ::: "memory")
; #define PG8_WAIT_L(n) asm volatile("s_waitcnt lgkmcnt(" #n ")" ::: "memory")
; #define PG8_BAR __builtin_amdgcn_s_barrier()
; #define PG8_SCHED __builtin_amdgcn_sched_barrier(0)
; template <class Epi, class Sched, bool ALIGN_EPI>
; __device__ __forceinline__ void gemm_phase(LAS unsigned char* lds, const Gemm g, const Sched& S, const Epi& E, const int wid) {
;     ...
;             PG8_LDB(B0, 1, 0); PG8_LDB(B1, 1, 1); PG8_SCHED; PG8_LDA(At, 1, 0); PG8_STAGE(PG8_SA(0, 1), a2 + hstepA, voffA);
;             PG8_WAIT_V(8); PG8_WAIT_L(0); PG8_BAR; PG8_MMA(0, 0, At, B0); PG8_MMA(0, 1, At, B1); PG8_BAR; PG8_SCHED;
;             PG8_LDA(At, 1, 1); PG8_STAGE(PG8_SB(1, 0), b3, voffB); PG8_STAGE(PG8_SB(1, 1), b3 + hstepB, voffB); PG8_STAGE(PG8_SA(1, 0), a3, voffA);
;             PG8_WAIT_V(8); PG8_WAIT_L(0); PG8_BAR; PG8_MMA(1, 0, At, B0); PG8_MMA(1, 1, At, B1); PG8_BAR; PG8_SCHED;
;         }
;         if constexpr (ALIGN_EPI) { if (wr == 0) PG8_BAR; }
	s_add_i32 s38, 0, 0x18000
	s_add_i32 s39, 0, 0x1c000
	v_add_u32_e32 v162, s38, v144
	v_add_u32_e32 v178, s39, v144
	ds_read_b128 v[150:153], v162
	ds_read_b128 v[154:157], v162 offset:1024
	ds_read_b128 v[158:161], v162 offset:2048
	ds_read_b128 v[162:165], v162 offset:3072
	ds_read_b128 v[166:169], v178
	ds_read_b128 v[170:173], v178 offset:1024
	ds_read_b128 v[174:177], v178 offset:2048
	ds_read_b128 v[178:181], v178 offset:3072
	s_add_u32 s56, s56, 0x80000
	s_addc_u32 s57, s57, 0
	s_mov_b32 m0, s52
	ds_read_b128 v[182:185], v149 offset:32768
	ds_read_b128 v[186:189], v149 offset:33792
	ds_read_b128 v[190:193], v149 offset:34816
	ds_read_b128 v[194:197], v149 offset:35840
	ds_read_b128 v[198:201], v149 offset:36864
	ds_read_b128 v[202:205], v149 offset:37888
	ds_read_b128 v[206:209], v149 offset:38912
	ds_read_b128 v[210:213], v149 offset:39936
	global_load_lds_dwordx4 v134, s[56:57]
	s_mov_b32 m0, s53
	s_nop 0
	global_load_lds_dwordx4 v130, s[56:57]
	s_waitcnt vmcnt(8)
	s_waitcnt lgkmcnt(0)
	s_barrier
	s_setprio 1
	s_waitcnt lgkmcnt(0)
	v_mfma_f32_16x16x32_bf16 v[124:127], v[150:153], v[182:185], v[124:127]
	v_mfma_f32_16x16x32_bf16 v[120:123], v[158:161], v[182:185], v[120:123]
	v_mfma_f32_16x16x32_bf16 v[108:111], v[150:153], v[190:193], v[108:111]
	v_mfma_f32_16x16x32_bf16 v[104:107], v[158:161], v[190:193], v[104:107]
	v_mfma_f32_16x16x32_bf16 v[92:95], v[150:153], v[198:201], v[92:95]
	v_mfma_f32_16x16x32_bf16 v[88:91], v[158:161], v[198:201], v[88:91]
	v_mfma_f32_16x16x32_bf16 v[76:79], v[150:153], v[206:209], v[76:79]
	v_mfma_f32_16x16x32_bf16 v[72:75], v[158:161], v[206:209], v[72:75]
	v_mfma_f32_16x16x32_bf16 v[124:127], v[154:157], v[186:189], v[124:127]
	v_mfma_f32_16x16x32_bf16 v[120:123], v[162:165], v[186:189], v[120:123]
	v_mfma_f32_16x16x32_bf16 v[108:111], v[154:157], v[194:197], v[108:111]
	v_mfma_f32_16x16x32_bf16 v[104:107], v[162:165], v[194:197], v[104:107]
	v_mfma_f32_16x16x32_bf16 v[92:95], v[154:157], v[202:205], v[92:95]
	v_mfma_f32_16x16x32_bf16 v[88:91], v[162:165], v[202:205], v[88:91]
	v_mfma_f32_16x16x32_bf16 v[76:79], v[154:157], v[210:213], v[76:79]
	v_mfma_f32_16x16x32_bf16 v[72:75], v[162:165], v[210:213], v[72:75]
	s_setprio 0
	s_setprio 1
	v_mfma_f32_16x16x32_bf16 v[116:119], v[166:169], v[182:185], v[116:119]
	v_mfma_f32_16x16x32_bf16 v[112:115], v[174:177], v[182:185], v[112:115]
	v_mfma_f32_16x16x32_bf16 v[100:103], v[166:169], v[190:193], v[100:103]
	v_mfma_f32_16x16x32_bf16 v[96:99], v[174:177], v[190:193], v[96:99]
	v_mfma_f32_16x16x32_bf16 v[84:87], v[166:169], v[198:201], v[84:87]
	v_mfma_f32_16x16x32_bf16 v[80:83], v[174:177], v[198:201], v[80:83]
	v_mfma_f32_16x16x32_bf16 v[68:71], v[166:169], v[206:209], v[68:71]
	v_mfma_f32_16x16x32_bf16 v[64:67], v[174:177], v[206:209], v[64:67]
	v_mfma_f32_16x16x32_bf16 v[116:119], v[170:173], v[186:189], v[116:119]
	v_mfma_f32_16x16x32_bf16 v[112:115], v[178:181], v[186:189], v[112:115]
	v_mfma_f32_16x16x32_bf16 v[100:103], v[170:173], v[194:197], v[100:103]
	v_mfma_f32_16x16x32_bf16 v[96:99], v[178:181], v[194:197], v[96:99]
	v_mfma_f32_16x16x32_bf16 v[84:87], v[170:173], v[202:205], v[84:87]
	v_mfma_f32_16x16x32_bf16 v[80:83], v[178:181], v[202:205], v[80:83]
	v_mfma_f32_16x16x32_bf16 v[68:71], v[170:173], v[210:213], v[68:71]
	v_mfma_f32_16x16x32_bf16 v[64:67], v[178:181], v[210:213], v[64:67]
	s_setprio 0
	s_barrier
	s_add_u32 s56, s54, 0x8000
	s_addc_u32 s57, s55, 0
	s_add_i32 s38, s38, s3
	s_mov_b32 m0, s38
	ds_read_b128 v[182:185], v149 offset:49152
	ds_read_b128 v[186:189], v149 offset:50176
	ds_read_b128 v[190:193], v149 offset:51200
	ds_read_b128 v[194:197], v149 offset:52224
	ds_read_b128 v[198:201], v149 offset:53248
	ds_read_b128 v[202:205], v149 offset:54272
	ds_read_b128 v[206:209], v149 offset:55296
	ds_read_b128 v[210:213], v149 offset:56320
	global_load_lds_dwordx4 v132, s[56:57]
	s_add_i32 m0, s38, 0x2000
	s_add_u32 s54, s54, 0x9000
	s_addc_u32 s55, s55, 0
	s_add_i32 s38, s39, s3
	global_load_lds_dwordx4 v128, s[56:57]
	s_mov_b32 m0, s38
	v_lshl_add_u64 v[214:215], v[214:215], 0, s[12:13]
	global_load_lds_dwordx4 v132, s[54:55]
	s_add_i32 m0, s38, 0x2000
	s_nop 0
	global_load_lds_dwordx4 v128, s[54:55]
	s_mov_b32 m0, s61
	s_nop 0
	global_load_lds_dwordx4 v[214:215], off
	v_lshl_add_u64 v[214:215], v[216:217], 0, s[12:13]
	s_mov_b32 m0, s62
	s_nop 0
	global_load_lds_dwordx4 v[214:215], off
	s_waitcnt vmcnt(8)
	s_waitcnt lgkmcnt(0)
	s_barrier
	s_setprio 1
	s_waitcnt lgkmcnt(0)
	v_mfma_f32_16x16x32_bf16 v[60:63], v[150:153], v[182:185], v[60:63]
	v_mfma_f32_16x16x32_bf16 v[56:59], v[158:161], v[182:185], v[56:59]
	v_mfma_f32_16x16x32_bf16 v[44:47], v[150:153], v[190:193], v[44:47]
	v_mfma_f32_16x16x32_bf16 v[40:43], v[158:161], v[190:193], v[40:43]
	v_mfma_f32_16x16x32_bf16 v[28:31], v[150:153], v[198:201], v[28:31]
	v_mfma_f32_16x16x32_bf16 v[24:27], v[158:161], v[198:201], v[24:27]
	v_mfma_f32_16x16x32_bf16 v[12:15], v[150:153], v[206:209], v[12:15]
	v_mfma_f32_16x16x32_bf16 v[8:11], v[158:161], v[206:209], v[8:11]
	v_mfma_f32_16x16x32_bf16 v[60:63], v[154:157], v[186:189], v[60:63]
	v_mfma_f32_16x16x32_bf16 v[56:59], v[162:165], v[186:189], v[56:59]
	v_mfma_f32_16x16x32_bf16 v[44:47], v[154:157], v[194:197], v[44:47]
	v_mfma_f32_16x16x32_bf16 v[40:43], v[162:165], v[194:197], v[40:43]
	v_mfma_f32_16x16x32_bf16 v[28:31], v[154:157], v[202:205], v[28:31]
	v_mfma_f32_16x16x32_bf16 v[24:27], v[162:165], v[202:205], v[24:27]
	v_mfma_f32_16x16x32_bf16 v[12:15], v[154:157], v[210:213], v[12:15]
	v_mfma_f32_16x16x32_bf16 v[8:11], v[162:165], v[210:213], v[8:11]
	s_setprio 0
	s_setprio 1
	v_mfma_f32_16x16x32_bf16 v[52:55], v[166:169], v[182:185], v[52:55]
	v_mfma_f32_16x16x32_bf16 v[48:51], v[174:177], v[182:185], v[48:51]
	v_mfma_f32_16x16x32_bf16 v[36:39], v[166:169], v[190:193], v[36:39]
	v_mfma_f32_16x16x32_bf16 v[32:35], v[174:177], v[190:193], v[32:35]
	v_mfma_f32_16x16x32_bf16 v[20:23], v[166:169], v[198:201], v[20:23]
	v_mfma_f32_16x16x32_bf16 v[16:19], v[174:177], v[198:201], v[16:19]
	v_mfma_f32_16x16x32_bf16 v[4:7], v[166:169], v[206:209], v[4:7]
	v_mfma_f32_16x16x32_bf16 v[0:3], v[174:177], v[206:209], v[0:3]
	v_mfma_f32_16x16x32_bf16 v[52:55], v[170:173], v[186:189], v[52:55]
	v_mfma_f32_16x16x32_bf16 v[48:51], v[178:181], v[186:189], v[48:51]
	v_mfma_f32_16x16x32_bf16 v[36:39], v[170:173], v[194:197], v[36:39]
	v_mfma_f32_16x16x32_bf16 v[32:35], v[178:181], v[194:197], v[32:35]
	v_mfma_f32_16x16x32_bf16 v[20:23], v[170:173], v[202:205], v[20:23]
	v_mfma_f32_16x16x32_bf16 v[16:19], v[178:181], v[202:205], v[16:19]
	v_mfma_f32_16x16x32_bf16 v[4:7], v[170:173], v[210:213], v[4:7]
	v_mfma_f32_16x16x32_bf16 v[0:3], v[178:181], v[210:213], v[0:3]
	s_setprio 0
	s_barrier
	s_add_i32 s67, s67, 2
	s_add_u32 s65, s65, 0x10000
	s_addc_u32 s66, s66, 0
	s_add_u32 s24, s24, 0x100
	s_addc_u32 s25, s25, 0
	s_cmp_gt_u32 s67, 29
	s_cbranch_scc0 .LBB0_499
	s_and_b64 vcc, exec, s[28:29]
	s_cbranch_vccz .LBB0_502
	s_barrier

; #define PG8_STAGE(bufoff, gbase, voff) do { _Pragma("unroll") for (int _i = 0; _i < 2; ++_i) \
;         __builtin_amdgcn_global_load_lds((const unsigned*)((const char*)(gbase) + (voff)[_i]), (LAS unsigned*)(lds + (bufoff) + ldsw + _i * 8192), 16, 0, 0); } while (0)
; #define PG8_LDA(dst, b, h) do { _Pragma("unroll") for (int m = 0; m < 4; ++m) _Pragma("unroll") for (int k = 0; k < 2; ++k) dst[m][k] = *(const LAS bf16x8*)(lds + PG8_SA(b, h) + aoff + m * 2048 + k * 1024); } while (0)
; #define PG8_LDB(dst, b, h) do { _Pragma("unroll") for (int n = 0; n < 2; ++n) _Pragma("unroll") for (int k = 0; k < 2; ++k) dst[n][k] = *(const LAS bf16x8*)(lds + PG8_SB(b, h) + boff + n * 2048 + k * 1024); } while (0)
; #define PG8_MMA(ai, bj, At, Bt) do { __builtin_amdgcn_s_setprio(1); _Pragma("unroll") for (int m = 0; m < 4; ++m) _Pragma("unroll") for (int n = 0; n < 2; ++n) _Pragma("unroll") for (int k = 0; k < 2; ++k) \
;         acc[ai][bj][m][n] = __builtin_amdgcn_mfma_f32_16x16x32_bf16(Bt[n][k], At[m][k], acc[ai][bj][m][n], 0, 0, 0); __builtin_amdgcn_s_setprio(0); } while (0)
; #define PG8_WAIT_V(n) asm volatile("s_waitcnt vmcnt(" #n ")" ::: "memory")
; #define PG8_WAIT_L(n) asm volatile("s_waitcnt lgkmcnt(" #n ")" ::: "memory")
; #define PG8_BAR __builtin_amdgcn_s_barrier()
; #define PG8_SCHED __builtin_amdgcn_sched_barrier(0)
; template <class Epi, class Sched, bool ALIGN_EPI>
; __device__ __forceinline__ void gemm_phase(LAS unsigned char* lds, const Gemm g, const Sched& S, const Epi& E, const int wid) {
;     ...
;             const char* a1 = cA + (size_t)(t + 1) * kstepA;
;             const char* a2 = last ? nA : cA + (size_t)(t + 2) * kstepA; const char* b2 = last ? nB : cB + (size_t)(t + 2) * kstep;
;             const char* a3 = a2 + kstepA; const char* b3 = b2 + kstep;
;             PG8_LDB(B0, 0, 0); PG8_LDB(B1, 0, 1); PG8_SCHED; PG8_LDA(At, 0, 0); PG8_STAGE(PG8_SA(1, 1), a1 + hstepA, voffA);
;             PG8_WAIT_V(8); PG8_WAIT_L(0); PG8_BAR; PG8_MMA(0, 0, At, B0); PG8_MMA(0, 1, At, B1); PG8_BAR; PG8_SCHED;
;             PG8_LDA(At, 0, 1); PG8_STAGE(PG8_SB(0, 0), b2, voffB); PG8_STAGE(PG8_SB(0, 1), b2 + hstepB, voffB); PG8_STAGE(PG8_SA(0, 0), a2, voffA);
;             PG8_WAIT_V(8); PG8_WAIT_L(0); PG8_BAR; PG8_MMA(1, 0, At, B0); PG8_MMA(1, 1, At, B1); PG8_BAR; PG8_SCHED;
.LBB0_579:
	ds_read_b128 v[120:123], v184
	ds_read_b128 v[132:135], v184 offset:1024
	ds_read_b128 v[136:139], v184 offset:2048
	ds_read_b128 v[140:143], v184 offset:3072
	ds_read_b128 v[144:147], v185
	ds_read_b128 v[148:151], v185 offset:1024
	ds_read_b128 v[152:155], v185 offset:2048
	ds_read_b128 v[176:179], v185 offset:3072
	s_add_u32 s38, s58, 0xfff00080
	s_addc_u32 s39, s59, -1
	s_cmp_eq_u32 s57, 60
	s_cselect_b32 s63, s23, s39
	s_cselect_b32 s62, s35, s38
	s_cselect_b32 s61, s21, s55
	s_cselect_b32 s60, s52, s53
	s_add_i32 m0, s4, 0xc000
	ds_read_b128 v[188:191], v186
	ds_read_b128 v[192:195], v186 offset:1024
	ds_read_b128 v[196:199], v186 offset:2048
	ds_read_b128 v[200:203], v186 offset:3072
	ds_read_b128 v[204:207], v186 offset:4096
	ds_read_b128 v[208:211], v186 offset:5120
	ds_read_b128 v[212:215], v186 offset:6144
	ds_read_b128 v[216:219], v186 offset:7168
	global_load_lds_dwordx4 v168, s[58:59]
	s_add_i32 m0, s4, 0xe000
	s_nop 0
	global_load_lds_dwordx4 v170, s[58:59]
	s_waitcnt vmcnt(8)
	s_waitcnt lgkmcnt(0)
	s_barrier
	s_setprio 1
	s_waitcnt lgkmcnt(0)
	v_mfma_f32_16x16x32_bf16 v[128:131], v[120:123], v[188:191], v[128:131]
	v_mfma_f32_16x16x32_bf16 v[124:127], v[136:139], v[188:191], v[124:127]
	v_mfma_f32_16x16x32_bf16 v[108:111], v[120:123], v[196:199], v[108:111]
	v_mfma_f32_16x16x32_bf16 v[104:107], v[136:139], v[196:199], v[104:107]
	v_mfma_f32_16x16x32_bf16 v[92:95], v[120:123], v[204:207], v[92:95]
	v_mfma_f32_16x16x32_bf16 v[88:91], v[136:139], v[204:207], v[88:91]
	v_mfma_f32_16x16x32_bf16 v[76:79], v[120:123], v[212:215], v[76:79]
	v_mfma_f32_16x16x32_bf16 v[72:75], v[136:139], v[212:215], v[72:75]
	v_mfma_f32_16x16x32_bf16 v[128:131], v[132:135], v[192:195], v[128:131]
	v_mfma_f32_16x16x32_bf16 v[124:127], v[140:143], v[192:195], v[124:127]
	v_mfma_f32_16x16x32_bf16 v[108:111], v[132:135], v[200:203], v[108:111]
	v_mfma_f32_16x16x32_bf16 v[104:107], v[140:143], v[200:203], v[104:107]
	v_mfma_f32_16x16x32_bf16 v[92:95], v[132:135], v[208:211], v[92:95]
	v_mfma_f32_16x16x32_bf16 v[88:91], v[140:143], v[208:211], v[88:91]
	v_mfma_f32_16x16x32_bf16 v[76:79], v[132:135], v[216:219], v[76:79]
	v_mfma_f32_16x16x32_bf16 v[72:75], v[140:143], v[216:219], v[72:75]
	s_setprio 0
	s_setprio 1
	v_mfma_f32_16x16x32_bf16 v[116:119], v[144:147], v[188:191], v[116:119]
	v_mfma_f32_16x16x32_bf16 v[112:115], v[152:155], v[188:191], v[112:115]
	v_mfma_f32_16x16x32_bf16 v[100:103], v[144:147], v[196:199], v[100:103]
	v_mfma_f32_16x16x32_bf16 v[96:99], v[152:155], v[196:199], v[96:99]
	v_mfma_f32_16x16x32_bf16 v[84:87], v[144:147], v[204:207], v[84:87]
	v_mfma_f32_16x16x32_bf16 v[80:83], v[152:155], v[204:207], v[80:83]
	v_mfma_f32_16x16x32_bf16 v[68:71], v[144:147], v[212:215], v[68:71]
	v_mfma_f32_16x16x32_bf16 v[64:67], v[152:155], v[212:215], v[64:67]
	v_mfma_f32_16x16x32_bf16 v[116:119], v[148:151], v[192:195], v[116:119]
	v_mfma_f32_16x16x32_bf16 v[112:115], v[176:179], v[192:195], v[112:115]
	v_mfma_f32_16x16x32_bf16 v[100:103], v[148:151], v[200:203], v[100:103]
	v_mfma_f32_16x16x32_bf16 v[96:99], v[176:179], v[200:203], v[96:99]
	v_mfma_f32_16x16x32_bf16 v[84:87], v[148:151], v[208:211], v[84:87]
	v_mfma_f32_16x16x32_bf16 v[80:83], v[176:179], v[208:211], v[80:83]
	v_mfma_f32_16x16x32_bf16 v[68:71], v[148:151], v[216:219], v[68:71]
	v_mfma_f32_16x16x32_bf16 v[64:67], v[176:179], v[216:219], v[64:67]
	s_setprio 0
	s_barrier
	s_add_i32 s38, s66, s3
	s_mov_b32 m0, s38
	ds_read_b128 v[188:191], v186 offset:16384
	ds_read_b128 v[192:195], v186 offset:17408
	ds_read_b128 v[196:199], v186 offset:18432
	ds_read_b128 v[200:203], v186 offset:19456
	ds_read_b128 v[204:207], v186 offset:20480
	ds_read_b128 v[208:211], v186 offset:21504
	ds_read_b128 v[212:215], v186 offset:22528
	ds_read_b128 v[216:219], v186 offset:23552
	global_load_lds_dwordx4 v158, s[60:61]
	s_add_i32 m0, s38, 0x2000
	s_add_u32 s70, s60, 0x1000
	s_addc_u32 s71, s61, 0
	s_add_i32 s38, s67, s3
	global_load_lds_dwordx4 v162, s[60:61]
	s_mov_b32 m0, s38
	v_lshl_add_u64 v[220:221], s[62:63], 0, v[160:161]
	global_load_lds_dwordx4 v158, s[70:71]
	s_add_i32 m0, s38, 0x2000
	s_nop 0
	global_load_lds_dwordx4 v162, s[70:71]
	v_lshl_add_u64 v[180:181], s[62:63], 0, v[156:157]
	s_mov_b32 m0, s4
	s_nop 0
	global_load_lds_dwordx4 v[180:181], off
	s_mov_b32 m0, s5
	s_nop 0
	global_load_lds_dwordx4 v[220:221], off
	s_waitcnt vmcnt(8)
	s_waitcnt lgkmcnt(0)
	s_barrier
	s_setprio 1
	s_waitcnt lgkmcnt(0)
	v_mfma_f32_16x16x32_bf16 v[60:63], v[120:123], v[188:191], v[60:63]
	v_mfma_f32_16x16x32_bf16 v[56:59], v[136:139], v[188:191], v[56:59]
	v_mfma_f32_16x16x32_bf16 v[44:47], v[120:123], v[196:199], v[44:47]
	v_mfma_f32_16x16x32_bf16 v[40:43], v[136:139], v[196:199], v[40:43]
	v_mfma_f32_16x16x32_bf16 v[28:31], v[120:123], v[204:207], v[28:31]
	v_mfma_f32_16x16x32_bf16 v[24:27], v[136:139], v[204:207], v[24:27]
	v_mfma_f32_16x16x32_bf16 v[12:15], v[120:123], v[212:215], v[12:15]
	v_mfma_f32_16x16x32_bf16 v[8:11], v[136:139], v[212:215], v[8:11]
	v_mfma_f32_16x16x32_bf16 v[60:63], v[132:135], v[192:195], v[60:63]
	v_mfma_f32_16x16x32_bf16 v[56:59], v[140:143], v[192:195], v[56:59]
	v_mfma_f32_16x16x32_bf16 v[44:47], v[132:135], v[200:203], v[44:47]
	v_mfma_f32_16x16x32_bf16 v[40:43], v[140:143], v[200:203], v[40:43]
	v_mfma_f32_16x16x32_bf16 v[28:31], v[132:135], v[208:211], v[28:31]
	v_mfma_f32_16x16x32_bf16 v[24:27], v[140:143], v[208:211], v[24:27]
	v_mfma_f32_16x16x32_bf16 v[12:15], v[132:135], v[216:219], v[12:15]
	v_mfma_f32_16x16x32_bf16 v[8:11], v[140:143], v[216:219], v[8:11]
	s_setprio 0
	s_setprio 1
	v_mfma_f32_16x16x32_bf16 v[52:55], v[144:147], v[188:191], v[52:55]
	v_mfma_f32_16x16x32_bf16 v[48:51], v[152:155], v[188:191], v[48:51]
	v_mfma_f32_16x16x32_bf16 v[36:39], v[144:147], v[196:199], v[36:39]
	v_mfma_f32_16x16x32_bf16 v[32:35], v[152:155], v[196:199], v[32:35]
	v_mfma_f32_16x16x32_bf16 v[20:23], v[144:147], v[204:207], v[20:23]
	v_mfma_f32_16x16x32_bf16 v[16:19], v[152:155], v[204:207], v[16:19]
	v_mfma_f32_16x16x32_bf16 v[4:7], v[144:147], v[212:215], v[4:7]
	v_mfma_f32_16x16x32_bf16 v[0:3], v[152:155], v[212:215], v[0:3]
	v_mfma_f32_16x16x32_bf16 v[52:55], v[148:151], v[192:195], v[52:55]
	v_mfma_f32_16x16x32_bf16 v[48:51], v[176:179], v[192:195], v[48:51]
	v_mfma_f32_16x16x32_bf16 v[36:39], v[148:151], v[200:203], v[36:39]
	v_mfma_f32_16x16x32_bf16 v[32:35], v[176:179], v[200:203], v[32:35]
	v_mfma_f32_16x16x32_bf16 v[20:23], v[148:151], v[208:211], v[20:23]
	v_mfma_f32_16x16x32_bf16 v[16:19], v[176:179], v[208:211], v[16:19]
	v_mfma_f32_16x16x32_bf16 v[4:7], v[148:151], v[216:219], v[4:7]
	v_mfma_f32_16x16x32_bf16 v[0:3], v[176:179], v[216:219], v[0:3]
	s_setprio 0
	s_barrier
; #define PG8_STAGE(bufoff, gbase, voff) do { _Pragma("unroll") for (int _i = 0; _i < 2; ++_i) \
;         __builtin_amdgcn_global_load_lds((const unsigned*)((const char*)(gbase) + (voff)[_i]), (LAS unsigned*)(lds + (bufoff) + ldsw + _i * 8192), 16, 0, 0); } while (0)
; #define PG8_LDA(dst, b, h) do { _Pragma("unroll") for (int m = 0; m < 4; ++m) _Pragma("unroll") for (int k = 0; k < 2; ++k) dst[m][k] = *(const LAS bf16x8*)(lds + PG8_SA(b, h) + aoff + m * 2048 + k * 1024); } while (0)
; #define PG8_LDB(dst, b, h) do { _Pragma("unroll") for (int n = 0; n < 2; ++n) _Pragma("unroll") for (int k = 0; k < 2; ++k) dst[n][k] = *(const LAS bf16x8*)(lds + PG8_SB(b, h) + boff + n * 2048 + k * 1024); } while (0)
; #define PG8_MMA(ai, bj, At, Bt) do { __builtin_amdgcn_s_setprio(1); _Pragma("unroll") for (int m = 0; m < 4; ++m) _Pragma("unroll") for (int n = 0; n < 2; ++n) _Pragma("unroll") for (int k = 0; k < 2; ++k) \
;         acc[ai][bj][m][n] = __builtin_amdgcn_mfma_f32_16x16x32_bf16(Bt[n][k], At[m][k], acc[ai][bj][m][n], 0, 0, 0); __builtin_amdgcn_s_setprio(0); } while (0)
; #define PG8_WAIT_V(n) asm volatile("s_waitcnt vmcnt(" #n ")" ::: "memory")
; #define PG8_WAIT_L(n) asm volatile("s_waitcnt lgkmcnt(" #n ")" ::: "memory")
; #define PG8_BAR __builtin_amdgcn_s_barrier()
; #define PG8_SCHED __builtin_amdgcn_sched_barrier(0)
; template <class Epi, class Sched, bool ALIGN_EPI>
; __device__ __forceinline__ void gemm_phase(LAS unsigned char* lds, const Gemm g, const Sched& S, const Epi& E, const int wid) {
;     ...
;             PG8_LDB(B0, 1, 0); PG8_LDB(B1, 1, 1); PG8_SCHED; PG8_LDA(At, 1, 0); PG8_STAGE(PG8_SA(0, 1), a2 + hstepA, voffA);
;             PG8_WAIT_V(8); PG8_WAIT_L(0); PG8_BAR; PG8_MMA(0, 0, At, B0); PG8_MMA(0, 1, At, B1); PG8_BAR; PG8_SCHED;
;             PG8_LDA(At, 1, 1); PG8_STAGE(PG8_SB(1, 0), b3, voffB); PG8_STAGE(PG8_SB(1, 1), b3 + hstepB, voffB); PG8_STAGE(PG8_SA(1, 0), a3, voffA);
;             PG8_WAIT_V(8); PG8_WAIT_L(0); PG8_BAR; PG8_MMA(1, 0, At, B0); PG8_MMA(1, 1, At, B1); PG8_BAR; PG8_SCHED;
;         }
;         if constexpr (ALIGN_EPI) { if (wr == 0) PG8_BAR; }
	s_add_i32 s38, 0, 0x18000
	s_add_i32 s39, 0, 0x1c000
	v_add_u32_e32 v140, s38, v182
	v_add_u32_e32 v164, s39, v182
	ds_read_b128 v[120:123], v140
	ds_read_b128 v[132:135], v140 offset:1024
	ds_read_b128 v[136:139], v140 offset:2048
	ds_read_b128 v[140:143], v140 offset:3072
	ds_read_b128 v[144:147], v164
	ds_read_b128 v[148:151], v164 offset:1024
	ds_read_b128 v[152:155], v164 offset:2048
	ds_read_b128 v[176:179], v164 offset:3072
	s_add_u32 s62, s62, 0x100000
	s_addc_u32 s63, s63, 0
	s_mov_b32 m0, s44
	ds_read_b128 v[188:191], v186 offset:32768
	ds_read_b128 v[192:195], v186 offset:33792
	ds_read_b128 v[196:199], v186 offset:34816
	ds_read_b128 v[200:203], v186 offset:35840
	ds_read_b128 v[204:207], v186 offset:36864
	ds_read_b128 v[208:211], v186 offset:37888
	ds_read_b128 v[212:215], v186 offset:38912
	ds_read_b128 v[216:219], v186 offset:39936
	global_load_lds_dwordx4 v156, s[62:63]
	s_mov_b32 m0, s45
	s_nop 0
	global_load_lds_dwordx4 v160, s[62:63]
	s_waitcnt vmcnt(8)
	s_waitcnt lgkmcnt(0)
	s_barrier
	s_setprio 1
	s_waitcnt lgkmcnt(0)
	v_mfma_f32_16x16x32_bf16 v[128:131], v[120:123], v[188:191], v[128:131]
	v_mfma_f32_16x16x32_bf16 v[124:127], v[136:139], v[188:191], v[124:127]
	v_mfma_f32_16x16x32_bf16 v[108:111], v[120:123], v[196:199], v[108:111]
	v_mfma_f32_16x16x32_bf16 v[104:107], v[136:139], v[196:199], v[104:107]
	v_mfma_f32_16x16x32_bf16 v[92:95], v[120:123], v[204:207], v[92:95]
	v_mfma_f32_16x16x32_bf16 v[88:91], v[136:139], v[204:207], v[88:91]
	v_mfma_f32_16x16x32_bf16 v[76:79], v[120:123], v[212:215], v[76:79]
	v_mfma_f32_16x16x32_bf16 v[72:75], v[136:139], v[212:215], v[72:75]
	v_mfma_f32_16x16x32_bf16 v[128:131], v[132:135], v[192:195], v[128:131]
	v_mfma_f32_16x16x32_bf16 v[124:127], v[140:143], v[192:195], v[124:127]
	v_mfma_f32_16x16x32_bf16 v[108:111], v[132:135], v[200:203], v[108:111]
	v_mfma_f32_16x16x32_bf16 v[104:107], v[140:143], v[200:203], v[104:107]
	v_mfma_f32_16x16x32_bf16 v[92:95], v[132:135], v[208:211], v[92:95]
	v_mfma_f32_16x16x32_bf16 v[88:91], v[140:143], v[208:211], v[88:91]
	v_mfma_f32_16x16x32_bf16 v[76:79], v[132:135], v[216:219], v[76:79]
	v_mfma_f32_16x16x32_bf16 v[72:75], v[140:143], v[216:219], v[72:75]
	s_setprio 0
	s_setprio 1
	v_mfma_f32_16x16x32_bf16 v[116:119], v[144:147], v[188:191], v[116:119]
	v_mfma_f32_16x16x32_bf16 v[112:115], v[152:155], v[188:191], v[112:115]
	v_mfma_f32_16x16x32_bf16 v[100:103], v[144:147], v[196:199], v[100:103]
	v_mfma_f32_16x16x32_bf16 v[96:99], v[152:155], v[196:199], v[96:99]
	v_mfma_f32_16x16x32_bf16 v[84:87], v[144:147], v[204:207], v[84:87]
	v_mfma_f32_16x16x32_bf16 v[80:83], v[152:155], v[204:207], v[80:83]
	v_mfma_f32_16x16x32_bf16 v[68:71], v[144:147], v[212:215], v[68:71]
	v_mfma_f32_16x16x32_bf16 v[64:67], v[152:155], v[212:215], v[64:67]
	v_mfma_f32_16x16x32_bf16 v[116:119], v[148:151], v[192:195], v[116:119]
	v_mfma_f32_16x16x32_bf16 v[112:115], v[176:179], v[192:195], v[112:115]
	v_mfma_f32_16x16x32_bf16 v[100:103], v[148:151], v[200:203], v[100:103]
	v_mfma_f32_16x16x32_bf16 v[96:99], v[176:179], v[200:203], v[96:99]
	v_mfma_f32_16x16x32_bf16 v[84:87], v[148:151], v[208:211], v[84:87]
	v_mfma_f32_16x16x32_bf16 v[80:83], v[176:179], v[208:211], v[80:83]
	v_mfma_f32_16x16x32_bf16 v[68:71], v[148:151], v[216:219], v[68:71]
	v_mfma_f32_16x16x32_bf16 v[64:67], v[176:179], v[216:219], v[64:67]
	s_setprio 0
	s_barrier
	s_add_u32 s62, s60, 0x8000
	s_addc_u32 s63, s61, 0
	s_add_i32 s38, s38, s3
	s_mov_b32 m0, s38
	ds_read_b128 v[188:191], v186 offset:49152
	ds_read_b128 v[192:195], v186 offset:50176
	ds_read_b128 v[196:199], v186 offset:51200
	ds_read_b128 v[200:203], v186 offset:52224
	ds_read_b128 v[204:207], v186 offset:53248
	ds_read_b128 v[208:211], v186 offset:54272
	ds_read_b128 v[212:215], v186 offset:55296
	ds_read_b128 v[216:219], v186 offset:56320
	global_load_lds_dwordx4 v158, s[62:63]
	s_add_i32 m0, s38, 0x2000
	s_add_u32 s60, s60, 0x9000
	s_addc_u32 s61, s61, 0
	s_add_i32 s38, s39, s3
	global_load_lds_dwordx4 v162, s[62:63]
	s_mov_b32 m0, s38
	v_lshl_add_u64 v[180:181], v[180:181], 0, s[16:17]
	global_load_lds_dwordx4 v158, s[60:61]
	s_add_i32 m0, s38, 0x2000
	s_nop 0
	global_load_lds_dwordx4 v162, s[60:61]
	s_mov_b32 m0, s64
	s_nop 0
	global_load_lds_dwordx4 v[180:181], off
	v_lshl_add_u64 v[180:181], v[220:221], 0, s[16:17]
	s_mov_b32 m0, s65
	s_nop 0
	global_load_lds_dwordx4 v[180:181], off
	s_waitcnt vmcnt(8)
	s_waitcnt lgkmcnt(0)
	s_barrier
	s_setprio 1
	s_waitcnt lgkmcnt(0)
	v_mfma_f32_16x16x32_bf16 v[60:63], v[120:123], v[188:191], v[60:63]
	v_mfma_f32_16x16x32_bf16 v[56:59], v[136:139], v[188:191], v[56:59]
	v_mfma_f32_16x16x32_bf16 v[44:47], v[120:123], v[196:199], v[44:47]
	v_mfma_f32_16x16x32_bf16 v[40:43], v[136:139], v[196:199], v[40:43]
	v_mfma_f32_16x16x32_bf16 v[28:31], v[120:123], v[204:207], v[28:31]
	v_mfma_f32_16x16x32_bf16 v[24:27], v[136:139], v[204:207], v[24:27]
	v_mfma_f32_16x16x32_bf16 v[12:15], v[120:123], v[212:215], v[12:15]
	v_mfma_f32_16x16x32_bf16 v[8:11], v[136:139], v[212:215], v[8:11]
	v_mfma_f32_16x16x32_bf16 v[60:63], v[132:135], v[192:195], v[60:63]
	v_mfma_f32_16x16x32_bf16 v[56:59], v[140:143], v[192:195], v[56:59]
	v_mfma_f32_16x16x32_bf16 v[44:47], v[132:135], v[200:203], v[44:47]
	v_mfma_f32_16x16x32_bf16 v[40:43], v[140:143], v[200:203], v[40:43]
	v_mfma_f32_16x16x32_bf16 v[28:31], v[132:135], v[208:211], v[28:31]
	v_mfma_f32_16x16x32_bf16 v[24:27], v[140:143], v[208:211], v[24:27]
	v_mfma_f32_16x16x32_bf16 v[12:15], v[132:135], v[216:219], v[12:15]
	v_mfma_f32_16x16x32_bf16 v[8:11], v[140:143], v[216:219], v[8:11]
	s_setprio 0
	s_setprio 1
	v_mfma_f32_16x16x32_bf16 v[52:55], v[144:147], v[188:191], v[52:55]
	v_mfma_f32_16x16x32_bf16 v[48:51], v[152:155], v[188:191], v[48:51]
	v_mfma_f32_16x16x32_bf16 v[36:39], v[144:147], v[196:199], v[36:39]
	v_mfma_f32_16x16x32_bf16 v[32:35], v[152:155], v[196:199], v[32:35]
	v_mfma_f32_16x16x32_bf16 v[20:23], v[144:147], v[204:207], v[20:23]
	v_mfma_f32_16x16x32_bf16 v[16:19], v[152:155], v[204:207], v[16:19]
	v_mfma_f32_16x16x32_bf16 v[4:7], v[144:147], v[212:215], v[4:7]
	v_mfma_f32_16x16x32_bf16 v[0:3], v[152:155], v[212:215], v[0:3]
	v_mfma_f32_16x16x32_bf16 v[52:55], v[148:151], v[192:195], v[52:55]
	v_mfma_f32_16x16x32_bf16 v[48:51], v[176:179], v[192:195], v[48:51]
	v_mfma_f32_16x16x32_bf16 v[36:39], v[148:151], v[200:203], v[36:39]
	v_mfma_f32_16x16x32_bf16 v[32:35], v[176:179], v[200:203], v[32:35]
	v_mfma_f32_16x16x32_bf16 v[20:23], v[148:151], v[208:211], v[20:23]
	v_mfma_f32_16x16x32_bf16 v[16:19], v[176:179], v[208:211], v[16:19]
	v_mfma_f32_16x16x32_bf16 v[4:7], v[148:151], v[216:219], v[4:7]
	v_mfma_f32_16x16x32_bf16 v[0:3], v[176:179], v[216:219], v[0:3]
	s_setprio 0
	s_barrier
	s_add_i32 s57, s57, 2
	s_add_u32 s53, s53, 0x10000
	s_addc_u32 s55, s55, 0
	s_add_u32 s58, s58, 0x100
	s_addc_u32 s59, s59, 0
	s_cmp_gt_u32 s57, 61
	s_cbranch_scc0 .LBB0_579
	s_and_b64 vcc, exec, s[28:29]
	s_cbranch_vccz .LBB0_582
	s_barrier

; #define PG8_STAGE(bufoff, gbase, voff) do { _Pragma("unroll") for (int _i = 0; _i < 2; ++_i) \
;         __builtin_amdgcn_global_load_lds((const unsigned*)((const char*)(gbase) + (voff)[_i]), (LAS unsigned*)(lds + (bufoff) + ldsw + _i * 8192), 16, 0, 0); } while (0)
; #define PG8_LDA(dst, b, h) do { _Pragma("unroll") for (int m = 0; m < 4; ++m) _Pragma("unroll") for (int k = 0; k < 2; ++k) dst[m][k] = *(const LAS bf16x8*)(lds + PG8_SA(b, h) + aoff + m * 2048 + k * 1024); } while (0)
; #define PG8_LDB(dst, b, h) do { _Pragma("unroll") for (int n = 0; n < 2; ++n) _Pragma("unroll") for (int k = 0; k < 2; ++k) dst[n][k] = *(const LAS bf16x8*)(lds + PG8_SB(b, h) + boff + n * 2048 + k * 1024); } while (0)
; #define PG8_MMA(ai, bj, At, Bt) do { __builtin_amdgcn_s_setprio(1); _Pragma("unroll") for (int m = 0; m < 4; ++m) _Pragma("unroll") for (int n = 0; n < 2; ++n) _Pragma("unroll") for (int k = 0; k < 2; ++k) \
;         acc[ai][bj][m][n] = __builtin_amdgcn_mfma_f32_16x16x32_bf16(Bt[n][k], At[m][k], acc[ai][bj][m][n], 0, 0, 0); __builtin_amdgcn_s_setprio(0); } while (0)
; #define PG8_WAIT_V(n) asm volatile("s_waitcnt vmcnt(" #n ")" ::: "memory")
; #define PG8_WAIT_L(n) asm volatile("s_waitcnt lgkmcnt(" #n ")" ::: "memory")
; #define PG8_BAR __builtin_amdgcn_s_barrier()
; #define PG8_SCHED __builtin_amdgcn_sched_barrier(0)
; template <class Epi, class Sched, bool ALIGN_EPI>
; __device__ __forceinline__ void gemm_phase(LAS unsigned char* lds, const Gemm g, const Sched& S, const Epi& E, const int wid) {
;     ...
;             const char* a1 = cA + (size_t)(t + 1) * kstepA;
;             const char* a2 = last ? nA : cA + (size_t)(t + 2) * kstepA; const char* b2 = last ? nB : cB + (size_t)(t + 2) * kstep;
;             const char* a3 = a2 + kstepA; const char* b3 = b2 + kstep;
;             PG8_LDB(B0, 0, 0); PG8_LDB(B1, 0, 1); PG8_SCHED; PG8_LDA(At, 0, 0); PG8_STAGE(PG8_SA(1, 1), a1 + hstepA, voffA);
;             PG8_WAIT_V(8); PG8_WAIT_L(0); PG8_BAR; PG8_MMA(0, 0, At, B0); PG8_MMA(0, 1, At, B1); PG8_BAR; PG8_SCHED;
;             PG8_LDA(At, 0, 1); PG8_STAGE(PG8_SB(0, 0), b2, voffB); PG8_STAGE(PG8_SB(0, 1), b2 + hstepB, voffB); PG8_STAGE(PG8_SA(0, 0), a2, voffA);
;             PG8_WAIT_V(8); PG8_WAIT_L(0); PG8_BAR; PG8_MMA(1, 0, At, B0); PG8_MMA(1, 1, At, B1); PG8_BAR; PG8_SCHED;
.LBB0_687:
	s_add_u32 s38, s18, 0x4000
	s_addc_u32 s39, s19, 0
	s_and_b64 s[62:63], s[64:65], exec
	s_cselect_b32 s66, s35, s38
	s_cselect_b32 s67, s27, s39
	s_add_u32 s62, s66, 0x8000
	s_addc_u32 s63, s67, 0
	s_add_i32 s38, 0, 0x10000
	v_add_u32_e32 v138, s38, v160
	ds_read_b128 v[130:133], v138
	ds_read_b128 v[134:137], v138 offset:1024
	ds_read_b128 v[170:173], v138 offset:2048
	ds_read_b128 v[174:177], v138 offset:3072
	v_add_u32_e32 v138, s53, v160
	ds_read_b128 v[178:181], v138
	ds_read_b128 v[182:185], v138 offset:1024
	ds_read_b128 v[186:189], v138 offset:2048
	ds_read_b128 v[190:193], v138 offset:3072
	s_and_b64 s[64:65], s[64:65], exec
	s_cselect_b32 s65, s25, s70
	s_cselect_b32 s64, s61, s69
	s_add_i32 m0, s23, 0xc000
	ds_read_b128 v[194:197], v166
	ds_read_b128 v[198:201], v166 offset:1024
	ds_read_b128 v[202:205], v166 offset:2048
	ds_read_b128 v[206:209], v166 offset:3072
	ds_read_b128 v[210:213], v166 offset:4096
	ds_read_b128 v[214:217], v166 offset:5120
	ds_read_b128 v[218:221], v166 offset:6144
	ds_read_b128 v[222:225], v166 offset:7168
	global_load_lds_dwordx4 v150, s[18:19]
	s_add_i32 m0, s23, 0xe000
	s_nop 0
	global_load_lds_dwordx4 v152, s[18:19]
	s_waitcnt vmcnt(8)
	s_waitcnt lgkmcnt(0)
	s_barrier
	s_setprio 1
	s_waitcnt lgkmcnt(0)
	v_mfma_f32_16x16x32_bf16 v[124:127], v[130:133], v[194:197], v[124:127]
	v_mfma_f32_16x16x32_bf16 v[120:123], v[170:173], v[194:197], v[120:123]
	v_mfma_f32_16x16x32_bf16 v[108:111], v[130:133], v[202:205], v[108:111]
	v_mfma_f32_16x16x32_bf16 v[104:107], v[170:173], v[202:205], v[104:107]
	v_mfma_f32_16x16x32_bf16 v[92:95], v[130:133], v[210:213], v[92:95]
	v_mfma_f32_16x16x32_bf16 v[88:91], v[170:173], v[210:213], v[88:91]
	v_mfma_f32_16x16x32_bf16 v[76:79], v[130:133], v[218:221], v[76:79]
	v_mfma_f32_16x16x32_bf16 v[72:75], v[170:173], v[218:221], v[72:75]
	v_mfma_f32_16x16x32_bf16 v[124:127], v[134:137], v[198:201], v[124:127]
	v_mfma_f32_16x16x32_bf16 v[120:123], v[174:177], v[198:201], v[120:123]
	v_mfma_f32_16x16x32_bf16 v[108:111], v[134:137], v[206:209], v[108:111]
	v_mfma_f32_16x16x32_bf16 v[104:107], v[174:177], v[206:209], v[104:107]
	v_mfma_f32_16x16x32_bf16 v[92:95], v[134:137], v[214:217], v[92:95]
	v_mfma_f32_16x16x32_bf16 v[88:91], v[174:177], v[214:217], v[88:91]
	v_mfma_f32_16x16x32_bf16 v[76:79], v[134:137], v[222:225], v[76:79]
	v_mfma_f32_16x16x32_bf16 v[72:75], v[174:177], v[222:225], v[72:75]
	s_setprio 0
	s_setprio 1
	v_mfma_f32_16x16x32_bf16 v[116:119], v[178:181], v[194:197], v[116:119]
	v_mfma_f32_16x16x32_bf16 v[112:115], v[186:189], v[194:197], v[112:115]
	v_mfma_f32_16x16x32_bf16 v[100:103], v[178:181], v[202:205], v[100:103]
	v_mfma_f32_16x16x32_bf16 v[96:99], v[186:189], v[202:205], v[96:99]
	v_mfma_f32_16x16x32_bf16 v[84:87], v[178:181], v[210:213], v[84:87]
	v_mfma_f32_16x16x32_bf16 v[80:83], v[186:189], v[210:213], v[80:83]
	v_mfma_f32_16x16x32_bf16 v[68:71], v[178:181], v[218:221], v[68:71]
	v_mfma_f32_16x16x32_bf16 v[64:67], v[186:189], v[218:221], v[64:67]
	v_mfma_f32_16x16x32_bf16 v[116:119], v[182:185], v[198:201], v[116:119]
	v_mfma_f32_16x16x32_bf16 v[112:115], v[190:193], v[198:201], v[112:115]
	v_mfma_f32_16x16x32_bf16 v[100:103], v[182:185], v[206:209], v[100:103]
	v_mfma_f32_16x16x32_bf16 v[96:99], v[190:193], v[206:209], v[96:99]
	v_mfma_f32_16x16x32_bf16 v[84:87], v[182:185], v[214:217], v[84:87]
	v_mfma_f32_16x16x32_bf16 v[80:83], v[190:193], v[214:217], v[80:83]
	v_mfma_f32_16x16x32_bf16 v[68:71], v[182:185], v[222:225], v[68:71]
	v_mfma_f32_16x16x32_bf16 v[64:67], v[190:193], v[222:225], v[64:67]
	s_setprio 0
	s_barrier
	s_add_i32 s38, s38, s3
	s_mov_b32 m0, s38
	ds_read_b128 v[194:197], v166 offset:16384
	ds_read_b128 v[198:201], v166 offset:17408
	ds_read_b128 v[202:205], v166 offset:18432
	ds_read_b128 v[206:209], v166 offset:19456
	ds_read_b128 v[210:213], v166 offset:20480
	ds_read_b128 v[214:217], v166 offset:21504
	ds_read_b128 v[218:221], v166 offset:22528
	ds_read_b128 v[222:225], v166 offset:23552
	global_load_lds_dwordx4 v144, s[64:65]
	s_add_i32 m0, s38, 0x2000
	s_add_u32 s72, s64, 0x1000
	s_addc_u32 s73, s65, 0
	s_add_i32 s38, s53, s3
	global_load_lds_dwordx4 v140, s[64:65]
	s_mov_b32 m0, s38
	s_nop 0
	global_load_lds_dwordx4 v144, s[72:73]
	s_add_i32 m0, s38, 0x2000
	s_nop 0
	global_load_lds_dwordx4 v140, s[72:73]
	s_mov_b32 m0, s23
	s_nop 0
	global_load_lds_dwordx4 v146, s[66:67]
	s_mov_b32 m0, s30
	s_nop 0
	global_load_lds_dwordx4 v142, s[66:67]
	s_waitcnt vmcnt(8)
	s_waitcnt lgkmcnt(0)
	s_barrier
	s_setprio 1
	s_waitcnt lgkmcnt(0)
	v_mfma_f32_16x16x32_bf16 v[60:63], v[130:133], v[194:197], v[60:63]
	v_mfma_f32_16x16x32_bf16 v[56:59], v[170:173], v[194:197], v[56:59]
	v_mfma_f32_16x16x32_bf16 v[44:47], v[130:133], v[202:205], v[44:47]
	v_mfma_f32_16x16x32_bf16 v[40:43], v[170:173], v[202:205], v[40:43]
	v_mfma_f32_16x16x32_bf16 v[28:31], v[130:133], v[210:213], v[28:31]
	v_mfma_f32_16x16x32_bf16 v[24:27], v[170:173], v[210:213], v[24:27]
	v_mfma_f32_16x16x32_bf16 v[12:15], v[130:133], v[218:221], v[12:15]
	v_mfma_f32_16x16x32_bf16 v[8:11], v[170:173], v[218:221], v[8:11]
	v_mfma_f32_16x16x32_bf16 v[60:63], v[134:137], v[198:201], v[60:63]
	v_mfma_f32_16x16x32_bf16 v[56:59], v[174:177], v[198:201], v[56:59]
	v_mfma_f32_16x16x32_bf16 v[44:47], v[134:137], v[206:209], v[44:47]
	v_mfma_f32_16x16x32_bf16 v[40:43], v[174:177], v[206:209], v[40:43]
	v_mfma_f32_16x16x32_bf16 v[28:31], v[134:137], v[214:217], v[28:31]
	v_mfma_f32_16x16x32_bf16 v[24:27], v[174:177], v[214:217], v[24:27]
	v_mfma_f32_16x16x32_bf16 v[12:15], v[134:137], v[222:225], v[12:15]
	v_mfma_f32_16x16x32_bf16 v[8:11], v[174:177], v[222:225], v[8:11]
	s_setprio 0
	s_setprio 1
	v_mfma_f32_16x16x32_bf16 v[52:55], v[178:181], v[194:197], v[52:55]
	v_mfma_f32_16x16x32_bf16 v[48:51], v[186:189], v[194:197], v[48:51]
	v_mfma_f32_16x16x32_bf16 v[36:39], v[178:181], v[202:205], v[36:39]
	v_mfma_f32_16x16x32_bf16 v[32:35], v[186:189], v[202:205], v[32:35]
	v_mfma_f32_16x16x32_bf16 v[20:23], v[178:181], v[210:213], v[20:23]
	v_mfma_f32_16x16x32_bf16 v[16:19], v[186:189], v[210:213], v[16:19]
	v_mfma_f32_16x16x32_bf16 v[4:7], v[178:181], v[218:221], v[4:7]
	v_mfma_f32_16x16x32_bf16 v[0:3], v[186:189], v[218:221], v[0:3]
	v_mfma_f32_16x16x32_bf16 v[52:55], v[182:185], v[198:201], v[52:55]
	v_mfma_f32_16x16x32_bf16 v[48:51], v[190:193], v[198:201], v[48:51]
	v_mfma_f32_16x16x32_bf16 v[36:39], v[182:185], v[206:209], v[36:39]
	v_mfma_f32_16x16x32_bf16 v[32:35], v[190:193], v[206:209], v[32:35]
	v_mfma_f32_16x16x32_bf16 v[20:23], v[182:185], v[214:217], v[20:23]
	v_mfma_f32_16x16x32_bf16 v[16:19], v[190:193], v[214:217], v[16:19]
	v_mfma_f32_16x16x32_bf16 v[4:7], v[182:185], v[222:225], v[4:7]
	v_mfma_f32_16x16x32_bf16 v[0:3], v[190:193], v[222:225], v[0:3]
	s_setprio 0
	s_barrier
; #define PG8_STAGE(bufoff, gbase, voff) do { _Pragma("unroll") for (int _i = 0; _i < 2; ++_i) \
;         __builtin_amdgcn_global_load_lds((const unsigned*)((const char*)(gbase) + (voff)[_i]), (LAS unsigned*)(lds + (bufoff) + ldsw + _i * 8192), 16, 0, 0); } while (0)
; #define PG8_LDA(dst, b, h) do { _Pragma("unroll") for (int m = 0; m < 4; ++m) _Pragma("unroll") for (int k = 0; k < 2; ++k) dst[m][k] = *(const LAS bf16x8*)(lds + PG8_SA(b, h) + aoff + m * 2048 + k * 1024); } while (0)
; #define PG8_LDB(dst, b, h) do { _Pragma("unroll") for (int n = 0; n < 2; ++n) _Pragma("unroll") for (int k = 0; k < 2; ++k) dst[n][k] = *(const LAS bf16x8*)(lds + PG8_SB(b, h) + boff + n * 2048 + k * 1024); } while (0)
; #define PG8_MMA(ai, bj, At, Bt) do { __builtin_amdgcn_s_setprio(1); _Pragma("unroll") for (int m = 0; m < 4; ++m) _Pragma("unroll") for (int n = 0; n < 2; ++n) _Pragma("unroll") for (int k = 0; k < 2; ++k) \
;         acc[ai][bj][m][n] = __builtin_amdgcn_mfma_f32_16x16x32_bf16(Bt[n][k], At[m][k], acc[ai][bj][m][n], 0, 0, 0); __builtin_amdgcn_s_setprio(0); } while (0)
; #define PG8_WAIT_V(n) asm volatile("s_waitcnt vmcnt(" #n ")" ::: "memory")
; #define PG8_WAIT_L(n) asm volatile("s_waitcnt lgkmcnt(" #n ")" ::: "memory")
; #define PG8_BAR __builtin_amdgcn_s_barrier()
; #define PG8_SCHED __builtin_amdgcn_sched_barrier(0)
; template <class Epi, class Sched, bool ALIGN_EPI>
; __device__ __forceinline__ void gemm_phase(LAS unsigned char* lds, const Gemm g, const Sched& S, const Epi& E, const int wid) {
;     ...
;             PG8_LDB(B0, 1, 0); PG8_LDB(B1, 1, 1); PG8_SCHED; PG8_LDA(At, 1, 0); PG8_STAGE(PG8_SA(0, 1), a2 + hstepA, voffA);
;             PG8_WAIT_V(8); PG8_WAIT_L(0); PG8_BAR; PG8_MMA(0, 0, At, B0); PG8_MMA(0, 1, At, B1); PG8_BAR; PG8_SCHED;
;             PG8_LDA(At, 1, 1); PG8_STAGE(PG8_SB(1, 0), b3, voffB); PG8_STAGE(PG8_SB(1, 1), b3 + hstepB, voffB); PG8_STAGE(PG8_SA(1, 0), a3, voffA);
;             PG8_WAIT_V(8); PG8_WAIT_L(0); PG8_BAR; PG8_MMA(1, 0, At, B0); PG8_MMA(1, 1, At, B1); PG8_BAR; PG8_SCHED;
;         }
	s_add_i32 s38, 0, 0x18000
	v_add_u32_e32 v138, s38, v160
	s_add_i32 s39, 0, 0x1c000
	ds_read_b128 v[130:133], v138
	ds_read_b128 v[134:137], v138 offset:1024
	ds_read_b128 v[170:173], v138 offset:2048
	ds_read_b128 v[174:177], v138 offset:3072
	v_add_u32_e32 v138, s39, v160
	ds_read_b128 v[178:181], v138
	ds_read_b128 v[182:185], v138 offset:1024
	ds_read_b128 v[186:189], v138 offset:2048
	ds_read_b128 v[190:193], v138 offset:3072
	s_add_u32 s66, s66, 0x4000
	s_addc_u32 s67, s67, 0
	s_mov_b32 m0, s31
	ds_read_b128 v[194:197], v166 offset:32768
	ds_read_b128 v[198:201], v166 offset:33792
	ds_read_b128 v[202:205], v166 offset:34816
	ds_read_b128 v[206:209], v166 offset:35840
	ds_read_b128 v[210:213], v166 offset:36864
	ds_read_b128 v[214:217], v166 offset:37888
	ds_read_b128 v[218:221], v166 offset:38912
	ds_read_b128 v[222:225], v166 offset:39936
	global_load_lds_dwordx4 v146, s[66:67]
	s_mov_b32 m0, s43
	s_nop 0
	global_load_lds_dwordx4 v142, s[66:67]
	s_waitcnt vmcnt(8)
	s_waitcnt lgkmcnt(0)
	s_barrier
	s_setprio 1
	s_waitcnt lgkmcnt(0)
	v_mfma_f32_16x16x32_bf16 v[124:127], v[130:133], v[194:197], v[124:127]
	v_mfma_f32_16x16x32_bf16 v[120:123], v[170:173], v[194:197], v[120:123]
	v_mfma_f32_16x16x32_bf16 v[108:111], v[130:133], v[202:205], v[108:111]
	v_mfma_f32_16x16x32_bf16 v[104:107], v[170:173], v[202:205], v[104:107]
	v_mfma_f32_16x16x32_bf16 v[92:95], v[130:133], v[210:213], v[92:95]
	v_mfma_f32_16x16x32_bf16 v[88:91], v[170:173], v[210:213], v[88:91]
	v_mfma_f32_16x16x32_bf16 v[76:79], v[130:133], v[218:221], v[76:79]
	v_mfma_f32_16x16x32_bf16 v[72:75], v[170:173], v[218:221], v[72:75]
	v_mfma_f32_16x16x32_bf16 v[124:127], v[134:137], v[198:201], v[124:127]
	v_mfma_f32_16x16x32_bf16 v[120:123], v[174:177], v[198:201], v[120:123]
	v_mfma_f32_16x16x32_bf16 v[108:111], v[134:137], v[206:209], v[108:111]
	v_mfma_f32_16x16x32_bf16 v[104:107], v[174:177], v[206:209], v[104:107]
	v_mfma_f32_16x16x32_bf16 v[92:95], v[134:137], v[214:217], v[92:95]
	v_mfma_f32_16x16x32_bf16 v[88:91], v[174:177], v[214:217], v[88:91]
	v_mfma_f32_16x16x32_bf16 v[76:79], v[134:137], v[222:225], v[76:79]
	v_mfma_f32_16x16x32_bf16 v[72:75], v[174:177], v[222:225], v[72:75]
	s_setprio 0
	s_setprio 1
	v_mfma_f32_16x16x32_bf16 v[116:119], v[178:181], v[194:197], v[116:119]
	v_mfma_f32_16x16x32_bf16 v[112:115], v[186:189], v[194:197], v[112:115]
	v_mfma_f32_16x16x32_bf16 v[100:103], v[178:181], v[202:205], v[100:103]
	v_mfma_f32_16x16x32_bf16 v[96:99], v[186:189], v[202:205], v[96:99]
	v_mfma_f32_16x16x32_bf16 v[84:87], v[178:181], v[210:213], v[84:87]
	v_mfma_f32_16x16x32_bf16 v[80:83], v[186:189], v[210:213], v[80:83]
	v_mfma_f32_16x16x32_bf16 v[68:71], v[178:181], v[218:221], v[68:71]
	v_mfma_f32_16x16x32_bf16 v[64:67], v[186:189], v[218:221], v[64:67]
	v_mfma_f32_16x16x32_bf16 v[116:119], v[182:185], v[198:201], v[116:119]
	v_mfma_f32_16x16x32_bf16 v[112:115], v[190:193], v[198:201], v[112:115]
	v_mfma_f32_16x16x32_bf16 v[100:103], v[182:185], v[206:209], v[100:103]
	v_mfma_f32_16x16x32_bf16 v[96:99], v[190:193], v[206:209], v[96:99]
	v_mfma_f32_16x16x32_bf16 v[84:87], v[182:185], v[214:217], v[84:87]
	v_mfma_f32_16x16x32_bf16 v[80:83], v[190:193], v[214:217], v[80:83]
	v_mfma_f32_16x16x32_bf16 v[68:71], v[182:185], v[222:225], v[68:71]
	v_mfma_f32_16x16x32_bf16 v[64:67], v[190:193], v[222:225], v[64:67]
	s_setprio 0
	s_barrier
	s_add_u32 s66, s64, 0x8000
	s_addc_u32 s67, s65, 0
	s_add_i32 s38, s38, s3
	s_mov_b32 m0, s38
	ds_read_b128 v[194:197], v166 offset:49152
	ds_read_b128 v[198:201], v166 offset:50176
	ds_read_b128 v[202:205], v166 offset:51200
	ds_read_b128 v[206:209], v166 offset:52224
	ds_read_b128 v[210:213], v166 offset:53248
	ds_read_b128 v[214:217], v166 offset:54272
	ds_read_b128 v[218:221], v166 offset:55296
	ds_read_b128 v[222:225], v166 offset:56320
	global_load_lds_dwordx4 v144, s[66:67]
	s_add_i32 m0, s38, 0x2000
	s_add_u32 s64, s64, 0x9000
	s_addc_u32 s65, s65, 0
	s_add_i32 s38, s39, s3
	global_load_lds_dwordx4 v140, s[66:67]
	s_mov_b32 m0, s38
	s_nop 0
	global_load_lds_dwordx4 v144, s[64:65]
	s_add_i32 m0, s38, 0x2000
	s_nop 0
	global_load_lds_dwordx4 v140, s[64:65]
	s_mov_b32 m0, s47
	s_nop 0
	global_load_lds_dwordx4 v146, s[62:63]
	s_mov_b32 m0, s49
	s_nop 0
	global_load_lds_dwordx4 v142, s[62:63]
	s_waitcnt vmcnt(8)
	s_waitcnt lgkmcnt(0)
	s_barrier
	s_setprio 1
	s_waitcnt lgkmcnt(0)
	v_mfma_f32_16x16x32_bf16 v[60:63], v[130:133], v[194:197], v[60:63]
	v_mfma_f32_16x16x32_bf16 v[56:59], v[170:173], v[194:197], v[56:59]
	v_mfma_f32_16x16x32_bf16 v[44:47], v[130:133], v[202:205], v[44:47]
	v_mfma_f32_16x16x32_bf16 v[40:43], v[170:173], v[202:205], v[40:43]
	v_mfma_f32_16x16x32_bf16 v[28:31], v[130:133], v[210:213], v[28:31]
	v_mfma_f32_16x16x32_bf16 v[24:27], v[170:173], v[210:213], v[24:27]
	v_mfma_f32_16x16x32_bf16 v[12:15], v[130:133], v[218:221], v[12:15]
	v_mfma_f32_16x16x32_bf16 v[8:11], v[170:173], v[218:221], v[8:11]
	v_mfma_f32_16x16x32_bf16 v[60:63], v[134:137], v[198:201], v[60:63]
	v_mfma_f32_16x16x32_bf16 v[56:59], v[174:177], v[198:201], v[56:59]
	v_mfma_f32_16x16x32_bf16 v[44:47], v[134:137], v[206:209], v[44:47]
	v_mfma_f32_16x16x32_bf16 v[40:43], v[174:177], v[206:209], v[40:43]
	v_mfma_f32_16x16x32_bf16 v[28:31], v[134:137], v[214:217], v[28:31]
	v_mfma_f32_16x16x32_bf16 v[24:27], v[174:177], v[214:217], v[24:27]
	v_mfma_f32_16x16x32_bf16 v[12:15], v[134:137], v[222:225], v[12:15]
	v_mfma_f32_16x16x32_bf16 v[8:11], v[174:177], v[222:225], v[8:11]
	s_setprio 0
	s_setprio 1
	v_mfma_f32_16x16x32_bf16 v[52:55], v[178:181], v[194:197], v[52:55]
	v_mfma_f32_16x16x32_bf16 v[48:51], v[186:189], v[194:197], v[48:51]
	v_mfma_f32_16x16x32_bf16 v[36:39], v[178:181], v[202:205], v[36:39]
	v_mfma_f32_16x16x32_bf16 v[32:35], v[186:189], v[202:205], v[32:35]
	v_mfma_f32_16x16x32_bf16 v[20:23], v[178:181], v[210:213], v[20:23]
	v_mfma_f32_16x16x32_bf16 v[16:19], v[186:189], v[210:213], v[16:19]
	v_mfma_f32_16x16x32_bf16 v[4:7], v[178:181], v[218:221], v[4:7]
	v_mfma_f32_16x16x32_bf16 v[0:3], v[186:189], v[218:221], v[0:3]
	v_mfma_f32_16x16x32_bf16 v[52:55], v[182:185], v[198:201], v[52:55]
	v_mfma_f32_16x16x32_bf16 v[48:51], v[190:193], v[198:201], v[48:51]
	v_mfma_f32_16x16x32_bf16 v[36:39], v[182:185], v[206:209], v[36:39]
	v_mfma_f32_16x16x32_bf16 v[32:35], v[190:193], v[206:209], v[32:35]
	v_mfma_f32_16x16x32_bf16 v[20:23], v[182:185], v[214:217], v[20:23]
	v_mfma_f32_16x16x32_bf16 v[16:19], v[190:193], v[214:217], v[16:19]
	v_mfma_f32_16x16x32_bf16 v[4:7], v[182:185], v[222:225], v[4:7]
	v_mfma_f32_16x16x32_bf16 v[0:3], v[190:193], v[222:225], v[0:3]
	s_setprio 0
	s_barrier
	s_add_i32 s71, s71, 2
	s_add_u32 s18, s18, 0x10000
	s_addc_u32 s19, s19, 0
	s_add_u32 s69, s69, 0x10000
	s_addc_u32 s70, s70, 0
	s_cmp_gt_u32 s71, 61
	s_cbranch_scc1 .LBB0_690

; #define PG8_STAGE(bufoff, gbase, voff) do { _Pragma("unroll") for (int _i = 0; _i < 2; ++_i) \
;         __builtin_amdgcn_global_load_lds((const unsigned*)((const char*)(gbase) + (voff)[_i]), (LAS unsigned*)(lds + (bufoff) + ldsw + _i * 8192), 16, 0, 0); } while (0)
; #define PG8_LDA(dst, b, h) do { _Pragma("unroll") for (int m = 0; m < 4; ++m) _Pragma("unroll") for (int k = 0; k < 2; ++k) dst[m][k] = *(const LAS bf16x8*)(lds + PG8_SA(b, h) + aoff + m * 2048 + k * 1024); } while (0)
; #define PG8_LDB(dst, b, h) do { _Pragma("unroll") for (int n = 0; n < 2; ++n) _Pragma("unroll") for (int k = 0; k < 2; ++k) dst[n][k] = *(const LAS bf16x8*)(lds + PG8_SB(b, h) + boff + n * 2048 + k * 1024); } while (0)
; #define PG8_MMA(ai, bj, At, Bt) do { __builtin_amdgcn_s_setprio(1); _Pragma("unroll") for (int m = 0; m < 4; ++m) _Pragma("unroll") for (int n = 0; n < 2; ++n) _Pragma("unroll") for (int k = 0; k < 2; ++k) \
;         acc[ai][bj][m][n] = __builtin_amdgcn_mfma_f32_16x16x32_bf16(Bt[n][k], At[m][k], acc[ai][bj][m][n], 0, 0, 0); __builtin_amdgcn_s_setprio(0); } while (0)
; #define PG8_WAIT_V(n) asm volatile("s_waitcnt vmcnt(" #n ")" ::: "memory")
; #define PG8_WAIT_L(n) asm volatile("s_waitcnt lgkmcnt(" #n ")" ::: "memory")
; #define PG8_BAR __builtin_amdgcn_s_barrier()
; #define PG8_SCHED __builtin_amdgcn_sched_barrier(0)
; template <class Epi, class Sched, bool ALIGN_EPI>
; __device__ __forceinline__ void gemm_phase(LAS unsigned char* lds, const Gemm g, const Sched& S, const Epi& E, const int wid) {
;     ...
;             const char* a1 = cA + (size_t)(t + 1) * kstepA;
;             const char* a2 = last ? nA : cA + (size_t)(t + 2) * kstepA; const char* b2 = last ? nB : cB + (size_t)(t + 2) * kstep;
;             const char* a3 = a2 + kstepA; const char* b3 = b2 + kstep;
;             PG8_LDB(B0, 0, 0); PG8_LDB(B1, 0, 1); PG8_SCHED; PG8_LDA(At, 0, 0); PG8_STAGE(PG8_SA(1, 1), a1 + hstepA, voffA);
;             PG8_WAIT_V(8); PG8_WAIT_L(0); PG8_BAR; PG8_MMA(0, 0, At, B0); PG8_MMA(0, 1, At, B1); PG8_BAR; PG8_SCHED;
;             PG8_LDA(At, 0, 1); PG8_STAGE(PG8_SB(0, 0), b2, voffB); PG8_STAGE(PG8_SB(0, 1), b2 + hstepB, voffB); PG8_STAGE(PG8_SA(0, 0), a2, voffA);
;             PG8_WAIT_V(8); PG8_WAIT_L(0); PG8_BAR; PG8_MMA(1, 0, At, B0); PG8_MMA(1, 1, At, B1); PG8_BAR; PG8_SCHED;
.LBB0_791:
	ds_read_b128 v[72:75], v202
	ds_read_b128 v[76:79], v202 offset:1024
	ds_read_b128 v[136:139], v202 offset:2048
	ds_read_b128 v[140:143], v202 offset:3072
	ds_read_b128 v[144:147], v203
	ds_read_b128 v[148:151], v203 offset:1024
	ds_read_b128 v[152:155], v203 offset:2048
	ds_read_b128 v[178:181], v203 offset:3072
	s_add_u32 s38, s20, 0x4000
	s_addc_u32 s39, s21, 0
	s_cmpk_eq_i32 s53, 0xfc
	s_cselect_b32 s76, s5, s38
	s_cselect_b32 s77, s4, s39
	s_cselect_b32 s74, s31, s35
	s_cselect_b32 s75, s30, s52
	s_add_u32 s72, s76, 0x8000
	s_addc_u32 s73, s77, 0
	s_add_i32 m0, s45, 0xc000
	ds_read_b128 v[182:185], v204
	ds_read_b128 v[186:189], v204 offset:1024
	ds_read_b128 v[190:193], v204 offset:2048
	ds_read_b128 v[194:197], v204 offset:3072
	ds_read_b128 v[208:211], v204 offset:4096
	ds_read_b128 v[212:215], v204 offset:5120
	ds_read_b128 v[216:219], v204 offset:6144
	ds_read_b128 v[220:223], v204 offset:7168
	global_load_lds_dwordx4 v168, s[20:21]
	s_add_i32 m0, s45, 0xe000
	s_nop 0
	global_load_lds_dwordx4 v170, s[20:21]
	s_waitcnt vmcnt(8)
	s_waitcnt lgkmcnt(0)
	s_barrier
	s_setprio 1
	s_waitcnt lgkmcnt(0)
	v_mfma_f32_16x16x32_bf16 v[132:135], v[72:75], v[182:185], v[132:135]
	v_mfma_f32_16x16x32_bf16 v[128:131], v[136:139], v[182:185], v[128:131]
	v_mfma_f32_16x16x32_bf16 v[116:119], v[72:75], v[190:193], v[116:119]
	v_mfma_f32_16x16x32_bf16 v[112:115], v[136:139], v[190:193], v[112:115]
	v_mfma_f32_16x16x32_bf16 v[100:103], v[72:75], v[208:211], v[100:103]
	v_mfma_f32_16x16x32_bf16 v[96:99], v[136:139], v[208:211], v[96:99]
	v_mfma_f32_16x16x32_bf16 v[84:87], v[72:75], v[216:219], v[84:87]
	v_mfma_f32_16x16x32_bf16 v[80:83], v[136:139], v[216:219], v[80:83]
	v_mfma_f32_16x16x32_bf16 v[132:135], v[76:79], v[186:189], v[132:135]
	v_mfma_f32_16x16x32_bf16 v[128:131], v[140:143], v[186:189], v[128:131]
	v_mfma_f32_16x16x32_bf16 v[116:119], v[76:79], v[194:197], v[116:119]
	v_mfma_f32_16x16x32_bf16 v[112:115], v[140:143], v[194:197], v[112:115]
	v_mfma_f32_16x16x32_bf16 v[100:103], v[76:79], v[212:215], v[100:103]
	v_mfma_f32_16x16x32_bf16 v[96:99], v[140:143], v[212:215], v[96:99]
	v_mfma_f32_16x16x32_bf16 v[84:87], v[76:79], v[220:223], v[84:87]
	v_mfma_f32_16x16x32_bf16 v[80:83], v[140:143], v[220:223], v[80:83]
	s_setprio 0
	s_setprio 1
	v_mfma_f32_16x16x32_bf16 v[124:127], v[144:147], v[182:185], v[124:127]
	v_mfma_f32_16x16x32_bf16 v[120:123], v[152:155], v[182:185], v[120:123]
	v_mfma_f32_16x16x32_bf16 v[108:111], v[144:147], v[190:193], v[108:111]
	v_mfma_f32_16x16x32_bf16 v[104:107], v[152:155], v[190:193], v[104:107]
	v_mfma_f32_16x16x32_bf16 v[92:95], v[144:147], v[208:211], v[92:95]
	v_mfma_f32_16x16x32_bf16 v[88:91], v[152:155], v[208:211], v[88:91]
	v_mfma_f32_16x16x32_bf16 v[68:71], v[144:147], v[216:219], v[68:71]
	v_mfma_f32_16x16x32_bf16 v[64:67], v[152:155], v[216:219], v[64:67]
	v_mfma_f32_16x16x32_bf16 v[124:127], v[148:151], v[186:189], v[124:127]
	v_mfma_f32_16x16x32_bf16 v[120:123], v[178:181], v[186:189], v[120:123]
	v_mfma_f32_16x16x32_bf16 v[108:111], v[148:151], v[194:197], v[108:111]
	v_mfma_f32_16x16x32_bf16 v[104:107], v[178:181], v[194:197], v[104:107]
	v_mfma_f32_16x16x32_bf16 v[92:95], v[148:151], v[212:215], v[92:95]
	v_mfma_f32_16x16x32_bf16 v[88:91], v[178:181], v[212:215], v[88:91]
	v_mfma_f32_16x16x32_bf16 v[68:71], v[148:151], v[220:223], v[68:71]
	v_mfma_f32_16x16x32_bf16 v[64:67], v[178:181], v[220:223], v[64:67]
	s_setprio 0
	s_barrier
	s_add_i32 s38, s81, s3
	s_mov_b32 m0, s38
	ds_read_b128 v[182:185], v204 offset:16384
	ds_read_b128 v[186:189], v204 offset:17408
	ds_read_b128 v[190:193], v204 offset:18432
	ds_read_b128 v[194:197], v204 offset:19456
	ds_read_b128 v[208:211], v204 offset:20480
	ds_read_b128 v[212:215], v204 offset:21504
	ds_read_b128 v[216:219], v204 offset:22528
	ds_read_b128 v[220:223], v204 offset:23552
	global_load_lds_dwordx4 v158, s[74:75]
	s_add_i32 m0, s38, 0x2000
	s_add_u32 s54, s74, 0x1000
	s_addc_u32 s55, s75, 0
	s_add_i32 s38, s85, s3
	global_load_lds_dwordx4 v162, s[74:75]
	s_mov_b32 m0, s38
	s_nop 0
	global_load_lds_dwordx4 v158, s[54:55]
	s_add_i32 m0, s38, 0x2000
	s_nop 0
	global_load_lds_dwordx4 v162, s[54:55]
	s_mov_b32 m0, s45
	s_nop 0
	global_load_lds_dwordx4 v156, s[76:77]
	s_mov_b32 m0, s46
	s_nop 0
	global_load_lds_dwordx4 v160, s[76:77]
	s_waitcnt vmcnt(8)
	s_waitcnt lgkmcnt(0)
	s_barrier
	s_setprio 1
	s_waitcnt lgkmcnt(0)
	v_mfma_f32_16x16x32_bf16 v[60:63], v[72:75], v[182:185], v[60:63]
	v_mfma_f32_16x16x32_bf16 v[56:59], v[136:139], v[182:185], v[56:59]
	v_mfma_f32_16x16x32_bf16 v[44:47], v[72:75], v[190:193], v[44:47]
	v_mfma_f32_16x16x32_bf16 v[40:43], v[136:139], v[190:193], v[40:43]
	v_mfma_f32_16x16x32_bf16 v[28:31], v[72:75], v[208:211], v[28:31]
	v_mfma_f32_16x16x32_bf16 v[24:27], v[136:139], v[208:211], v[24:27]
	v_mfma_f32_16x16x32_bf16 v[12:15], v[72:75], v[216:219], v[12:15]
	v_mfma_f32_16x16x32_bf16 v[8:11], v[136:139], v[216:219], v[8:11]
	v_mfma_f32_16x16x32_bf16 v[60:63], v[76:79], v[186:189], v[60:63]
	v_mfma_f32_16x16x32_bf16 v[56:59], v[140:143], v[186:189], v[56:59]
	v_mfma_f32_16x16x32_bf16 v[44:47], v[76:79], v[194:197], v[44:47]
	v_mfma_f32_16x16x32_bf16 v[40:43], v[140:143], v[194:197], v[40:43]
	v_mfma_f32_16x16x32_bf16 v[28:31], v[76:79], v[212:215], v[28:31]
	v_mfma_f32_16x16x32_bf16 v[24:27], v[140:143], v[212:215], v[24:27]
	v_mfma_f32_16x16x32_bf16 v[12:15], v[76:79], v[220:223], v[12:15]
	v_mfma_f32_16x16x32_bf16 v[8:11], v[140:143], v[220:223], v[8:11]
	s_setprio 0
	s_setprio 1
	v_mfma_f32_16x16x32_bf16 v[52:55], v[144:147], v[182:185], v[52:55]
	v_mfma_f32_16x16x32_bf16 v[48:51], v[152:155], v[182:185], v[48:51]
	v_mfma_f32_16x16x32_bf16 v[36:39], v[144:147], v[190:193], v[36:39]
	v_mfma_f32_16x16x32_bf16 v[32:35], v[152:155], v[190:193], v[32:35]
	v_mfma_f32_16x16x32_bf16 v[20:23], v[144:147], v[208:211], v[20:23]
	v_mfma_f32_16x16x32_bf16 v[16:19], v[152:155], v[208:211], v[16:19]
	v_mfma_f32_16x16x32_bf16 v[4:7], v[144:147], v[216:219], v[4:7]
	v_mfma_f32_16x16x32_bf16 v[0:3], v[152:155], v[216:219], v[0:3]
	v_mfma_f32_16x16x32_bf16 v[52:55], v[148:151], v[186:189], v[52:55]
	v_mfma_f32_16x16x32_bf16 v[48:51], v[178:181], v[186:189], v[48:51]
	v_mfma_f32_16x16x32_bf16 v[36:39], v[148:151], v[194:197], v[36:39]
	v_mfma_f32_16x16x32_bf16 v[32:35], v[178:181], v[194:197], v[32:35]
	v_mfma_f32_16x16x32_bf16 v[20:23], v[148:151], v[212:215], v[20:23]
	v_mfma_f32_16x16x32_bf16 v[16:19], v[178:181], v[212:215], v[16:19]
	v_mfma_f32_16x16x32_bf16 v[4:7], v[148:151], v[220:223], v[4:7]
	v_mfma_f32_16x16x32_bf16 v[0:3], v[178:181], v[220:223], v[0:3]
	s_setprio 0
	s_barrier
; #define PG8_STAGE(bufoff, gbase, voff) do { _Pragma("unroll") for (int _i = 0; _i < 2; ++_i) \
;         __builtin_amdgcn_global_load_lds((const unsigned*)((const char*)(gbase) + (voff)[_i]), (LAS unsigned*)(lds + (bufoff) + ldsw + _i * 8192), 16, 0, 0); } while (0)
; #define PG8_LDA(dst, b, h) do { _Pragma("unroll") for (int m = 0; m < 4; ++m) _Pragma("unroll") for (int k = 0; k < 2; ++k) dst[m][k] = *(const LAS bf16x8*)(lds + PG8_SA(b, h) + aoff + m * 2048 + k * 1024); } while (0)
; #define PG8_LDB(dst, b, h) do { _Pragma("unroll") for (int n = 0; n < 2; ++n) _Pragma("unroll") for (int k = 0; k < 2; ++k) dst[n][k] = *(const LAS bf16x8*)(lds + PG8_SB(b, h) + boff + n * 2048 + k * 1024); } while (0)
; #define PG8_MMA(ai, bj, At, Bt) do { __builtin_amdgcn_s_setprio(1); _Pragma("unroll") for (int m = 0; m < 4; ++m) _Pragma("unroll") for (int n = 0; n < 2; ++n) _Pragma("unroll") for (int k = 0; k < 2; ++k) \
;         acc[ai][bj][m][n] = __builtin_amdgcn_mfma_f32_16x16x32_bf16(Bt[n][k], At[m][k], acc[ai][bj][m][n], 0, 0, 0); __builtin_amdgcn_s_setprio(0); } while (0)
; #define PG8_WAIT_V(n) asm volatile("s_waitcnt vmcnt(" #n ")" ::: "memory")
; #define PG8_WAIT_L(n) asm volatile("s_waitcnt lgkmcnt(" #n ")" ::: "memory")
; #define PG8_BAR __builtin_amdgcn_s_barrier()
; #define PG8_SCHED __builtin_amdgcn_sched_barrier(0)
; template <class Epi, class Sched, bool ALIGN_EPI>
; __device__ __forceinline__ void gemm_phase(LAS unsigned char* lds, const Gemm g, const Sched& S, const Epi& E, const int wid) {
;     ...
;             PG8_LDB(B0, 1, 0); PG8_LDB(B1, 1, 1); PG8_SCHED; PG8_LDA(At, 1, 0); PG8_STAGE(PG8_SA(0, 1), a2 + hstepA, voffA);
;             PG8_WAIT_V(8); PG8_WAIT_L(0); PG8_BAR; PG8_MMA(0, 0, At, B0); PG8_MMA(0, 1, At, B1); PG8_BAR; PG8_SCHED;
;             PG8_LDA(At, 1, 1); PG8_STAGE(PG8_SB(1, 0), b3, voffB); PG8_STAGE(PG8_SB(1, 1), b3 + hstepB, voffB); PG8_STAGE(PG8_SA(1, 0), a3, voffA);
;             PG8_WAIT_V(8); PG8_WAIT_L(0); PG8_BAR; PG8_MMA(1, 0, At, B0); PG8_MMA(1, 1, At, B1); PG8_BAR; PG8_SCHED;
;         }
;         if constexpr (ALIGN_EPI) { if (wr == 0) PG8_BAR; }
	s_add_i32 s38, 0, 0x18000
	s_add_i32 s39, 0, 0x1c000
	v_add_u32_e32 v140, s38, v198
	v_add_u32_e32 v164, s39, v198
	ds_read_b128 v[72:75], v140
	ds_read_b128 v[76:79], v140 offset:1024
	ds_read_b128 v[136:139], v140 offset:2048
	ds_read_b128 v[140:143], v140 offset:3072
	ds_read_b128 v[144:147], v164
	ds_read_b128 v[148:151], v164 offset:1024
	ds_read_b128 v[152:155], v164 offset:2048
	ds_read_b128 v[178:181], v164 offset:3072
	s_add_u32 s54, s76, 0x4000
	s_addc_u32 s55, s77, 0
	s_mov_b32 m0, s47
	ds_read_b128 v[182:185], v204 offset:32768
	ds_read_b128 v[186:189], v204 offset:33792
	ds_read_b128 v[190:193], v204 offset:34816
	ds_read_b128 v[194:197], v204 offset:35840
	ds_read_b128 v[208:211], v204 offset:36864
	ds_read_b128 v[212:215], v204 offset:37888
	ds_read_b128 v[216:219], v204 offset:38912
	ds_read_b128 v[220:223], v204 offset:39936
	global_load_lds_dwordx4 v156, s[54:55]
	s_mov_b32 m0, s49
	s_nop 0
	global_load_lds_dwordx4 v160, s[54:55]
	s_waitcnt vmcnt(8)
	s_waitcnt lgkmcnt(0)
	s_barrier
	s_setprio 1
	s_waitcnt lgkmcnt(0)
	v_mfma_f32_16x16x32_bf16 v[132:135], v[72:75], v[182:185], v[132:135]
	v_mfma_f32_16x16x32_bf16 v[128:131], v[136:139], v[182:185], v[128:131]
	v_mfma_f32_16x16x32_bf16 v[116:119], v[72:75], v[190:193], v[116:119]
	v_mfma_f32_16x16x32_bf16 v[112:115], v[136:139], v[190:193], v[112:115]
	v_mfma_f32_16x16x32_bf16 v[100:103], v[72:75], v[208:211], v[100:103]
	v_mfma_f32_16x16x32_bf16 v[96:99], v[136:139], v[208:211], v[96:99]
	v_mfma_f32_16x16x32_bf16 v[84:87], v[72:75], v[216:219], v[84:87]
	v_mfma_f32_16x16x32_bf16 v[80:83], v[136:139], v[216:219], v[80:83]
	v_mfma_f32_16x16x32_bf16 v[132:135], v[76:79], v[186:189], v[132:135]
	v_mfma_f32_16x16x32_bf16 v[128:131], v[140:143], v[186:189], v[128:131]
	v_mfma_f32_16x16x32_bf16 v[116:119], v[76:79], v[194:197], v[116:119]
	v_mfma_f32_16x16x32_bf16 v[112:115], v[140:143], v[194:197], v[112:115]
	v_mfma_f32_16x16x32_bf16 v[100:103], v[76:79], v[212:215], v[100:103]
	v_mfma_f32_16x16x32_bf16 v[96:99], v[140:143], v[212:215], v[96:99]
	v_mfma_f32_16x16x32_bf16 v[84:87], v[76:79], v[220:223], v[84:87]
	v_mfma_f32_16x16x32_bf16 v[80:83], v[140:143], v[220:223], v[80:83]
	s_setprio 0
	s_setprio 1
	v_mfma_f32_16x16x32_bf16 v[124:127], v[144:147], v[182:185], v[124:127]
	v_mfma_f32_16x16x32_bf16 v[120:123], v[152:155], v[182:185], v[120:123]
	v_mfma_f32_16x16x32_bf16 v[108:111], v[144:147], v[190:193], v[108:111]
	v_mfma_f32_16x16x32_bf16 v[104:107], v[152:155], v[190:193], v[104:107]
	v_mfma_f32_16x16x32_bf16 v[92:95], v[144:147], v[208:211], v[92:95]
	v_mfma_f32_16x16x32_bf16 v[88:91], v[152:155], v[208:211], v[88:91]
	v_mfma_f32_16x16x32_bf16 v[68:71], v[144:147], v[216:219], v[68:71]
	v_mfma_f32_16x16x32_bf16 v[64:67], v[152:155], v[216:219], v[64:67]
	v_mfma_f32_16x16x32_bf16 v[124:127], v[148:151], v[186:189], v[124:127]
	v_mfma_f32_16x16x32_bf16 v[120:123], v[178:181], v[186:189], v[120:123]
	v_mfma_f32_16x16x32_bf16 v[108:111], v[148:151], v[194:197], v[108:111]
	v_mfma_f32_16x16x32_bf16 v[104:107], v[178:181], v[194:197], v[104:107]
	v_mfma_f32_16x16x32_bf16 v[92:95], v[148:151], v[212:215], v[92:95]
	v_mfma_f32_16x16x32_bf16 v[88:91], v[178:181], v[212:215], v[88:91]
	v_mfma_f32_16x16x32_bf16 v[68:71], v[148:151], v[220:223], v[68:71]
	v_mfma_f32_16x16x32_bf16 v[64:67], v[178:181], v[220:223], v[64:67]
	s_setprio 0
	s_barrier
	s_add_u32 s54, s74, 0x8000
	s_addc_u32 s55, s75, 0
	s_add_i32 s38, s38, s3
	s_mov_b32 m0, s38
	ds_read_b128 v[182:185], v204 offset:49152
	ds_read_b128 v[186:189], v204 offset:50176
	ds_read_b128 v[190:193], v204 offset:51200
	ds_read_b128 v[194:197], v204 offset:52224
	ds_read_b128 v[208:211], v204 offset:53248
	ds_read_b128 v[212:215], v204 offset:54272
	ds_read_b128 v[216:219], v204 offset:55296
	ds_read_b128 v[220:223], v204 offset:56320
	global_load_lds_dwordx4 v158, s[54:55]
	s_add_i32 m0, s38, 0x2000
	s_nop 0
	global_load_lds_dwordx4 v162, s[54:55]
	s_add_u32 s54, s74, 0x9000
	s_addc_u32 s55, s75, 0
	s_add_i32 s38, s39, s3
	s_mov_b32 m0, s38
	s_nop 0
	global_load_lds_dwordx4 v158, s[54:55]
	s_add_i32 m0, s38, 0x2000
	s_nop 0
	global_load_lds_dwordx4 v162, s[54:55]
	s_mov_b32 m0, s78
	s_nop 0
	global_load_lds_dwordx4 v156, s[72:73]
	s_mov_b32 m0, s79
	s_nop 0
	global_load_lds_dwordx4 v160, s[72:73]
	s_waitcnt vmcnt(8)
	s_waitcnt lgkmcnt(0)
	s_barrier
	s_setprio 1
	s_waitcnt lgkmcnt(0)
	v_mfma_f32_16x16x32_bf16 v[60:63], v[72:75], v[182:185], v[60:63]
	v_mfma_f32_16x16x32_bf16 v[56:59], v[136:139], v[182:185], v[56:59]
	v_mfma_f32_16x16x32_bf16 v[44:47], v[72:75], v[190:193], v[44:47]
	v_mfma_f32_16x16x32_bf16 v[40:43], v[136:139], v[190:193], v[40:43]
	v_mfma_f32_16x16x32_bf16 v[28:31], v[72:75], v[208:211], v[28:31]
	v_mfma_f32_16x16x32_bf16 v[24:27], v[136:139], v[208:211], v[24:27]
	v_mfma_f32_16x16x32_bf16 v[12:15], v[72:75], v[216:219], v[12:15]
	v_mfma_f32_16x16x32_bf16 v[8:11], v[136:139], v[216:219], v[8:11]
	v_mfma_f32_16x16x32_bf16 v[60:63], v[76:79], v[186:189], v[60:63]
	v_mfma_f32_16x16x32_bf16 v[56:59], v[140:143], v[186:189], v[56:59]
	v_mfma_f32_16x16x32_bf16 v[44:47], v[76:79], v[194:197], v[44:47]
	v_mfma_f32_16x16x32_bf16 v[40:43], v[140:143], v[194:197], v[40:43]
	v_mfma_f32_16x16x32_bf16 v[28:31], v[76:79], v[212:215], v[28:31]
	v_mfma_f32_16x16x32_bf16 v[24:27], v[140:143], v[212:215], v[24:27]
	v_mfma_f32_16x16x32_bf16 v[12:15], v[76:79], v[220:223], v[12:15]
	v_mfma_f32_16x16x32_bf16 v[8:11], v[140:143], v[220:223], v[8:11]
	s_setprio 0
	s_setprio 1
	v_mfma_f32_16x16x32_bf16 v[52:55], v[144:147], v[182:185], v[52:55]
	v_mfma_f32_16x16x32_bf16 v[48:51], v[152:155], v[182:185], v[48:51]
	v_mfma_f32_16x16x32_bf16 v[36:39], v[144:147], v[190:193], v[36:39]
	v_mfma_f32_16x16x32_bf16 v[32:35], v[152:155], v[190:193], v[32:35]
	v_mfma_f32_16x16x32_bf16 v[20:23], v[144:147], v[208:211], v[20:23]
	v_mfma_f32_16x16x32_bf16 v[16:19], v[152:155], v[208:211], v[16:19]
	v_mfma_f32_16x16x32_bf16 v[4:7], v[144:147], v[216:219], v[4:7]
	v_mfma_f32_16x16x32_bf16 v[0:3], v[152:155], v[216:219], v[0:3]
	v_mfma_f32_16x16x32_bf16 v[52:55], v[148:151], v[186:189], v[52:55]
	v_mfma_f32_16x16x32_bf16 v[48:51], v[178:181], v[186:189], v[48:51]
	v_mfma_f32_16x16x32_bf16 v[36:39], v[148:151], v[194:197], v[36:39]
	v_mfma_f32_16x16x32_bf16 v[32:35], v[178:181], v[194:197], v[32:35]
	v_mfma_f32_16x16x32_bf16 v[20:23], v[148:151], v[212:215], v[20:23]
	v_mfma_f32_16x16x32_bf16 v[16:19], v[178:181], v[212:215], v[16:19]
	v_mfma_f32_16x16x32_bf16 v[4:7], v[148:151], v[220:223], v[4:7]
	v_mfma_f32_16x16x32_bf16 v[0:3], v[178:181], v[220:223], v[0:3]
	s_setprio 0
	s_barrier
	s_add_i32 s53, s53, 2
	s_add_u32 s35, s35, 0x10000
	s_addc_u32 s52, s52, 0
	s_add_u32 s20, s20, 0x10000
	s_addc_u32 s21, s21, 0
	s_cmpk_gt_u32 s53, 0xfd
	s_cbranch_scc0 .LBB0_791
	s_and_b64 vcc, exec, s[28:29]
	s_cbranch_vccz .LBB0_794
	s_barrier

; #define PG8_STAGE(bufoff, gbase, voff) do { _Pragma("unroll") for (int _i = 0; _i < 2; ++_i) \
;         __builtin_amdgcn_global_load_lds((const unsigned*)((const char*)(gbase) + (voff)[_i]), (LAS unsigned*)(lds + (bufoff) + ldsw + _i * 8192), 16, 0, 0); } while (0)
; #define PG8_LDA(dst, b, h) do { _Pragma("unroll") for (int m = 0; m < 4; ++m) _Pragma("unroll") for (int k = 0; k < 2; ++k) dst[m][k] = *(const LAS bf16x8*)(lds + PG8_SA(b, h) + aoff + m * 2048 + k * 1024); } while (0)
; #define PG8_LDB(dst, b, h) do { _Pragma("unroll") for (int n = 0; n < 2; ++n) _Pragma("unroll") for (int k = 0; k < 2; ++k) dst[n][k] = *(const LAS bf16x8*)(lds + PG8_SB(b, h) + boff + n * 2048 + k * 1024); } while (0)
; #define PG8_MMA(ai, bj, At, Bt) do { __builtin_amdgcn_s_setprio(1); _Pragma("unroll") for (int m = 0; m < 4; ++m) _Pragma("unroll") for (int n = 0; n < 2; ++n) _Pragma("unroll") for (int k = 0; k < 2; ++k) \
;         acc[ai][bj][m][n] = __builtin_amdgcn_mfma_f32_16x16x32_bf16(Bt[n][k], At[m][k], acc[ai][bj][m][n], 0, 0, 0); __builtin_amdgcn_s_setprio(0); } while (0)
; #define PG8_WAIT_V(n) asm volatile("s_waitcnt vmcnt(" #n ")" ::: "memory")
; #define PG8_WAIT_L(n) asm volatile("s_waitcnt lgkmcnt(" #n ")" ::: "memory")
; #define PG8_BAR __builtin_amdgcn_s_barrier()
; #define PG8_SCHED __builtin_amdgcn_sched_barrier(0)
; template <class Epi, class Sched, bool ALIGN_EPI>
; __device__ __forceinline__ void gemm_phase(LAS unsigned char* lds, const Gemm g, const Sched& S, const Epi& E, const int wid) {
;     ...
;             const char* a1 = cA + (size_t)(t + 1) * kstepA;
;             const char* a2 = last ? nA : cA + (size_t)(t + 2) * kstepA; const char* b2 = last ? nB : cB + (size_t)(t + 2) * kstep;
;             const char* a3 = a2 + kstepA; const char* b3 = b2 + kstep;
;             PG8_LDB(B0, 0, 0); PG8_LDB(B1, 0, 1); PG8_SCHED; PG8_LDA(At, 0, 0); PG8_STAGE(PG8_SA(1, 1), a1 + hstepA, voffA);
;             PG8_WAIT_V(8); PG8_WAIT_L(0); PG8_BAR; PG8_MMA(0, 0, At, B0); PG8_MMA(0, 1, At, B1); PG8_BAR; PG8_SCHED;
;             PG8_LDA(At, 0, 1); PG8_STAGE(PG8_SB(0, 0), b2, voffB); PG8_STAGE(PG8_SB(0, 1), b2 + hstepB, voffB); PG8_STAGE(PG8_SA(0, 0), a2, voffA);
;             PG8_WAIT_V(8); PG8_WAIT_L(0); PG8_BAR; PG8_MMA(1, 0, At, B0); PG8_MMA(1, 1, At, B1); PG8_BAR; PG8_SCHED;
.LBB0_920:
	v_add_u32_e32 v142, s89, v170
	s_waitcnt lgkmcnt(0)
	ds_read_b128 v[130:133], v142
	ds_read_b128 v[134:137], v142 offset:1024
	ds_read_b128 v[138:141], v142 offset:2048
	ds_read_b128 v[182:185], v142 offset:3072
	v_add_u32_e32 v142, s90, v170
	s_add_u32 s38, s68, 0x4000
	ds_read_b128 v[186:189], v142
	ds_read_b128 v[190:193], v142 offset:1024
	ds_read_b128 v[194:197], v142 offset:2048
	ds_read_b128 v[198:201], v142 offset:3072
	s_addc_u32 s39, s69, 0
	s_and_b64 s[70:71], s[72:73], exec
	s_cselect_b32 s74, s5, s38
	s_cselect_b32 s75, s4, s39
	s_add_u32 s70, s74, 0x8000
	s_addc_u32 s71, s75, 0
	s_and_b64 s[72:73], s[72:73], exec
	s_cselect_b32 s73, s19, s35
	s_cselect_b32 s72, s30, s31
	s_add_i32 m0, s44, 0xc000
	ds_read_b128 v[202:205], v177
	ds_read_b128 v[206:209], v177 offset:1024
	ds_read_b128 v[210:213], v177 offset:2048
	ds_read_b128 v[214:217], v177 offset:3072
	ds_read_b128 v[218:221], v177 offset:4096
	ds_read_b128 v[222:225], v177 offset:5120
	ds_read_b128 v[226:229], v177 offset:6144
	ds_read_b128 v[230:233], v177 offset:7168
	global_load_lds_dwordx4 v158, s[68:69]
	s_add_i32 m0, s44, 0xe000
	s_nop 0
	global_load_lds_dwordx4 v160, s[68:69]
	s_waitcnt vmcnt(8)
	s_waitcnt lgkmcnt(0)
	s_barrier
	s_setprio 1
	s_waitcnt lgkmcnt(0)
	v_mfma_f32_16x16x32_bf16 v[124:127], v[130:133], v[202:205], v[124:127]
	v_mfma_f32_16x16x32_bf16 v[120:123], v[138:141], v[202:205], v[120:123]
	v_mfma_f32_16x16x32_bf16 v[108:111], v[130:133], v[210:213], v[108:111]
	v_mfma_f32_16x16x32_bf16 v[104:107], v[138:141], v[210:213], v[104:107]
	v_mfma_f32_16x16x32_bf16 v[92:95], v[130:133], v[218:221], v[92:95]
	v_mfma_f32_16x16x32_bf16 v[88:91], v[138:141], v[218:221], v[88:91]
	v_mfma_f32_16x16x32_bf16 v[76:79], v[130:133], v[226:229], v[76:79]
	v_mfma_f32_16x16x32_bf16 v[72:75], v[138:141], v[226:229], v[72:75]
	v_mfma_f32_16x16x32_bf16 v[124:127], v[134:137], v[206:209], v[124:127]
	v_mfma_f32_16x16x32_bf16 v[120:123], v[182:185], v[206:209], v[120:123]
	v_mfma_f32_16x16x32_bf16 v[108:111], v[134:137], v[214:217], v[108:111]
	v_mfma_f32_16x16x32_bf16 v[104:107], v[182:185], v[214:217], v[104:107]
	v_mfma_f32_16x16x32_bf16 v[92:95], v[134:137], v[222:225], v[92:95]
	v_mfma_f32_16x16x32_bf16 v[88:91], v[182:185], v[222:225], v[88:91]
	v_mfma_f32_16x16x32_bf16 v[76:79], v[134:137], v[230:233], v[76:79]
	v_mfma_f32_16x16x32_bf16 v[72:75], v[182:185], v[230:233], v[72:75]
	s_setprio 0
	s_setprio 1
	v_mfma_f32_16x16x32_bf16 v[116:119], v[186:189], v[202:205], v[116:119]
	v_mfma_f32_16x16x32_bf16 v[112:115], v[194:197], v[202:205], v[112:115]
	v_mfma_f32_16x16x32_bf16 v[100:103], v[186:189], v[210:213], v[100:103]
	v_mfma_f32_16x16x32_bf16 v[96:99], v[194:197], v[210:213], v[96:99]
	v_mfma_f32_16x16x32_bf16 v[84:87], v[186:189], v[218:221], v[84:87]
	v_mfma_f32_16x16x32_bf16 v[80:83], v[194:197], v[218:221], v[80:83]
	v_mfma_f32_16x16x32_bf16 v[68:71], v[186:189], v[226:229], v[68:71]
	v_mfma_f32_16x16x32_bf16 v[64:67], v[194:197], v[226:229], v[64:67]
	v_mfma_f32_16x16x32_bf16 v[116:119], v[190:193], v[206:209], v[116:119]
	v_mfma_f32_16x16x32_bf16 v[112:115], v[198:201], v[206:209], v[112:115]
	v_mfma_f32_16x16x32_bf16 v[100:103], v[190:193], v[214:217], v[100:103]
	v_mfma_f32_16x16x32_bf16 v[96:99], v[198:201], v[214:217], v[96:99]
	v_mfma_f32_16x16x32_bf16 v[84:87], v[190:193], v[222:225], v[84:87]
	v_mfma_f32_16x16x32_bf16 v[80:83], v[198:201], v[222:225], v[80:83]
	v_mfma_f32_16x16x32_bf16 v[68:71], v[190:193], v[230:233], v[68:71]
	v_mfma_f32_16x16x32_bf16 v[64:67], v[198:201], v[230:233], v[64:67]
	s_setprio 0
	s_barrier
	s_add_i32 s38, s89, s3
	s_mov_b32 m0, s38
	ds_read_b128 v[202:205], v177 offset:16384
	ds_read_b128 v[206:209], v177 offset:17408
	ds_read_b128 v[210:213], v177 offset:18432
	ds_read_b128 v[214:217], v177 offset:19456
	ds_read_b128 v[218:221], v177 offset:20480
	ds_read_b128 v[222:225], v177 offset:21504
	ds_read_b128 v[226:229], v177 offset:22528
	ds_read_b128 v[230:233], v177 offset:23552
	global_load_lds_dwordx4 v146, s[72:73]
	s_add_i32 m0, s38, 0x2000
	s_add_u32 s94, s72, 0x1000
	s_addc_u32 s95, s73, 0
	s_add_i32 s38, s90, s3
	global_load_lds_dwordx4 v150, s[72:73]
	s_mov_b32 m0, s38
	s_nop 0
	global_load_lds_dwordx4 v146, s[94:95]
	s_add_i32 m0, s38, 0x2000
	s_nop 0
	global_load_lds_dwordx4 v150, s[94:95]
	s_mov_b32 m0, s44
	s_nop 0
	global_load_lds_dwordx4 v144, s[74:75]
	s_mov_b32 m0, s45
	s_nop 0
	global_load_lds_dwordx4 v148, s[74:75]
	s_waitcnt vmcnt(8)
	s_waitcnt lgkmcnt(0)
	s_barrier
	s_setprio 1
	s_waitcnt lgkmcnt(0)
	v_mfma_f32_16x16x32_bf16 v[60:63], v[130:133], v[202:205], v[60:63]
	v_mfma_f32_16x16x32_bf16 v[56:59], v[138:141], v[202:205], v[56:59]
	v_mfma_f32_16x16x32_bf16 v[44:47], v[130:133], v[210:213], v[44:47]
	v_mfma_f32_16x16x32_bf16 v[40:43], v[138:141], v[210:213], v[40:43]
	v_mfma_f32_16x16x32_bf16 v[28:31], v[130:133], v[218:221], v[28:31]
	v_mfma_f32_16x16x32_bf16 v[24:27], v[138:141], v[218:221], v[24:27]
	v_mfma_f32_16x16x32_bf16 v[12:15], v[130:133], v[226:229], v[12:15]
	v_mfma_f32_16x16x32_bf16 v[8:11], v[138:141], v[226:229], v[8:11]
	v_mfma_f32_16x16x32_bf16 v[60:63], v[134:137], v[206:209], v[60:63]
	v_mfma_f32_16x16x32_bf16 v[56:59], v[182:185], v[206:209], v[56:59]
	v_mfma_f32_16x16x32_bf16 v[44:47], v[134:137], v[214:217], v[44:47]
	v_mfma_f32_16x16x32_bf16 v[40:43], v[182:185], v[214:217], v[40:43]
	v_mfma_f32_16x16x32_bf16 v[28:31], v[134:137], v[222:225], v[28:31]
	v_mfma_f32_16x16x32_bf16 v[24:27], v[182:185], v[222:225], v[24:27]
	v_mfma_f32_16x16x32_bf16 v[12:15], v[134:137], v[230:233], v[12:15]
	v_mfma_f32_16x16x32_bf16 v[8:11], v[182:185], v[230:233], v[8:11]
	s_setprio 0
	s_setprio 1
	v_mfma_f32_16x16x32_bf16 v[52:55], v[186:189], v[202:205], v[52:55]
	v_mfma_f32_16x16x32_bf16 v[48:51], v[194:197], v[202:205], v[48:51]
	v_mfma_f32_16x16x32_bf16 v[36:39], v[186:189], v[210:213], v[36:39]
	v_mfma_f32_16x16x32_bf16 v[32:35], v[194:197], v[210:213], v[32:35]
	v_mfma_f32_16x16x32_bf16 v[20:23], v[186:189], v[218:221], v[20:23]
	v_mfma_f32_16x16x32_bf16 v[16:19], v[194:197], v[218:221], v[16:19]
	v_mfma_f32_16x16x32_bf16 v[4:7], v[186:189], v[226:229], v[4:7]
	v_mfma_f32_16x16x32_bf16 v[0:3], v[194:197], v[226:229], v[0:3]
	v_mfma_f32_16x16x32_bf16 v[52:55], v[190:193], v[206:209], v[52:55]
	v_mfma_f32_16x16x32_bf16 v[48:51], v[198:201], v[206:209], v[48:51]
	v_mfma_f32_16x16x32_bf16 v[36:39], v[190:193], v[214:217], v[36:39]
	v_mfma_f32_16x16x32_bf16 v[32:35], v[198:201], v[214:217], v[32:35]
	v_mfma_f32_16x16x32_bf16 v[20:23], v[190:193], v[222:225], v[20:23]
	v_mfma_f32_16x16x32_bf16 v[16:19], v[198:201], v[222:225], v[16:19]
	v_mfma_f32_16x16x32_bf16 v[4:7], v[190:193], v[230:233], v[4:7]
	v_mfma_f32_16x16x32_bf16 v[0:3], v[198:201], v[230:233], v[0:3]
	s_setprio 0
	s_barrier
; #define PG8_STAGE(bufoff, gbase, voff) do { _Pragma("unroll") for (int _i = 0; _i < 2; ++_i) \
;         __builtin_amdgcn_global_load_lds((const unsigned*)((const char*)(gbase) + (voff)[_i]), (LAS unsigned*)(lds + (bufoff) + ldsw + _i * 8192), 16, 0, 0); } while (0)
; #define PG8_LDA(dst, b, h) do { _Pragma("unroll") for (int m = 0; m < 4; ++m) _Pragma("unroll") for (int k = 0; k < 2; ++k) dst[m][k] = *(const LAS bf16x8*)(lds + PG8_SA(b, h) + aoff + m * 2048 + k * 1024); } while (0)
; #define PG8_LDB(dst, b, h) do { _Pragma("unroll") for (int n = 0; n < 2; ++n) _Pragma("unroll") for (int k = 0; k < 2; ++k) dst[n][k] = *(const LAS bf16x8*)(lds + PG8_SB(b, h) + boff + n * 2048 + k * 1024); } while (0)
; #define PG8_MMA(ai, bj, At, Bt) do { __builtin_amdgcn_s_setprio(1); _Pragma("unroll") for (int m = 0; m < 4; ++m) _Pragma("unroll") for (int n = 0; n < 2; ++n) _Pragma("unroll") for (int k = 0; k < 2; ++k) \
;         acc[ai][bj][m][n] = __builtin_amdgcn_mfma_f32_16x16x32_bf16(Bt[n][k], At[m][k], acc[ai][bj][m][n], 0, 0, 0); __builtin_amdgcn_s_setprio(0); } while (0)
; #define PG8_WAIT_V(n) asm volatile("s_waitcnt vmcnt(" #n ")" ::: "memory")
; #define PG8_WAIT_L(n) asm volatile("s_waitcnt lgkmcnt(" #n ")" ::: "memory")
; #define PG8_BAR __builtin_amdgcn_s_barrier()
; #define PG8_SCHED __builtin_amdgcn_sched_barrier(0)
; template <class Epi, class Sched, bool ALIGN_EPI>
; __device__ __forceinline__ void gemm_phase(LAS unsigned char* lds, const Gemm g, const Sched& S, const Epi& E, const int wid) {
;     ...
;             PG8_LDB(B0, 1, 0); PG8_LDB(B1, 1, 1); PG8_SCHED; PG8_LDA(At, 1, 0); PG8_STAGE(PG8_SA(0, 1), a2 + hstepA, voffA);
;             PG8_WAIT_V(8); PG8_WAIT_L(0); PG8_BAR; PG8_MMA(0, 0, At, B0); PG8_MMA(0, 1, At, B1); PG8_BAR; PG8_SCHED;
;             PG8_LDA(At, 1, 1); PG8_STAGE(PG8_SB(1, 0), b3, voffB); PG8_STAGE(PG8_SB(1, 1), b3 + hstepB, voffB); PG8_STAGE(PG8_SA(1, 0), a3, voffA);
;             PG8_WAIT_V(8); PG8_WAIT_L(0); PG8_BAR; PG8_MMA(1, 0, At, B0); PG8_MMA(1, 1, At, B1); PG8_BAR; PG8_SCHED;
;         }
	s_add_i32 s38, 0, 0x18000
	v_add_u32_e32 v142, s38, v170
	s_add_i32 s39, 0, 0x1c000
	ds_read_b128 v[130:133], v142
	ds_read_b128 v[134:137], v142 offset:1024
	ds_read_b128 v[138:141], v142 offset:2048
	ds_read_b128 v[182:185], v142 offset:3072
	v_add_u32_e32 v142, s39, v170
	ds_read_b128 v[186:189], v142
	ds_read_b128 v[190:193], v142 offset:1024
	ds_read_b128 v[194:197], v142 offset:2048
	ds_read_b128 v[198:201], v142 offset:3072
	s_add_u32 s74, s74, 0x4000
	s_addc_u32 s75, s75, 0
	s_mov_b32 m0, s46
	ds_read_b128 v[202:205], v177 offset:32768
	ds_read_b128 v[206:209], v177 offset:33792
	ds_read_b128 v[210:213], v177 offset:34816
	ds_read_b128 v[214:217], v177 offset:35840
	ds_read_b128 v[218:221], v177 offset:36864
	ds_read_b128 v[222:225], v177 offset:37888
	ds_read_b128 v[226:229], v177 offset:38912
	ds_read_b128 v[230:233], v177 offset:39936
	global_load_lds_dwordx4 v144, s[74:75]
	s_mov_b32 m0, s47
	s_nop 0
	global_load_lds_dwordx4 v148, s[74:75]
	s_waitcnt vmcnt(8)
	s_waitcnt lgkmcnt(0)
	s_barrier
	s_setprio 1
	s_waitcnt lgkmcnt(0)
	v_mfma_f32_16x16x32_bf16 v[124:127], v[130:133], v[202:205], v[124:127]
	v_mfma_f32_16x16x32_bf16 v[120:123], v[138:141], v[202:205], v[120:123]
	v_mfma_f32_16x16x32_bf16 v[108:111], v[130:133], v[210:213], v[108:111]
	v_mfma_f32_16x16x32_bf16 v[104:107], v[138:141], v[210:213], v[104:107]
	v_mfma_f32_16x16x32_bf16 v[92:95], v[130:133], v[218:221], v[92:95]
	v_mfma_f32_16x16x32_bf16 v[88:91], v[138:141], v[218:221], v[88:91]
	v_mfma_f32_16x16x32_bf16 v[76:79], v[130:133], v[226:229], v[76:79]
	v_mfma_f32_16x16x32_bf16 v[72:75], v[138:141], v[226:229], v[72:75]
	v_mfma_f32_16x16x32_bf16 v[124:127], v[134:137], v[206:209], v[124:127]
	v_mfma_f32_16x16x32_bf16 v[120:123], v[182:185], v[206:209], v[120:123]
	v_mfma_f32_16x16x32_bf16 v[108:111], v[134:137], v[214:217], v[108:111]
	v_mfma_f32_16x16x32_bf16 v[104:107], v[182:185], v[214:217], v[104:107]
	v_mfma_f32_16x16x32_bf16 v[92:95], v[134:137], v[222:225], v[92:95]
	v_mfma_f32_16x16x32_bf16 v[88:91], v[182:185], v[222:225], v[88:91]
	v_mfma_f32_16x16x32_bf16 v[76:79], v[134:137], v[230:233], v[76:79]
	v_mfma_f32_16x16x32_bf16 v[72:75], v[182:185], v[230:233], v[72:75]
	s_setprio 0
	s_setprio 1
	v_mfma_f32_16x16x32_bf16 v[116:119], v[186:189], v[202:205], v[116:119]
	v_mfma_f32_16x16x32_bf16 v[112:115], v[194:197], v[202:205], v[112:115]
	v_mfma_f32_16x16x32_bf16 v[100:103], v[186:189], v[210:213], v[100:103]
	v_mfma_f32_16x16x32_bf16 v[96:99], v[194:197], v[210:213], v[96:99]
	v_mfma_f32_16x16x32_bf16 v[84:87], v[186:189], v[218:221], v[84:87]
	v_mfma_f32_16x16x32_bf16 v[80:83], v[194:197], v[218:221], v[80:83]
	v_mfma_f32_16x16x32_bf16 v[68:71], v[186:189], v[226:229], v[68:71]
	v_mfma_f32_16x16x32_bf16 v[64:67], v[194:197], v[226:229], v[64:67]
	v_mfma_f32_16x16x32_bf16 v[116:119], v[190:193], v[206:209], v[116:119]
	v_mfma_f32_16x16x32_bf16 v[112:115], v[198:201], v[206:209], v[112:115]
	v_mfma_f32_16x16x32_bf16 v[100:103], v[190:193], v[214:217], v[100:103]
	v_mfma_f32_16x16x32_bf16 v[96:99], v[198:201], v[214:217], v[96:99]
	v_mfma_f32_16x16x32_bf16 v[84:87], v[190:193], v[222:225], v[84:87]
	v_mfma_f32_16x16x32_bf16 v[80:83], v[198:201], v[222:225], v[80:83]
	v_mfma_f32_16x16x32_bf16 v[68:71], v[190:193], v[230:233], v[68:71]
	v_mfma_f32_16x16x32_bf16 v[64:67], v[198:201], v[230:233], v[64:67]
	s_setprio 0
	s_barrier
	s_add_u32 s74, s72, 0x8000
	s_addc_u32 s75, s73, 0
	s_add_i32 s38, s38, s3
	s_mov_b32 m0, s38
	ds_read_b128 v[202:205], v177 offset:49152
	ds_read_b128 v[206:209], v177 offset:50176
	ds_read_b128 v[210:213], v177 offset:51200
	ds_read_b128 v[214:217], v177 offset:52224
	ds_read_b128 v[218:221], v177 offset:53248
	ds_read_b128 v[222:225], v177 offset:54272
	ds_read_b128 v[226:229], v177 offset:55296
	ds_read_b128 v[230:233], v177 offset:56320
	global_load_lds_dwordx4 v146, s[74:75]
	s_add_i32 m0, s38, 0x2000
	s_add_u32 s72, s72, 0x9000
	s_addc_u32 s73, s73, 0
	s_add_i32 s38, s39, s3
	global_load_lds_dwordx4 v150, s[74:75]
	s_mov_b32 m0, s38
	s_nop 0
	global_load_lds_dwordx4 v146, s[72:73]
	s_add_i32 m0, s38, 0x2000
	s_nop 0
	global_load_lds_dwordx4 v150, s[72:73]
	s_mov_b32 m0, s79
	s_nop 0
	global_load_lds_dwordx4 v144, s[70:71]
	s_mov_b32 m0, s80
	s_nop 0
	global_load_lds_dwordx4 v148, s[70:71]
	s_waitcnt vmcnt(8)
	s_waitcnt lgkmcnt(0)
	s_barrier
	s_setprio 1
	s_waitcnt lgkmcnt(0)
	v_mfma_f32_16x16x32_bf16 v[60:63], v[130:133], v[202:205], v[60:63]
	v_mfma_f32_16x16x32_bf16 v[56:59], v[138:141], v[202:205], v[56:59]
	v_mfma_f32_16x16x32_bf16 v[44:47], v[130:133], v[210:213], v[44:47]
	v_mfma_f32_16x16x32_bf16 v[40:43], v[138:141], v[210:213], v[40:43]
	v_mfma_f32_16x16x32_bf16 v[28:31], v[130:133], v[218:221], v[28:31]
	v_mfma_f32_16x16x32_bf16 v[24:27], v[138:141], v[218:221], v[24:27]
	v_mfma_f32_16x16x32_bf16 v[12:15], v[130:133], v[226:229], v[12:15]
	v_mfma_f32_16x16x32_bf16 v[8:11], v[138:141], v[226:229], v[8:11]
	v_mfma_f32_16x16x32_bf16 v[60:63], v[134:137], v[206:209], v[60:63]
	v_mfma_f32_16x16x32_bf16 v[56:59], v[182:185], v[206:209], v[56:59]
	v_mfma_f32_16x16x32_bf16 v[44:47], v[134:137], v[214:217], v[44:47]
	v_mfma_f32_16x16x32_bf16 v[40:43], v[182:185], v[214:217], v[40:43]
	v_mfma_f32_16x16x32_bf16 v[28:31], v[134:137], v[222:225], v[28:31]
	v_mfma_f32_16x16x32_bf16 v[24:27], v[182:185], v[222:225], v[24:27]
	v_mfma_f32_16x16x32_bf16 v[12:15], v[134:137], v[230:233], v[12:15]
	v_mfma_f32_16x16x32_bf16 v[8:11], v[182:185], v[230:233], v[8:11]
	s_setprio 0
	s_setprio 1
	v_mfma_f32_16x16x32_bf16 v[52:55], v[186:189], v[202:205], v[52:55]
	v_mfma_f32_16x16x32_bf16 v[48:51], v[194:197], v[202:205], v[48:51]
	v_mfma_f32_16x16x32_bf16 v[36:39], v[186:189], v[210:213], v[36:39]
	v_mfma_f32_16x16x32_bf16 v[32:35], v[194:197], v[210:213], v[32:35]
	v_mfma_f32_16x16x32_bf16 v[20:23], v[186:189], v[218:221], v[20:23]
	v_mfma_f32_16x16x32_bf16 v[16:19], v[194:197], v[218:221], v[16:19]
	v_mfma_f32_16x16x32_bf16 v[4:7], v[186:189], v[226:229], v[4:7]
	v_mfma_f32_16x16x32_bf16 v[0:3], v[194:197], v[226:229], v[0:3]
	v_mfma_f32_16x16x32_bf16 v[52:55], v[190:193], v[206:209], v[52:55]
	v_mfma_f32_16x16x32_bf16 v[48:51], v[198:201], v[206:209], v[48:51]
	v_mfma_f32_16x16x32_bf16 v[36:39], v[190:193], v[214:217], v[36:39]
	v_mfma_f32_16x16x32_bf16 v[32:35], v[198:201], v[214:217], v[32:35]
	v_mfma_f32_16x16x32_bf16 v[20:23], v[190:193], v[222:225], v[20:23]
	v_mfma_f32_16x16x32_bf16 v[16:19], v[198:201], v[222:225], v[16:19]
	v_mfma_f32_16x16x32_bf16 v[4:7], v[190:193], v[230:233], v[4:7]
	v_mfma_f32_16x16x32_bf16 v[0:3], v[198:201], v[230:233], v[0:3]
	s_setprio 0
	s_barrier
	s_add_i32 s54, s54, 2
	s_add_u32 s68, s68, 0x10000
	s_addc_u32 s69, s69, 0
	s_add_u32 s31, s31, 0x10000
	s_addc_u32 s35, s35, 0
	s_cmp_gt_u32 s54, 61
	s_cbranch_scc1 .LBB0_923

; #define PG8_STAGE(bufoff, gbase, voff) do { _Pragma("unroll") for (int _i = 0; _i < 2; ++_i) \
;         __builtin_amdgcn_global_load_lds((const unsigned*)((const char*)(gbase) + (voff)[_i]), (LAS unsigned*)(lds + (bufoff) + ldsw + _i * 8192), 16, 0, 0); } while (0)
; #define PG8_LDA(dst, b, h) do { _Pragma("unroll") for (int m = 0; m < 4; ++m) _Pragma("unroll") for (int k = 0; k < 2; ++k) dst[m][k] = *(const LAS bf16x8*)(lds + PG8_SA(b, h) + aoff + m * 2048 + k * 1024); } while (0)
; #define PG8_LDB(dst, b, h) do { _Pragma("unroll") for (int n = 0; n < 2; ++n) _Pragma("unroll") for (int k = 0; k < 2; ++k) dst[n][k] = *(const LAS bf16x8*)(lds + PG8_SB(b, h) + boff + n * 2048 + k * 1024); } while (0)
; #define PG8_MMA(ai, bj, At, Bt) do { __builtin_amdgcn_s_setprio(1); _Pragma("unroll") for (int m = 0; m < 4; ++m) _Pragma("unroll") for (int n = 0; n < 2; ++n) _Pragma("unroll") for (int k = 0; k < 2; ++k) \
;         acc[ai][bj][m][n] = __builtin_amdgcn_mfma_f32_16x16x32_bf16(Bt[n][k], At[m][k], acc[ai][bj][m][n], 0, 0, 0); __builtin_amdgcn_s_setprio(0); } while (0)
; #define PG8_WAIT_V(n) asm volatile("s_waitcnt vmcnt(" #n ")" ::: "memory")
; #define PG8_WAIT_L(n) asm volatile("s_waitcnt lgkmcnt(" #n ")" ::: "memory")
; #define PG8_BAR __builtin_amdgcn_s_barrier()
; #define PG8_SCHED __builtin_amdgcn_sched_barrier(0)
; template <class Epi, class Sched, bool ALIGN_EPI>
; __device__ __forceinline__ void gemm_phase(LAS unsigned char* lds, const Gemm g, const Sched& S, const Epi& E, const int wid) {
;     ...
;             const char* a1 = cA + (size_t)(t + 1) * kstepA;
;             const char* a2 = last ? nA : cA + (size_t)(t + 2) * kstepA; const char* b2 = last ? nB : cB + (size_t)(t + 2) * kstep;
;             const char* a3 = a2 + kstepA; const char* b3 = b2 + kstep;
;             PG8_LDB(B0, 0, 0); PG8_LDB(B1, 0, 1); PG8_SCHED; PG8_LDA(At, 0, 0); PG8_STAGE(PG8_SA(1, 1), a1 + hstepA, voffA);
;             PG8_WAIT_V(8); PG8_WAIT_L(0); PG8_BAR; PG8_MMA(0, 0, At, B0); PG8_MMA(0, 1, At, B1); PG8_BAR; PG8_SCHED;
;             PG8_LDA(At, 0, 1); PG8_STAGE(PG8_SB(0, 0), b2, voffB); PG8_STAGE(PG8_SB(0, 1), b2 + hstepB, voffB); PG8_STAGE(PG8_SA(0, 0), a2, voffA);
;             PG8_WAIT_V(8); PG8_WAIT_L(0); PG8_BAR; PG8_MMA(1, 0, At, B0); PG8_MMA(1, 1, At, B1); PG8_BAR; PG8_SCHED;
.LBB0_1438:
	ds_read_b128 v[72:75], v202
	ds_read_b128 v[76:79], v202 offset:1024
	ds_read_b128 v[136:139], v202 offset:2048
	ds_read_b128 v[140:143], v202 offset:3072
	ds_read_b128 v[144:147], v203
	ds_read_b128 v[148:151], v203 offset:1024
	ds_read_b128 v[152:155], v203 offset:2048
	ds_read_b128 v[178:181], v203 offset:3072
	s_add_u32 s38, s20, 0xfff00080
	s_addc_u32 s39, s21, -1
	s_cmp_eq_u32 s55, 60
	s_cselect_b32 s71, s4, s39
	s_cselect_b32 s70, s5, s38
	s_cselect_b32 s69, s30, s54
	s_cselect_b32 s68, s31, s35
	s_add_i32 m0, s44, 0xc000
	ds_read_b128 v[182:185], v204
	ds_read_b128 v[186:189], v204 offset:1024
	ds_read_b128 v[190:193], v204 offset:2048
	ds_read_b128 v[194:197], v204 offset:3072
	ds_read_b128 v[208:211], v204 offset:4096
	ds_read_b128 v[212:215], v204 offset:5120
	ds_read_b128 v[216:219], v204 offset:6144
	ds_read_b128 v[220:223], v204 offset:7168
	global_load_lds_dwordx4 v168, s[20:21]
	s_add_i32 m0, s44, 0xe000
	s_nop 0
	global_load_lds_dwordx4 v170, s[20:21]
	s_waitcnt vmcnt(8)
	s_waitcnt lgkmcnt(0)
	s_barrier
	s_setprio 1
	s_waitcnt lgkmcnt(0)
	v_mfma_f32_16x16x32_bf16 v[132:135], v[72:75], v[182:185], v[132:135]
	v_mfma_f32_16x16x32_bf16 v[128:131], v[136:139], v[182:185], v[128:131]
	v_mfma_f32_16x16x32_bf16 v[116:119], v[72:75], v[190:193], v[116:119]
	v_mfma_f32_16x16x32_bf16 v[112:115], v[136:139], v[190:193], v[112:115]
	v_mfma_f32_16x16x32_bf16 v[100:103], v[72:75], v[208:211], v[100:103]
	v_mfma_f32_16x16x32_bf16 v[96:99], v[136:139], v[208:211], v[96:99]
	v_mfma_f32_16x16x32_bf16 v[84:87], v[72:75], v[216:219], v[84:87]
	v_mfma_f32_16x16x32_bf16 v[80:83], v[136:139], v[216:219], v[80:83]
	v_mfma_f32_16x16x32_bf16 v[132:135], v[76:79], v[186:189], v[132:135]
	v_mfma_f32_16x16x32_bf16 v[128:131], v[140:143], v[186:189], v[128:131]
	v_mfma_f32_16x16x32_bf16 v[116:119], v[76:79], v[194:197], v[116:119]
	v_mfma_f32_16x16x32_bf16 v[112:115], v[140:143], v[194:197], v[112:115]
	v_mfma_f32_16x16x32_bf16 v[100:103], v[76:79], v[212:215], v[100:103]
	v_mfma_f32_16x16x32_bf16 v[96:99], v[140:143], v[212:215], v[96:99]
	v_mfma_f32_16x16x32_bf16 v[84:87], v[76:79], v[220:223], v[84:87]
	v_mfma_f32_16x16x32_bf16 v[80:83], v[140:143], v[220:223], v[80:83]
	s_setprio 0
	s_setprio 1
	v_mfma_f32_16x16x32_bf16 v[124:127], v[144:147], v[182:185], v[124:127]
	v_mfma_f32_16x16x32_bf16 v[120:123], v[152:155], v[182:185], v[120:123]
	v_mfma_f32_16x16x32_bf16 v[108:111], v[144:147], v[190:193], v[108:111]
	v_mfma_f32_16x16x32_bf16 v[104:107], v[152:155], v[190:193], v[104:107]
	v_mfma_f32_16x16x32_bf16 v[92:95], v[144:147], v[208:211], v[92:95]
	v_mfma_f32_16x16x32_bf16 v[88:91], v[152:155], v[208:211], v[88:91]
	v_mfma_f32_16x16x32_bf16 v[68:71], v[144:147], v[216:219], v[68:71]
	v_mfma_f32_16x16x32_bf16 v[64:67], v[152:155], v[216:219], v[64:67]
	v_mfma_f32_16x16x32_bf16 v[124:127], v[148:151], v[186:189], v[124:127]
	v_mfma_f32_16x16x32_bf16 v[120:123], v[178:181], v[186:189], v[120:123]
	v_mfma_f32_16x16x32_bf16 v[108:111], v[148:151], v[194:197], v[108:111]
	v_mfma_f32_16x16x32_bf16 v[104:107], v[178:181], v[194:197], v[104:107]
	v_mfma_f32_16x16x32_bf16 v[92:95], v[148:151], v[212:215], v[92:95]
	v_mfma_f32_16x16x32_bf16 v[88:91], v[178:181], v[212:215], v[88:91]
	v_mfma_f32_16x16x32_bf16 v[68:71], v[148:151], v[220:223], v[68:71]
	v_mfma_f32_16x16x32_bf16 v[64:67], v[178:181], v[220:223], v[64:67]
	s_setprio 0
	s_barrier
	s_add_i32 s38, s75, s3
	s_mov_b32 m0, s38
	ds_read_b128 v[182:185], v204 offset:16384
	ds_read_b128 v[186:189], v204 offset:17408
	ds_read_b128 v[190:193], v204 offset:18432
	ds_read_b128 v[194:197], v204 offset:19456
	ds_read_b128 v[208:211], v204 offset:20480
	ds_read_b128 v[212:215], v204 offset:21504
	ds_read_b128 v[216:219], v204 offset:22528
	ds_read_b128 v[220:223], v204 offset:23552
	global_load_lds_dwordx4 v158, s[68:69]
	s_add_i32 m0, s38, 0x2000
	s_add_u32 s38, s68, 0x1000
	s_addc_u32 s39, s69, 0
	s_add_i32 s57, s76, s3
	global_load_lds_dwordx4 v162, s[68:69]
	s_mov_b32 m0, s57
	v_lshl_add_u64 v[226:227], s[70:71], 0, v[160:161]
	global_load_lds_dwordx4 v158, s[38:39]
	s_add_i32 m0, s57, 0x2000
	s_nop 0
	global_load_lds_dwordx4 v162, s[38:39]
	v_lshl_add_u64 v[224:225], s[70:71], 0, v[156:157]
	s_mov_b32 m0, s44
	s_nop 0
	global_load_lds_dwordx4 v[224:225], off
	s_mov_b32 m0, s45
	s_nop 0
	global_load_lds_dwordx4 v[226:227], off
	s_waitcnt vmcnt(8)
	s_waitcnt lgkmcnt(0)
	s_barrier
	s_setprio 1
	s_waitcnt lgkmcnt(0)
	v_mfma_f32_16x16x32_bf16 v[60:63], v[72:75], v[182:185], v[60:63]
	v_mfma_f32_16x16x32_bf16 v[56:59], v[136:139], v[182:185], v[56:59]
	v_mfma_f32_16x16x32_bf16 v[44:47], v[72:75], v[190:193], v[44:47]
	v_mfma_f32_16x16x32_bf16 v[40:43], v[136:139], v[190:193], v[40:43]
	v_mfma_f32_16x16x32_bf16 v[28:31], v[72:75], v[208:211], v[28:31]
	v_mfma_f32_16x16x32_bf16 v[24:27], v[136:139], v[208:211], v[24:27]
	v_mfma_f32_16x16x32_bf16 v[12:15], v[72:75], v[216:219], v[12:15]
	v_mfma_f32_16x16x32_bf16 v[8:11], v[136:139], v[216:219], v[8:11]
	v_mfma_f32_16x16x32_bf16 v[60:63], v[76:79], v[186:189], v[60:63]
	v_mfma_f32_16x16x32_bf16 v[56:59], v[140:143], v[186:189], v[56:59]
	v_mfma_f32_16x16x32_bf16 v[44:47], v[76:79], v[194:197], v[44:47]
	v_mfma_f32_16x16x32_bf16 v[40:43], v[140:143], v[194:197], v[40:43]
	v_mfma_f32_16x16x32_bf16 v[28:31], v[76:79], v[212:215], v[28:31]
	v_mfma_f32_16x16x32_bf16 v[24:27], v[140:143], v[212:215], v[24:27]
	v_mfma_f32_16x16x32_bf16 v[12:15], v[76:79], v[220:223], v[12:15]
	v_mfma_f32_16x16x32_bf16 v[8:11], v[140:143], v[220:223], v[8:11]
	s_setprio 0
	s_setprio 1
	v_mfma_f32_16x16x32_bf16 v[52:55], v[144:147], v[182:185], v[52:55]
	v_mfma_f32_16x16x32_bf16 v[48:51], v[152:155], v[182:185], v[48:51]
	v_mfma_f32_16x16x32_bf16 v[36:39], v[144:147], v[190:193], v[36:39]
	v_mfma_f32_16x16x32_bf16 v[32:35], v[152:155], v[190:193], v[32:35]
	v_mfma_f32_16x16x32_bf16 v[20:23], v[144:147], v[208:211], v[20:23]
	v_mfma_f32_16x16x32_bf16 v[16:19], v[152:155], v[208:211], v[16:19]
	v_mfma_f32_16x16x32_bf16 v[4:7], v[144:147], v[216:219], v[4:7]
	v_mfma_f32_16x16x32_bf16 v[0:3], v[152:155], v[216:219], v[0:3]
	v_mfma_f32_16x16x32_bf16 v[52:55], v[148:151], v[186:189], v[52:55]
	v_mfma_f32_16x16x32_bf16 v[48:51], v[178:181], v[186:189], v[48:51]
	v_mfma_f32_16x16x32_bf16 v[36:39], v[148:151], v[194:197], v[36:39]
	v_mfma_f32_16x16x32_bf16 v[32:35], v[178:181], v[194:197], v[32:35]
	v_mfma_f32_16x16x32_bf16 v[20:23], v[148:151], v[212:215], v[20:23]
	v_mfma_f32_16x16x32_bf16 v[16:19], v[178:181], v[212:215], v[16:19]
	v_mfma_f32_16x16x32_bf16 v[4:7], v[148:151], v[220:223], v[4:7]
	v_mfma_f32_16x16x32_bf16 v[0:3], v[178:181], v[220:223], v[0:3]
	s_setprio 0
	s_barrier
; #define PG8_STAGE(bufoff, gbase, voff) do { _Pragma("unroll") for (int _i = 0; _i < 2; ++_i) \
;         __builtin_amdgcn_global_load_lds((const unsigned*)((const char*)(gbase) + (voff)[_i]), (LAS unsigned*)(lds + (bufoff) + ldsw + _i * 8192), 16, 0, 0); } while (0)
; #define PG8_LDA(dst, b, h) do { _Pragma("unroll") for (int m = 0; m < 4; ++m) _Pragma("unroll") for (int k = 0; k < 2; ++k) dst[m][k] = *(const LAS bf16x8*)(lds + PG8_SA(b, h) + aoff + m * 2048 + k * 1024); } while (0)
; #define PG8_LDB(dst, b, h) do { _Pragma("unroll") for (int n = 0; n < 2; ++n) _Pragma("unroll") for (int k = 0; k < 2; ++k) dst[n][k] = *(const LAS bf16x8*)(lds + PG8_SB(b, h) + boff + n * 2048 + k * 1024); } while (0)
; #define PG8_MMA(ai, bj, At, Bt) do { __builtin_amdgcn_s_setprio(1); _Pragma("unroll") for (int m = 0; m < 4; ++m) _Pragma("unroll") for (int n = 0; n < 2; ++n) _Pragma("unroll") for (int k = 0; k < 2; ++k) \
;         acc[ai][bj][m][n] = __builtin_amdgcn_mfma_f32_16x16x32_bf16(Bt[n][k], At[m][k], acc[ai][bj][m][n], 0, 0, 0); __builtin_amdgcn_s_setprio(0); } while (0)
; #define PG8_WAIT_V(n) asm volatile("s_waitcnt vmcnt(" #n ")" ::: "memory")
; #define PG8_WAIT_L(n) asm volatile("s_waitcnt lgkmcnt(" #n ")" ::: "memory")
; #define PG8_BAR __builtin_amdgcn_s_barrier()
; #define PG8_SCHED __builtin_amdgcn_sched_barrier(0)
; template <class Epi, class Sched, bool ALIGN_EPI>
; __device__ __forceinline__ void gemm_phase(LAS unsigned char* lds, const Gemm g, const Sched& S, const Epi& E, const int wid) {
;     ...
;             PG8_LDB(B0, 1, 0); PG8_LDB(B1, 1, 1); PG8_SCHED; PG8_LDA(At, 1, 0); PG8_STAGE(PG8_SA(0, 1), a2 + hstepA, voffA);
;             PG8_WAIT_V(8); PG8_WAIT_L(0); PG8_BAR; PG8_MMA(0, 0, At, B0); PG8_MMA(0, 1, At, B1); PG8_BAR; PG8_SCHED;
;             PG8_LDA(At, 1, 1); PG8_STAGE(PG8_SB(1, 0), b3, voffB); PG8_STAGE(PG8_SB(1, 1), b3 + hstepB, voffB); PG8_STAGE(PG8_SA(1, 0), a3, voffA);
;             PG8_WAIT_V(8); PG8_WAIT_L(0); PG8_BAR; PG8_MMA(1, 0, At, B0); PG8_MMA(1, 1, At, B1); PG8_BAR; PG8_SCHED;
;         }
	s_add_i32 s57, 0, 0x18000
	s_add_i32 s59, 0, 0x1c000
	v_add_u32_e32 v140, s57, v198
	v_add_u32_e32 v164, s59, v198
	ds_read_b128 v[72:75], v140
	ds_read_b128 v[76:79], v140 offset:1024
	ds_read_b128 v[136:139], v140 offset:2048
	ds_read_b128 v[140:143], v140 offset:3072
	ds_read_b128 v[144:147], v164
	ds_read_b128 v[148:151], v164 offset:1024
	ds_read_b128 v[152:155], v164 offset:2048
	ds_read_b128 v[178:181], v164 offset:3072
	s_add_u32 s38, s70, 0x100000
	s_addc_u32 s39, s71, 0
	s_mov_b32 m0, s46
	ds_read_b128 v[182:185], v204 offset:32768
	ds_read_b128 v[186:189], v204 offset:33792
	ds_read_b128 v[190:193], v204 offset:34816
	ds_read_b128 v[194:197], v204 offset:35840
	ds_read_b128 v[208:211], v204 offset:36864
	ds_read_b128 v[212:215], v204 offset:37888
	ds_read_b128 v[216:219], v204 offset:38912
	ds_read_b128 v[220:223], v204 offset:39936
	global_load_lds_dwordx4 v156, s[38:39]
	s_mov_b32 m0, s47
	s_nop 0
	global_load_lds_dwordx4 v160, s[38:39]
	s_waitcnt vmcnt(8)
	s_waitcnt lgkmcnt(0)
	s_barrier
	s_setprio 1
	s_waitcnt lgkmcnt(0)
	v_mfma_f32_16x16x32_bf16 v[132:135], v[72:75], v[182:185], v[132:135]
	v_mfma_f32_16x16x32_bf16 v[128:131], v[136:139], v[182:185], v[128:131]
	v_mfma_f32_16x16x32_bf16 v[116:119], v[72:75], v[190:193], v[116:119]
	v_mfma_f32_16x16x32_bf16 v[112:115], v[136:139], v[190:193], v[112:115]
	v_mfma_f32_16x16x32_bf16 v[100:103], v[72:75], v[208:211], v[100:103]
	v_mfma_f32_16x16x32_bf16 v[96:99], v[136:139], v[208:211], v[96:99]
	v_mfma_f32_16x16x32_bf16 v[84:87], v[72:75], v[216:219], v[84:87]
	v_mfma_f32_16x16x32_bf16 v[80:83], v[136:139], v[216:219], v[80:83]
	v_mfma_f32_16x16x32_bf16 v[132:135], v[76:79], v[186:189], v[132:135]
	v_mfma_f32_16x16x32_bf16 v[128:131], v[140:143], v[186:189], v[128:131]
	v_mfma_f32_16x16x32_bf16 v[116:119], v[76:79], v[194:197], v[116:119]
	v_mfma_f32_16x16x32_bf16 v[112:115], v[140:143], v[194:197], v[112:115]
	v_mfma_f32_16x16x32_bf16 v[100:103], v[76:79], v[212:215], v[100:103]
	v_mfma_f32_16x16x32_bf16 v[96:99], v[140:143], v[212:215], v[96:99]
	v_mfma_f32_16x16x32_bf16 v[84:87], v[76:79], v[220:223], v[84:87]
	v_mfma_f32_16x16x32_bf16 v[80:83], v[140:143], v[220:223], v[80:83]
	s_setprio 0
	s_setprio 1
	v_mfma_f32_16x16x32_bf16 v[124:127], v[144:147], v[182:185], v[124:127]
	v_mfma_f32_16x16x32_bf16 v[120:123], v[152:155], v[182:185], v[120:123]
	v_mfma_f32_16x16x32_bf16 v[108:111], v[144:147], v[190:193], v[108:111]
	v_mfma_f32_16x16x32_bf16 v[104:107], v[152:155], v[190:193], v[104:107]
	v_mfma_f32_16x16x32_bf16 v[92:95], v[144:147], v[208:211], v[92:95]
	v_mfma_f32_16x16x32_bf16 v[88:91], v[152:155], v[208:211], v[88:91]
	v_mfma_f32_16x16x32_bf16 v[68:71], v[144:147], v[216:219], v[68:71]
	v_mfma_f32_16x16x32_bf16 v[64:67], v[152:155], v[216:219], v[64:67]
	v_mfma_f32_16x16x32_bf16 v[124:127], v[148:151], v[186:189], v[124:127]
	v_mfma_f32_16x16x32_bf16 v[120:123], v[178:181], v[186:189], v[120:123]
	v_mfma_f32_16x16x32_bf16 v[108:111], v[148:151], v[194:197], v[108:111]
	v_mfma_f32_16x16x32_bf16 v[104:107], v[178:181], v[194:197], v[104:107]
	v_mfma_f32_16x16x32_bf16 v[92:95], v[148:151], v[212:215], v[92:95]
	v_mfma_f32_16x16x32_bf16 v[88:91], v[178:181], v[212:215], v[88:91]
	v_mfma_f32_16x16x32_bf16 v[68:71], v[148:151], v[220:223], v[68:71]
	v_mfma_f32_16x16x32_bf16 v[64:67], v[178:181], v[220:223], v[64:67]
	s_setprio 0
	s_barrier
	s_add_u32 s38, s68, 0x8000
	s_addc_u32 s39, s69, 0
	s_add_i32 s57, s57, s3
	s_mov_b32 m0, s57
	ds_read_b128 v[182:185], v204 offset:49152
	ds_read_b128 v[186:189], v204 offset:50176
	ds_read_b128 v[190:193], v204 offset:51200
	ds_read_b128 v[194:197], v204 offset:52224
	ds_read_b128 v[208:211], v204 offset:53248
	ds_read_b128 v[212:215], v204 offset:54272
	ds_read_b128 v[216:219], v204 offset:55296
	ds_read_b128 v[220:223], v204 offset:56320
	global_load_lds_dwordx4 v158, s[38:39]
	s_add_i32 m0, s57, 0x2000
	s_nop 0
	global_load_lds_dwordx4 v162, s[38:39]
	s_add_u32 s38, s68, 0x9000
	s_addc_u32 s39, s69, 0
	s_add_i32 s57, s59, s3
	s_mov_b32 m0, s57
	v_lshl_add_u64 v[224:225], v[224:225], 0, s[48:49]
	global_load_lds_dwordx4 v158, s[38:39]
	s_add_i32 m0, s57, 0x2000
	s_nop 0
	global_load_lds_dwordx4 v162, s[38:39]
	s_mov_b32 m0, s72
	s_nop 0
	global_load_lds_dwordx4 v[224:225], off
	v_lshl_add_u64 v[224:225], v[226:227], 0, s[48:49]
	s_mov_b32 m0, s73
	s_nop 0
	global_load_lds_dwordx4 v[224:225], off
	s_waitcnt vmcnt(8)
	s_waitcnt lgkmcnt(0)
	s_barrier
	s_setprio 1
	s_waitcnt lgkmcnt(0)
	v_mfma_f32_16x16x32_bf16 v[60:63], v[72:75], v[182:185], v[60:63]
	v_mfma_f32_16x16x32_bf16 v[56:59], v[136:139], v[182:185], v[56:59]
	v_mfma_f32_16x16x32_bf16 v[44:47], v[72:75], v[190:193], v[44:47]
	v_mfma_f32_16x16x32_bf16 v[40:43], v[136:139], v[190:193], v[40:43]
	v_mfma_f32_16x16x32_bf16 v[28:31], v[72:75], v[208:211], v[28:31]
	v_mfma_f32_16x16x32_bf16 v[24:27], v[136:139], v[208:211], v[24:27]
	v_mfma_f32_16x16x32_bf16 v[12:15], v[72:75], v[216:219], v[12:15]
	v_mfma_f32_16x16x32_bf16 v[8:11], v[136:139], v[216:219], v[8:11]
	v_mfma_f32_16x16x32_bf16 v[60:63], v[76:79], v[186:189], v[60:63]
	v_mfma_f32_16x16x32_bf16 v[56:59], v[140:143], v[186:189], v[56:59]
	v_mfma_f32_16x16x32_bf16 v[44:47], v[76:79], v[194:197], v[44:47]
	v_mfma_f32_16x16x32_bf16 v[40:43], v[140:143], v[194:197], v[40:43]
	v_mfma_f32_16x16x32_bf16 v[28:31], v[76:79], v[212:215], v[28:31]
	v_mfma_f32_16x16x32_bf16 v[24:27], v[140:143], v[212:215], v[24:27]
	v_mfma_f32_16x16x32_bf16 v[12:15], v[76:79], v[220:223], v[12:15]
	v_mfma_f32_16x16x32_bf16 v[8:11], v[140:143], v[220:223], v[8:11]
	s_setprio 0
	s_setprio 1
	v_mfma_f32_16x16x32_bf16 v[52:55], v[144:147], v[182:185], v[52:55]
	v_mfma_f32_16x16x32_bf16 v[48:51], v[152:155], v[182:185], v[48:51]
	v_mfma_f32_16x16x32_bf16 v[36:39], v[144:147], v[190:193], v[36:39]
	v_mfma_f32_16x16x32_bf16 v[32:35], v[152:155], v[190:193], v[32:35]
	v_mfma_f32_16x16x32_bf16 v[20:23], v[144:147], v[208:211], v[20:23]
	v_mfma_f32_16x16x32_bf16 v[16:19], v[152:155], v[208:211], v[16:19]
	v_mfma_f32_16x16x32_bf16 v[4:7], v[144:147], v[216:219], v[4:7]
	v_mfma_f32_16x16x32_bf16 v[0:3], v[152:155], v[216:219], v[0:3]
	v_mfma_f32_16x16x32_bf16 v[52:55], v[148:151], v[186:189], v[52:55]
	v_mfma_f32_16x16x32_bf16 v[48:51], v[178:181], v[186:189], v[48:51]
	v_mfma_f32_16x16x32_bf16 v[36:39], v[148:151], v[194:197], v[36:39]
	v_mfma_f32_16x16x32_bf16 v[32:35], v[178:181], v[194:197], v[32:35]
	v_mfma_f32_16x16x32_bf16 v[20:23], v[148:151], v[212:215], v[20:23]
	v_mfma_f32_16x16x32_bf16 v[16:19], v[178:181], v[212:215], v[16:19]
	v_mfma_f32_16x16x32_bf16 v[4:7], v[148:151], v[220:223], v[4:7]
	v_mfma_f32_16x16x32_bf16 v[0:3], v[178:181], v[220:223], v[0:3]
	s_setprio 0
	s_barrier
	s_add_i32 s55, s55, 2
	s_add_u32 s20, s20, 0x100
	s_addc_u32 s21, s21, 0
	s_add_u32 s35, s35, 0x10000
	s_addc_u32 s54, s54, 0
	s_cmp_gt_u32 s55, 61
	s_cbranch_scc0 .LBB0_1438
	s_and_b64 vcc, exec, s[28:29]
	s_cbranch_vccz .LBB0_1441
	s_barrier

; #define PG8_STAGE(bufoff, gbase, voff) do { _Pragma("unroll") for (int _i = 0; _i < 2; ++_i) \
;         __builtin_amdgcn_global_load_lds((const unsigned*)((const char*)(gbase) + (voff)[_i]), (LAS unsigned*)(lds + (bufoff) + ldsw + _i * 8192), 16, 0, 0); } while (0)
; #define PG8_LDA(dst, b, h) do { _Pragma("unroll") for (int m = 0; m < 4; ++m) _Pragma("unroll") for (int k = 0; k < 2; ++k) dst[m][k] = *(const LAS bf16x8*)(lds + PG8_SA(b, h) + aoff + m * 2048 + k * 1024); } while (0)
; #define PG8_LDB(dst, b, h) do { _Pragma("unroll") for (int n = 0; n < 2; ++n) _Pragma("unroll") for (int k = 0; k < 2; ++k) dst[n][k] = *(const LAS bf16x8*)(lds + PG8_SB(b, h) + boff + n * 2048 + k * 1024); } while (0)
; #define PG8_MMA(ai, bj, At, Bt) do { __builtin_amdgcn_s_setprio(1); _Pragma("unroll") for (int m = 0; m < 4; ++m) _Pragma("unroll") for (int n = 0; n < 2; ++n) _Pragma("unroll") for (int k = 0; k < 2; ++k) \
;         acc[ai][bj][m][n] = __builtin_amdgcn_mfma_f32_16x16x32_bf16(Bt[n][k], At[m][k], acc[ai][bj][m][n], 0, 0, 0); __builtin_amdgcn_s_setprio(0); } while (0)
; #define PG8_WAIT_V(n) asm volatile("s_waitcnt vmcnt(" #n ")" ::: "memory")
; #define PG8_WAIT_L(n) asm volatile("s_waitcnt lgkmcnt(" #n ")" ::: "memory")
; #define PG8_BAR __builtin_amdgcn_s_barrier()
; #define PG8_SCHED __builtin_amdgcn_sched_barrier(0)
; template <class Epi, class Sched, bool ALIGN_EPI>
; __device__ __forceinline__ void gemm_phase(LAS unsigned char* lds, const Gemm g, const Sched& S, const Epi& E, const int wid) {
;     ...
;             const char* a1 = cA + (size_t)(t + 1) * kstepA;
;             const char* a2 = last ? nA : cA + (size_t)(t + 2) * kstepA; const char* b2 = last ? nB : cB + (size_t)(t + 2) * kstep;
;             const char* a3 = a2 + kstepA; const char* b3 = b2 + kstep;
;             PG8_LDB(B0, 0, 0); PG8_LDB(B1, 0, 1); PG8_SCHED; PG8_LDA(At, 0, 0); PG8_STAGE(PG8_SA(1, 1), a1 + hstepA, voffA);
;             PG8_WAIT_V(8); PG8_WAIT_L(0); PG8_BAR; PG8_MMA(0, 0, At, B0); PG8_MMA(0, 1, At, B1); PG8_BAR; PG8_SCHED;
;             PG8_LDA(At, 0, 1); PG8_STAGE(PG8_SB(0, 0), b2, voffB); PG8_STAGE(PG8_SB(0, 1), b2 + hstepB, voffB); PG8_STAGE(PG8_SA(0, 0), a2, voffA);
;             PG8_WAIT_V(8); PG8_WAIT_L(0); PG8_BAR; PG8_MMA(1, 0, At, B0); PG8_MMA(1, 1, At, B1); PG8_BAR; PG8_SCHED;
.LBB0_1568:
	v_add_u32_e32 v138, s63, v160
	ds_read_b128 v[130:133], v138
	ds_read_b128 v[134:137], v138 offset:1024
	ds_read_b128 v[170:173], v138 offset:2048
	ds_read_b128 v[174:177], v138 offset:3072
	v_add_u32_e32 v138, s64, v160
	s_add_u32 s56, s16, 0x4000
	ds_read_b128 v[178:181], v138
	ds_read_b128 v[182:185], v138 offset:1024
	ds_read_b128 v[186:189], v138 offset:2048
	ds_read_b128 v[190:193], v138 offset:3072
	s_addc_u32 s57, s17, 0
	s_and_b64 s[38:39], s[58:59], exec
	s_cselect_b32 s60, s35, s56
	s_cselect_b32 s61, s27, s57
	s_add_u32 s56, s60, 0x8000
	s_addc_u32 s57, s61, 0
	s_and_b64 s[38:39], s[58:59], exec
	s_cselect_b32 s59, s25, s69
	s_cselect_b32 s58, s53, s68
	s_add_i32 m0, s31, 0xc000
	ds_read_b128 v[194:197], v166
	ds_read_b128 v[198:201], v166 offset:1024
	ds_read_b128 v[202:205], v166 offset:2048
	ds_read_b128 v[206:209], v166 offset:3072
	ds_read_b128 v[210:213], v166 offset:4096
	ds_read_b128 v[214:217], v166 offset:5120
	ds_read_b128 v[218:221], v166 offset:6144
	ds_read_b128 v[222:225], v166 offset:7168
	global_load_lds_dwordx4 v150, s[16:17]
	s_add_i32 m0, s31, 0xe000
	s_nop 0
	global_load_lds_dwordx4 v152, s[16:17]
	s_waitcnt vmcnt(8)
	s_waitcnt lgkmcnt(0)
	s_barrier
	s_setprio 1
	s_waitcnt lgkmcnt(0)
	v_mfma_f32_16x16x32_bf16 v[124:127], v[130:133], v[194:197], v[124:127]
	v_mfma_f32_16x16x32_bf16 v[120:123], v[170:173], v[194:197], v[120:123]
	v_mfma_f32_16x16x32_bf16 v[108:111], v[130:133], v[202:205], v[108:111]
	v_mfma_f32_16x16x32_bf16 v[104:107], v[170:173], v[202:205], v[104:107]
	v_mfma_f32_16x16x32_bf16 v[92:95], v[130:133], v[210:213], v[92:95]
	v_mfma_f32_16x16x32_bf16 v[88:91], v[170:173], v[210:213], v[88:91]
	v_mfma_f32_16x16x32_bf16 v[76:79], v[130:133], v[218:221], v[76:79]
	v_mfma_f32_16x16x32_bf16 v[72:75], v[170:173], v[218:221], v[72:75]
	v_mfma_f32_16x16x32_bf16 v[124:127], v[134:137], v[198:201], v[124:127]
	v_mfma_f32_16x16x32_bf16 v[120:123], v[174:177], v[198:201], v[120:123]
	v_mfma_f32_16x16x32_bf16 v[108:111], v[134:137], v[206:209], v[108:111]
	v_mfma_f32_16x16x32_bf16 v[104:107], v[174:177], v[206:209], v[104:107]
	v_mfma_f32_16x16x32_bf16 v[92:95], v[134:137], v[214:217], v[92:95]
	v_mfma_f32_16x16x32_bf16 v[88:91], v[174:177], v[214:217], v[88:91]
	v_mfma_f32_16x16x32_bf16 v[76:79], v[134:137], v[222:225], v[76:79]
	v_mfma_f32_16x16x32_bf16 v[72:75], v[174:177], v[222:225], v[72:75]
	s_setprio 0
	s_setprio 1
	v_mfma_f32_16x16x32_bf16 v[116:119], v[178:181], v[194:197], v[116:119]
	v_mfma_f32_16x16x32_bf16 v[112:115], v[186:189], v[194:197], v[112:115]
	v_mfma_f32_16x16x32_bf16 v[100:103], v[178:181], v[202:205], v[100:103]
	v_mfma_f32_16x16x32_bf16 v[96:99], v[186:189], v[202:205], v[96:99]
	v_mfma_f32_16x16x32_bf16 v[84:87], v[178:181], v[210:213], v[84:87]
	v_mfma_f32_16x16x32_bf16 v[80:83], v[186:189], v[210:213], v[80:83]
	v_mfma_f32_16x16x32_bf16 v[68:71], v[178:181], v[218:221], v[68:71]
	v_mfma_f32_16x16x32_bf16 v[64:67], v[186:189], v[218:221], v[64:67]
	v_mfma_f32_16x16x32_bf16 v[116:119], v[182:185], v[198:201], v[116:119]
	v_mfma_f32_16x16x32_bf16 v[112:115], v[190:193], v[198:201], v[112:115]
	v_mfma_f32_16x16x32_bf16 v[100:103], v[182:185], v[206:209], v[100:103]
	v_mfma_f32_16x16x32_bf16 v[96:99], v[190:193], v[206:209], v[96:99]
	v_mfma_f32_16x16x32_bf16 v[84:87], v[182:185], v[214:217], v[84:87]
	v_mfma_f32_16x16x32_bf16 v[80:83], v[190:193], v[214:217], v[80:83]
	v_mfma_f32_16x16x32_bf16 v[68:71], v[182:185], v[222:225], v[68:71]
	v_mfma_f32_16x16x32_bf16 v[64:67], v[190:193], v[222:225], v[64:67]
	s_setprio 0
	s_barrier
	s_add_i32 s38, s63, s3
	s_mov_b32 m0, s38
	ds_read_b128 v[194:197], v166 offset:16384
	ds_read_b128 v[198:201], v166 offset:17408
	ds_read_b128 v[202:205], v166 offset:18432
	ds_read_b128 v[206:209], v166 offset:19456
	ds_read_b128 v[210:213], v166 offset:20480
	ds_read_b128 v[214:217], v166 offset:21504
	ds_read_b128 v[218:221], v166 offset:22528
	ds_read_b128 v[222:225], v166 offset:23552
	global_load_lds_dwordx4 v144, s[58:59]
	s_add_i32 m0, s38, 0x2000
	s_add_u32 s38, s58, 0x1000
	s_addc_u32 s39, s59, 0
	s_add_i32 s71, s64, s3
	global_load_lds_dwordx4 v140, s[58:59]
	s_mov_b32 m0, s71
	s_nop 0
	global_load_lds_dwordx4 v144, s[38:39]
	s_add_i32 m0, s71, 0x2000
	s_nop 0
	global_load_lds_dwordx4 v140, s[38:39]
	s_mov_b32 m0, s31
	s_nop 0
	global_load_lds_dwordx4 v146, s[60:61]
	s_mov_b32 m0, s42
	s_nop 0
	global_load_lds_dwordx4 v142, s[60:61]
	s_waitcnt vmcnt(8)
	s_waitcnt lgkmcnt(0)
	s_barrier
	s_setprio 1
	s_waitcnt lgkmcnt(0)
	v_mfma_f32_16x16x32_bf16 v[60:63], v[130:133], v[194:197], v[60:63]
	v_mfma_f32_16x16x32_bf16 v[56:59], v[170:173], v[194:197], v[56:59]
	v_mfma_f32_16x16x32_bf16 v[44:47], v[130:133], v[202:205], v[44:47]
	v_mfma_f32_16x16x32_bf16 v[40:43], v[170:173], v[202:205], v[40:43]
	v_mfma_f32_16x16x32_bf16 v[28:31], v[130:133], v[210:213], v[28:31]
	v_mfma_f32_16x16x32_bf16 v[24:27], v[170:173], v[210:213], v[24:27]
	v_mfma_f32_16x16x32_bf16 v[12:15], v[130:133], v[218:221], v[12:15]
	v_mfma_f32_16x16x32_bf16 v[8:11], v[170:173], v[218:221], v[8:11]
	v_mfma_f32_16x16x32_bf16 v[60:63], v[134:137], v[198:201], v[60:63]
	v_mfma_f32_16x16x32_bf16 v[56:59], v[174:177], v[198:201], v[56:59]
	v_mfma_f32_16x16x32_bf16 v[44:47], v[134:137], v[206:209], v[44:47]
	v_mfma_f32_16x16x32_bf16 v[40:43], v[174:177], v[206:209], v[40:43]
	v_mfma_f32_16x16x32_bf16 v[28:31], v[134:137], v[214:217], v[28:31]
	v_mfma_f32_16x16x32_bf16 v[24:27], v[174:177], v[214:217], v[24:27]
	v_mfma_f32_16x16x32_bf16 v[12:15], v[134:137], v[222:225], v[12:15]
	v_mfma_f32_16x16x32_bf16 v[8:11], v[174:177], v[222:225], v[8:11]
	s_setprio 0
	s_setprio 1
	v_mfma_f32_16x16x32_bf16 v[52:55], v[178:181], v[194:197], v[52:55]
	v_mfma_f32_16x16x32_bf16 v[48:51], v[186:189], v[194:197], v[48:51]
	v_mfma_f32_16x16x32_bf16 v[36:39], v[178:181], v[202:205], v[36:39]
	v_mfma_f32_16x16x32_bf16 v[32:35], v[186:189], v[202:205], v[32:35]
	v_mfma_f32_16x16x32_bf16 v[20:23], v[178:181], v[210:213], v[20:23]
	v_mfma_f32_16x16x32_bf16 v[16:19], v[186:189], v[210:213], v[16:19]
	v_mfma_f32_16x16x32_bf16 v[4:7], v[178:181], v[218:221], v[4:7]
	v_mfma_f32_16x16x32_bf16 v[0:3], v[186:189], v[218:221], v[0:3]
	v_mfma_f32_16x16x32_bf16 v[52:55], v[182:185], v[198:201], v[52:55]
	v_mfma_f32_16x16x32_bf16 v[48:51], v[190:193], v[198:201], v[48:51]
	v_mfma_f32_16x16x32_bf16 v[36:39], v[182:185], v[206:209], v[36:39]
	v_mfma_f32_16x16x32_bf16 v[32:35], v[190:193], v[206:209], v[32:35]
	v_mfma_f32_16x16x32_bf16 v[20:23], v[182:185], v[214:217], v[20:23]
	v_mfma_f32_16x16x32_bf16 v[16:19], v[190:193], v[214:217], v[16:19]
	v_mfma_f32_16x16x32_bf16 v[4:7], v[182:185], v[222:225], v[4:7]
	v_mfma_f32_16x16x32_bf16 v[0:3], v[190:193], v[222:225], v[0:3]
	s_setprio 0
	s_barrier
; #define PG8_STAGE(bufoff, gbase, voff) do { _Pragma("unroll") for (int _i = 0; _i < 2; ++_i) \
;         __builtin_amdgcn_global_load_lds((const unsigned*)((const char*)(gbase) + (voff)[_i]), (LAS unsigned*)(lds + (bufoff) + ldsw + _i * 8192), 16, 0, 0); } while (0)
; #define PG8_LDA(dst, b, h) do { _Pragma("unroll") for (int m = 0; m < 4; ++m) _Pragma("unroll") for (int k = 0; k < 2; ++k) dst[m][k] = *(const LAS bf16x8*)(lds + PG8_SA(b, h) + aoff + m * 2048 + k * 1024); } while (0)
; #define PG8_LDB(dst, b, h) do { _Pragma("unroll") for (int n = 0; n < 2; ++n) _Pragma("unroll") for (int k = 0; k < 2; ++k) dst[n][k] = *(const LAS bf16x8*)(lds + PG8_SB(b, h) + boff + n * 2048 + k * 1024); } while (0)
; #define PG8_MMA(ai, bj, At, Bt) do { __builtin_amdgcn_s_setprio(1); _Pragma("unroll") for (int m = 0; m < 4; ++m) _Pragma("unroll") for (int n = 0; n < 2; ++n) _Pragma("unroll") for (int k = 0; k < 2; ++k) \
;         acc[ai][bj][m][n] = __builtin_amdgcn_mfma_f32_16x16x32_bf16(Bt[n][k], At[m][k], acc[ai][bj][m][n], 0, 0, 0); __builtin_amdgcn_s_setprio(0); } while (0)
; #define PG8_WAIT_V(n) asm volatile("s_waitcnt vmcnt(" #n ")" ::: "memory")
; #define PG8_WAIT_L(n) asm volatile("s_waitcnt lgkmcnt(" #n ")" ::: "memory")
; #define PG8_BAR __builtin_amdgcn_s_barrier()
; #define PG8_SCHED __builtin_amdgcn_sched_barrier(0)
; template <class Epi, class Sched, bool ALIGN_EPI>
; __device__ __forceinline__ void gemm_phase(LAS unsigned char* lds, const Gemm g, const Sched& S, const Epi& E, const int wid) {
;     ...
;             PG8_LDB(B0, 1, 0); PG8_LDB(B1, 1, 1); PG8_SCHED; PG8_LDA(At, 1, 0); PG8_STAGE(PG8_SA(0, 1), a2 + hstepA, voffA);
;             PG8_WAIT_V(8); PG8_WAIT_L(0); PG8_BAR; PG8_MMA(0, 0, At, B0); PG8_MMA(0, 1, At, B1); PG8_BAR; PG8_SCHED;
;             PG8_LDA(At, 1, 1); PG8_STAGE(PG8_SB(1, 0), b3, voffB); PG8_STAGE(PG8_SB(1, 1), b3 + hstepB, voffB); PG8_STAGE(PG8_SA(1, 0), a3, voffA);
;             PG8_WAIT_V(8); PG8_WAIT_L(0); PG8_BAR; PG8_MMA(1, 0, At, B0); PG8_MMA(1, 1, At, B1); PG8_BAR; PG8_SCHED;
;         }
	s_add_i32 s71, 0, 0x18000
	v_add_u32_e32 v138, s71, v160
	s_add_i32 s72, 0, 0x1c000
	ds_read_b128 v[130:133], v138
	ds_read_b128 v[134:137], v138 offset:1024
	ds_read_b128 v[170:173], v138 offset:2048
	ds_read_b128 v[174:177], v138 offset:3072
	v_add_u32_e32 v138, s72, v160
	ds_read_b128 v[178:181], v138
	ds_read_b128 v[182:185], v138 offset:1024
	ds_read_b128 v[186:189], v138 offset:2048
	ds_read_b128 v[190:193], v138 offset:3072
	s_add_u32 s38, s60, 0x4000
	s_addc_u32 s39, s61, 0
	s_mov_b32 m0, s43
	ds_read_b128 v[194:197], v166 offset:32768
	ds_read_b128 v[198:201], v166 offset:33792
	ds_read_b128 v[202:205], v166 offset:34816
	ds_read_b128 v[206:209], v166 offset:35840
	ds_read_b128 v[210:213], v166 offset:36864
	ds_read_b128 v[214:217], v166 offset:37888
	ds_read_b128 v[218:221], v166 offset:38912
	ds_read_b128 v[222:225], v166 offset:39936
	global_load_lds_dwordx4 v146, s[38:39]
	s_mov_b32 m0, s44
	s_nop 0
	global_load_lds_dwordx4 v142, s[38:39]
	s_waitcnt vmcnt(8)
	s_waitcnt lgkmcnt(0)
	s_barrier
	s_setprio 1
	s_waitcnt lgkmcnt(0)
	v_mfma_f32_16x16x32_bf16 v[124:127], v[130:133], v[194:197], v[124:127]
	v_mfma_f32_16x16x32_bf16 v[120:123], v[170:173], v[194:197], v[120:123]
	v_mfma_f32_16x16x32_bf16 v[108:111], v[130:133], v[202:205], v[108:111]
	v_mfma_f32_16x16x32_bf16 v[104:107], v[170:173], v[202:205], v[104:107]
	v_mfma_f32_16x16x32_bf16 v[92:95], v[130:133], v[210:213], v[92:95]
	v_mfma_f32_16x16x32_bf16 v[88:91], v[170:173], v[210:213], v[88:91]
	v_mfma_f32_16x16x32_bf16 v[76:79], v[130:133], v[218:221], v[76:79]
	v_mfma_f32_16x16x32_bf16 v[72:75], v[170:173], v[218:221], v[72:75]
	v_mfma_f32_16x16x32_bf16 v[124:127], v[134:137], v[198:201], v[124:127]
	v_mfma_f32_16x16x32_bf16 v[120:123], v[174:177], v[198:201], v[120:123]
	v_mfma_f32_16x16x32_bf16 v[108:111], v[134:137], v[206:209], v[108:111]
	v_mfma_f32_16x16x32_bf16 v[104:107], v[174:177], v[206:209], v[104:107]
	v_mfma_f32_16x16x32_bf16 v[92:95], v[134:137], v[214:217], v[92:95]
	v_mfma_f32_16x16x32_bf16 v[88:91], v[174:177], v[214:217], v[88:91]
	v_mfma_f32_16x16x32_bf16 v[76:79], v[134:137], v[222:225], v[76:79]
	v_mfma_f32_16x16x32_bf16 v[72:75], v[174:177], v[222:225], v[72:75]
	s_setprio 0
	s_setprio 1
	v_mfma_f32_16x16x32_bf16 v[116:119], v[178:181], v[194:197], v[116:119]
	v_mfma_f32_16x16x32_bf16 v[112:115], v[186:189], v[194:197], v[112:115]
	v_mfma_f32_16x16x32_bf16 v[100:103], v[178:181], v[202:205], v[100:103]
	v_mfma_f32_16x16x32_bf16 v[96:99], v[186:189], v[202:205], v[96:99]
	v_mfma_f32_16x16x32_bf16 v[84:87], v[178:181], v[210:213], v[84:87]
	v_mfma_f32_16x16x32_bf16 v[80:83], v[186:189], v[210:213], v[80:83]
	v_mfma_f32_16x16x32_bf16 v[68:71], v[178:181], v[218:221], v[68:71]
	v_mfma_f32_16x16x32_bf16 v[64:67], v[186:189], v[218:221], v[64:67]
	v_mfma_f32_16x16x32_bf16 v[116:119], v[182:185], v[198:201], v[116:119]
	v_mfma_f32_16x16x32_bf16 v[112:115], v[190:193], v[198:201], v[112:115]
	v_mfma_f32_16x16x32_bf16 v[100:103], v[182:185], v[206:209], v[100:103]
	v_mfma_f32_16x16x32_bf16 v[96:99], v[190:193], v[206:209], v[96:99]
	v_mfma_f32_16x16x32_bf16 v[84:87], v[182:185], v[214:217], v[84:87]
	v_mfma_f32_16x16x32_bf16 v[80:83], v[190:193], v[214:217], v[80:83]
	v_mfma_f32_16x16x32_bf16 v[68:71], v[182:185], v[222:225], v[68:71]
	v_mfma_f32_16x16x32_bf16 v[64:67], v[190:193], v[222:225], v[64:67]
	s_setprio 0
	s_barrier
	s_add_u32 s38, s58, 0x8000
	s_addc_u32 s39, s59, 0
	s_add_i32 s60, s71, s3
	s_mov_b32 m0, s60
	ds_read_b128 v[194:197], v166 offset:49152
	ds_read_b128 v[198:201], v166 offset:50176
	ds_read_b128 v[202:205], v166 offset:51200
	ds_read_b128 v[206:209], v166 offset:52224
	ds_read_b128 v[210:213], v166 offset:53248
	ds_read_b128 v[214:217], v166 offset:54272
	ds_read_b128 v[218:221], v166 offset:55296
	ds_read_b128 v[222:225], v166 offset:56320
	global_load_lds_dwordx4 v144, s[38:39]
	s_add_i32 m0, s60, 0x2000
	s_nop 0
	global_load_lds_dwordx4 v140, s[38:39]
	s_add_u32 s38, s58, 0x9000
	s_addc_u32 s39, s59, 0
	s_add_i32 s58, s72, s3
	s_mov_b32 m0, s58
	s_nop 0
	global_load_lds_dwordx4 v144, s[38:39]
	s_add_i32 m0, s58, 0x2000
	s_nop 0
	global_load_lds_dwordx4 v140, s[38:39]
	s_mov_b32 m0, s54
	s_nop 0
	global_load_lds_dwordx4 v146, s[56:57]
	s_mov_b32 m0, s55
	s_nop 0
	global_load_lds_dwordx4 v142, s[56:57]
	s_waitcnt vmcnt(8)
	s_waitcnt lgkmcnt(0)
	s_barrier
	s_setprio 1
	s_waitcnt lgkmcnt(0)
	v_mfma_f32_16x16x32_bf16 v[60:63], v[130:133], v[194:197], v[60:63]
	v_mfma_f32_16x16x32_bf16 v[56:59], v[170:173], v[194:197], v[56:59]
	v_mfma_f32_16x16x32_bf16 v[44:47], v[130:133], v[202:205], v[44:47]
	v_mfma_f32_16x16x32_bf16 v[40:43], v[170:173], v[202:205], v[40:43]
	v_mfma_f32_16x16x32_bf16 v[28:31], v[130:133], v[210:213], v[28:31]
	v_mfma_f32_16x16x32_bf16 v[24:27], v[170:173], v[210:213], v[24:27]
	v_mfma_f32_16x16x32_bf16 v[12:15], v[130:133], v[218:221], v[12:15]
	v_mfma_f32_16x16x32_bf16 v[8:11], v[170:173], v[218:221], v[8:11]
	v_mfma_f32_16x16x32_bf16 v[60:63], v[134:137], v[198:201], v[60:63]
	v_mfma_f32_16x16x32_bf16 v[56:59], v[174:177], v[198:201], v[56:59]
	v_mfma_f32_16x16x32_bf16 v[44:47], v[134:137], v[206:209], v[44:47]
	v_mfma_f32_16x16x32_bf16 v[40:43], v[174:177], v[206:209], v[40:43]
	v_mfma_f32_16x16x32_bf16 v[28:31], v[134:137], v[214:217], v[28:31]
	v_mfma_f32_16x16x32_bf16 v[24:27], v[174:177], v[214:217], v[24:27]
	v_mfma_f32_16x16x32_bf16 v[12:15], v[134:137], v[222:225], v[12:15]
	v_mfma_f32_16x16x32_bf16 v[8:11], v[174:177], v[222:225], v[8:11]
	s_setprio 0
	s_setprio 1
	v_mfma_f32_16x16x32_bf16 v[52:55], v[178:181], v[194:197], v[52:55]
	v_mfma_f32_16x16x32_bf16 v[48:51], v[186:189], v[194:197], v[48:51]
	v_mfma_f32_16x16x32_bf16 v[36:39], v[178:181], v[202:205], v[36:39]
	v_mfma_f32_16x16x32_bf16 v[32:35], v[186:189], v[202:205], v[32:35]
	v_mfma_f32_16x16x32_bf16 v[20:23], v[178:181], v[210:213], v[20:23]
	v_mfma_f32_16x16x32_bf16 v[16:19], v[186:189], v[210:213], v[16:19]
	v_mfma_f32_16x16x32_bf16 v[4:7], v[178:181], v[218:221], v[4:7]
	v_mfma_f32_16x16x32_bf16 v[0:3], v[186:189], v[218:221], v[0:3]
	v_mfma_f32_16x16x32_bf16 v[52:55], v[182:185], v[198:201], v[52:55]
	v_mfma_f32_16x16x32_bf16 v[48:51], v[190:193], v[198:201], v[48:51]
	v_mfma_f32_16x16x32_bf16 v[36:39], v[182:185], v[206:209], v[36:39]
	v_mfma_f32_16x16x32_bf16 v[32:35], v[190:193], v[206:209], v[32:35]
	v_mfma_f32_16x16x32_bf16 v[20:23], v[182:185], v[214:217], v[20:23]
	v_mfma_f32_16x16x32_bf16 v[16:19], v[190:193], v[214:217], v[16:19]
	v_mfma_f32_16x16x32_bf16 v[4:7], v[182:185], v[222:225], v[4:7]
	v_mfma_f32_16x16x32_bf16 v[0:3], v[190:193], v[222:225], v[0:3]
	s_setprio 0
	s_barrier
	s_add_i32 s70, s70, 2
	s_add_u32 s16, s16, 0x10000
	s_addc_u32 s17, s17, 0
	s_add_u32 s68, s68, 0x10000
	s_addc_u32 s69, s69, 0
	s_cmp_gt_u32 s70, 61
	s_cbranch_scc1 .LBB0_1571

; #define PG8_STAGE(bufoff, gbase, voff) do { _Pragma("unroll") for (int _i = 0; _i < 2; ++_i) \
;         __builtin_amdgcn_global_load_lds((const unsigned*)((const char*)(gbase) + (voff)[_i]), (LAS unsigned*)(lds + (bufoff) + ldsw + _i * 8192), 16, 0, 0); } while (0)
; #define PG8_LDA(dst, b, h) do { _Pragma("unroll") for (int m = 0; m < 4; ++m) _Pragma("unroll") for (int k = 0; k < 2; ++k) dst[m][k] = *(const LAS bf16x8*)(lds + PG8_SA(b, h) + aoff + m * 2048 + k * 1024); } while (0)
; #define PG8_LDB(dst, b, h) do { _Pragma("unroll") for (int n = 0; n < 2; ++n) _Pragma("unroll") for (int k = 0; k < 2; ++k) dst[n][k] = *(const LAS bf16x8*)(lds + PG8_SB(b, h) + boff + n * 2048 + k * 1024); } while (0)
; #define PG8_MMA(ai, bj, At, Bt) do { __builtin_amdgcn_s_setprio(1); _Pragma("unroll") for (int m = 0; m < 4; ++m) _Pragma("unroll") for (int n = 0; n < 2; ++n) _Pragma("unroll") for (int k = 0; k < 2; ++k) \
;         acc[ai][bj][m][n] = __builtin_amdgcn_mfma_f32_16x16x32_bf16(Bt[n][k], At[m][k], acc[ai][bj][m][n], 0, 0, 0); __builtin_amdgcn_s_setprio(0); } while (0)
; #define PG8_WAIT_V(n) asm volatile("s_waitcnt vmcnt(" #n ")" ::: "memory")
; #define PG8_WAIT_L(n) asm volatile("s_waitcnt lgkmcnt(" #n ")" ::: "memory")
; #define PG8_BAR __builtin_amdgcn_s_barrier()
; #define PG8_SCHED __builtin_amdgcn_sched_barrier(0)
; template <class Epi, class Sched, bool ALIGN_EPI>
; __device__ __forceinline__ void gemm_phase(LAS unsigned char* lds, const Gemm g, const Sched& S, const Epi& E, const int wid) {
;     ...
;             const char* a1 = cA + (size_t)(t + 1) * kstepA;
;             const char* a2 = last ? nA : cA + (size_t)(t + 2) * kstepA; const char* b2 = last ? nB : cB + (size_t)(t + 2) * kstep;
;             const char* a3 = a2 + kstepA; const char* b3 = b2 + kstep;
;             PG8_LDB(B0, 0, 0); PG8_LDB(B1, 0, 1); PG8_SCHED; PG8_LDA(At, 0, 0); PG8_STAGE(PG8_SA(1, 1), a1 + hstepA, voffA);
;             PG8_WAIT_V(8); PG8_WAIT_L(0); PG8_BAR; PG8_MMA(0, 0, At, B0); PG8_MMA(0, 1, At, B1); PG8_BAR; PG8_SCHED;
;             PG8_LDA(At, 0, 1); PG8_STAGE(PG8_SB(0, 0), b2, voffB); PG8_STAGE(PG8_SB(0, 1), b2 + hstepB, voffB); PG8_STAGE(PG8_SA(0, 0), a2, voffA);
;             PG8_WAIT_V(8); PG8_WAIT_L(0); PG8_BAR; PG8_MMA(1, 0, At, B0); PG8_MMA(1, 1, At, B1); PG8_BAR; PG8_SCHED;
.LBB0_1672:
	ds_read_b128 v[72:75], v202
	ds_read_b128 v[76:79], v202 offset:1024
	ds_read_b128 v[136:139], v202 offset:2048
	ds_read_b128 v[140:143], v202 offset:3072
	ds_read_b128 v[144:147], v203
	ds_read_b128 v[148:151], v203 offset:1024
	ds_read_b128 v[152:155], v203 offset:2048
	ds_read_b128 v[178:181], v203 offset:3072
	s_add_u32 s38, s16, 0x4000
	s_addc_u32 s60, s17, 0
	s_cmpk_eq_i32 s78, 0xfc
	s_cselect_b32 s64, s51, s38
	s_cselect_b32 s65, s35, s60
	s_cselect_b32 s62, s57, s59
	s_cselect_b32 s63, s49, s77
	s_add_u32 s60, s64, 0x8000
	s_addc_u32 s61, s65, 0
	s_add_i32 m0, s45, 0xc000
	ds_read_b128 v[182:185], v204
	ds_read_b128 v[186:189], v204 offset:1024
	ds_read_b128 v[190:193], v204 offset:2048
	ds_read_b128 v[194:197], v204 offset:3072
	ds_read_b128 v[208:211], v204 offset:4096
	ds_read_b128 v[212:215], v204 offset:5120
	ds_read_b128 v[216:219], v204 offset:6144
	ds_read_b128 v[220:223], v204 offset:7168
	global_load_lds_dwordx4 v168, s[16:17]
	s_add_i32 m0, s45, 0xe000
	s_nop 0
	global_load_lds_dwordx4 v170, s[16:17]
	s_waitcnt vmcnt(8)
	s_waitcnt lgkmcnt(0)
	s_barrier
	s_setprio 1
	s_waitcnt lgkmcnt(0)
	v_mfma_f32_16x16x32_bf16 v[132:135], v[72:75], v[182:185], v[132:135]
	v_mfma_f32_16x16x32_bf16 v[128:131], v[136:139], v[182:185], v[128:131]
	v_mfma_f32_16x16x32_bf16 v[116:119], v[72:75], v[190:193], v[116:119]
	v_mfma_f32_16x16x32_bf16 v[112:115], v[136:139], v[190:193], v[112:115]
	v_mfma_f32_16x16x32_bf16 v[100:103], v[72:75], v[208:211], v[100:103]
	v_mfma_f32_16x16x32_bf16 v[96:99], v[136:139], v[208:211], v[96:99]
	v_mfma_f32_16x16x32_bf16 v[84:87], v[72:75], v[216:219], v[84:87]
	v_mfma_f32_16x16x32_bf16 v[80:83], v[136:139], v[216:219], v[80:83]
	v_mfma_f32_16x16x32_bf16 v[132:135], v[76:79], v[186:189], v[132:135]
	v_mfma_f32_16x16x32_bf16 v[128:131], v[140:143], v[186:189], v[128:131]
	v_mfma_f32_16x16x32_bf16 v[116:119], v[76:79], v[194:197], v[116:119]
	v_mfma_f32_16x16x32_bf16 v[112:115], v[140:143], v[194:197], v[112:115]
	v_mfma_f32_16x16x32_bf16 v[100:103], v[76:79], v[212:215], v[100:103]
	v_mfma_f32_16x16x32_bf16 v[96:99], v[140:143], v[212:215], v[96:99]
	v_mfma_f32_16x16x32_bf16 v[84:87], v[76:79], v[220:223], v[84:87]
	v_mfma_f32_16x16x32_bf16 v[80:83], v[140:143], v[220:223], v[80:83]
	s_setprio 0
	s_setprio 1
	v_mfma_f32_16x16x32_bf16 v[124:127], v[144:147], v[182:185], v[124:127]
	v_mfma_f32_16x16x32_bf16 v[120:123], v[152:155], v[182:185], v[120:123]
	v_mfma_f32_16x16x32_bf16 v[108:111], v[144:147], v[190:193], v[108:111]
	v_mfma_f32_16x16x32_bf16 v[104:107], v[152:155], v[190:193], v[104:107]
	v_mfma_f32_16x16x32_bf16 v[92:95], v[144:147], v[208:211], v[92:95]
	v_mfma_f32_16x16x32_bf16 v[88:91], v[152:155], v[208:211], v[88:91]
	v_mfma_f32_16x16x32_bf16 v[68:71], v[144:147], v[216:219], v[68:71]
	v_mfma_f32_16x16x32_bf16 v[64:67], v[152:155], v[216:219], v[64:67]
	v_mfma_f32_16x16x32_bf16 v[124:127], v[148:151], v[186:189], v[124:127]
	v_mfma_f32_16x16x32_bf16 v[120:123], v[178:181], v[186:189], v[120:123]
	v_mfma_f32_16x16x32_bf16 v[108:111], v[148:151], v[194:197], v[108:111]
	v_mfma_f32_16x16x32_bf16 v[104:107], v[178:181], v[194:197], v[104:107]
	v_mfma_f32_16x16x32_bf16 v[92:95], v[148:151], v[212:215], v[92:95]
	v_mfma_f32_16x16x32_bf16 v[88:91], v[178:181], v[212:215], v[88:91]
	v_mfma_f32_16x16x32_bf16 v[68:71], v[148:151], v[220:223], v[68:71]
	v_mfma_f32_16x16x32_bf16 v[64:67], v[178:181], v[220:223], v[64:67]
	s_setprio 0
	s_barrier
	s_add_i32 s38, s72, s3
	s_mov_b32 m0, s38
	ds_read_b128 v[182:185], v204 offset:16384
	ds_read_b128 v[186:189], v204 offset:17408
	ds_read_b128 v[190:193], v204 offset:18432
	ds_read_b128 v[194:197], v204 offset:19456
	ds_read_b128 v[208:211], v204 offset:20480
	ds_read_b128 v[212:215], v204 offset:21504
	ds_read_b128 v[216:219], v204 offset:22528
	ds_read_b128 v[220:223], v204 offset:23552
	global_load_lds_dwordx4 v158, s[62:63]
	s_add_i32 m0, s38, 0x2000
	s_add_u32 s80, s62, 0x1000
	s_addc_u32 s81, s63, 0
	s_add_i32 s38, s73, s3
	global_load_lds_dwordx4 v162, s[62:63]
	s_mov_b32 m0, s38
	s_nop 0
	global_load_lds_dwordx4 v158, s[80:81]
	s_add_i32 m0, s38, 0x2000
	s_nop 0
	global_load_lds_dwordx4 v162, s[80:81]
	s_mov_b32 m0, s45
	s_nop 0
	global_load_lds_dwordx4 v156, s[64:65]
	s_mov_b32 m0, s47
	s_nop 0
	global_load_lds_dwordx4 v160, s[64:65]
	s_waitcnt vmcnt(8)
	s_waitcnt lgkmcnt(0)
	s_barrier
	s_setprio 1
	s_waitcnt lgkmcnt(0)
	v_mfma_f32_16x16x32_bf16 v[60:63], v[72:75], v[182:185], v[60:63]
	v_mfma_f32_16x16x32_bf16 v[56:59], v[136:139], v[182:185], v[56:59]
	v_mfma_f32_16x16x32_bf16 v[44:47], v[72:75], v[190:193], v[44:47]
	v_mfma_f32_16x16x32_bf16 v[40:43], v[136:139], v[190:193], v[40:43]
	v_mfma_f32_16x16x32_bf16 v[28:31], v[72:75], v[208:211], v[28:31]
	v_mfma_f32_16x16x32_bf16 v[24:27], v[136:139], v[208:211], v[24:27]
	v_mfma_f32_16x16x32_bf16 v[12:15], v[72:75], v[216:219], v[12:15]
	v_mfma_f32_16x16x32_bf16 v[8:11], v[136:139], v[216:219], v[8:11]
	v_mfma_f32_16x16x32_bf16 v[60:63], v[76:79], v[186:189], v[60:63]
	v_mfma_f32_16x16x32_bf16 v[56:59], v[140:143], v[186:189], v[56:59]
	v_mfma_f32_16x16x32_bf16 v[44:47], v[76:79], v[194:197], v[44:47]
	v_mfma_f32_16x16x32_bf16 v[40:43], v[140:143], v[194:197], v[40:43]
	v_mfma_f32_16x16x32_bf16 v[28:31], v[76:79], v[212:215], v[28:31]
	v_mfma_f32_16x16x32_bf16 v[24:27], v[140:143], v[212:215], v[24:27]
	v_mfma_f32_16x16x32_bf16 v[12:15], v[76:79], v[220:223], v[12:15]
	v_mfma_f32_16x16x32_bf16 v[8:11], v[140:143], v[220:223], v[8:11]
	s_setprio 0
	s_setprio 1
	v_mfma_f32_16x16x32_bf16 v[52:55], v[144:147], v[182:185], v[52:55]
	v_mfma_f32_16x16x32_bf16 v[48:51], v[152:155], v[182:185], v[48:51]
	v_mfma_f32_16x16x32_bf16 v[36:39], v[144:147], v[190:193], v[36:39]
	v_mfma_f32_16x16x32_bf16 v[32:35], v[152:155], v[190:193], v[32:35]
	v_mfma_f32_16x16x32_bf16 v[20:23], v[144:147], v[208:211], v[20:23]
	v_mfma_f32_16x16x32_bf16 v[16:19], v[152:155], v[208:211], v[16:19]
	v_mfma_f32_16x16x32_bf16 v[4:7], v[144:147], v[216:219], v[4:7]
	v_mfma_f32_16x16x32_bf16 v[0:3], v[152:155], v[216:219], v[0:3]
	v_mfma_f32_16x16x32_bf16 v[52:55], v[148:151], v[186:189], v[52:55]
	v_mfma_f32_16x16x32_bf16 v[48:51], v[178:181], v[186:189], v[48:51]
	v_mfma_f32_16x16x32_bf16 v[36:39], v[148:151], v[194:197], v[36:39]
	v_mfma_f32_16x16x32_bf16 v[32:35], v[178:181], v[194:197], v[32:35]
	v_mfma_f32_16x16x32_bf16 v[20:23], v[148:151], v[212:215], v[20:23]
	v_mfma_f32_16x16x32_bf16 v[16:19], v[178:181], v[212:215], v[16:19]
	v_mfma_f32_16x16x32_bf16 v[4:7], v[148:151], v[220:223], v[4:7]
	v_mfma_f32_16x16x32_bf16 v[0:3], v[178:181], v[220:223], v[0:3]
	s_setprio 0
	s_barrier
; #define PG8_STAGE(bufoff, gbase, voff) do { _Pragma("unroll") for (int _i = 0; _i < 2; ++_i) \
;         __builtin_amdgcn_global_load_lds((const unsigned*)((const char*)(gbase) + (voff)[_i]), (LAS unsigned*)(lds + (bufoff) + ldsw + _i * 8192), 16, 0, 0); } while (0)
; #define PG8_LDA(dst, b, h) do { _Pragma("unroll") for (int m = 0; m < 4; ++m) _Pragma("unroll") for (int k = 0; k < 2; ++k) dst[m][k] = *(const LAS bf16x8*)(lds + PG8_SA(b, h) + aoff + m * 2048 + k * 1024); } while (0)
; #define PG8_LDB(dst, b, h) do { _Pragma("unroll") for (int n = 0; n < 2; ++n) _Pragma("unroll") for (int k = 0; k < 2; ++k) dst[n][k] = *(const LAS bf16x8*)(lds + PG8_SB(b, h) + boff + n * 2048 + k * 1024); } while (0)
; #define PG8_MMA(ai, bj, At, Bt) do { __builtin_amdgcn_s_setprio(1); _Pragma("unroll") for (int m = 0; m < 4; ++m) _Pragma("unroll") for (int n = 0; n < 2; ++n) _Pragma("unroll") for (int k = 0; k < 2; ++k) \
;         acc[ai][bj][m][n] = __builtin_amdgcn_mfma_f32_16x16x32_bf16(Bt[n][k], At[m][k], acc[ai][bj][m][n], 0, 0, 0); __builtin_amdgcn_s_setprio(0); } while (0)
; #define PG8_WAIT_V(n) asm volatile("s_waitcnt vmcnt(" #n ")" ::: "memory")
; #define PG8_WAIT_L(n) asm volatile("s_waitcnt lgkmcnt(" #n ")" ::: "memory")
; #define PG8_BAR __builtin_amdgcn_s_barrier()
; #define PG8_SCHED __builtin_amdgcn_sched_barrier(0)
; template <class Epi, class Sched, bool ALIGN_EPI>
; __device__ __forceinline__ void gemm_phase(LAS unsigned char* lds, const Gemm g, const Sched& S, const Epi& E, const int wid) {
;     ...
;             PG8_LDB(B0, 1, 0); PG8_LDB(B1, 1, 1); PG8_SCHED; PG8_LDA(At, 1, 0); PG8_STAGE(PG8_SA(0, 1), a2 + hstepA, voffA);
;             PG8_WAIT_V(8); PG8_WAIT_L(0); PG8_BAR; PG8_MMA(0, 0, At, B0); PG8_MMA(0, 1, At, B1); PG8_BAR; PG8_SCHED;
;             PG8_LDA(At, 1, 1); PG8_STAGE(PG8_SB(1, 0), b3, voffB); PG8_STAGE(PG8_SB(1, 1), b3 + hstepB, voffB); PG8_STAGE(PG8_SA(1, 0), a3, voffA);
;             PG8_WAIT_V(8); PG8_WAIT_L(0); PG8_BAR; PG8_MMA(1, 0, At, B0); PG8_MMA(1, 1, At, B1); PG8_BAR; PG8_SCHED;
;         }
	s_add_i32 s38, 0, 0x18000
	s_add_i32 s79, 0, 0x1c000
	v_add_u32_e32 v140, s38, v198
	v_add_u32_e32 v164, s79, v198
	ds_read_b128 v[72:75], v140
	ds_read_b128 v[76:79], v140 offset:1024
	ds_read_b128 v[136:139], v140 offset:2048
	ds_read_b128 v[140:143], v140 offset:3072
	ds_read_b128 v[144:147], v164
	ds_read_b128 v[148:151], v164 offset:1024
	ds_read_b128 v[152:155], v164 offset:2048
	ds_read_b128 v[178:181], v164 offset:3072
	s_add_u32 s64, s64, 0x4000
	s_addc_u32 s65, s65, 0
	s_mov_b32 m0, s66
	ds_read_b128 v[182:185], v204 offset:32768
	ds_read_b128 v[186:189], v204 offset:33792
	ds_read_b128 v[190:193], v204 offset:34816
	ds_read_b128 v[194:197], v204 offset:35840
	ds_read_b128 v[208:211], v204 offset:36864
	ds_read_b128 v[212:215], v204 offset:37888
	ds_read_b128 v[216:219], v204 offset:38912
	ds_read_b128 v[220:223], v204 offset:39936
	global_load_lds_dwordx4 v156, s[64:65]
	s_mov_b32 m0, s67
	s_nop 0
	global_load_lds_dwordx4 v160, s[64:65]
	s_waitcnt vmcnt(8)
	s_waitcnt lgkmcnt(0)
	s_barrier
	s_setprio 1
	s_waitcnt lgkmcnt(0)
	v_mfma_f32_16x16x32_bf16 v[132:135], v[72:75], v[182:185], v[132:135]
	v_mfma_f32_16x16x32_bf16 v[128:131], v[136:139], v[182:185], v[128:131]
	v_mfma_f32_16x16x32_bf16 v[116:119], v[72:75], v[190:193], v[116:119]
	v_mfma_f32_16x16x32_bf16 v[112:115], v[136:139], v[190:193], v[112:115]
	v_mfma_f32_16x16x32_bf16 v[100:103], v[72:75], v[208:211], v[100:103]
	v_mfma_f32_16x16x32_bf16 v[96:99], v[136:139], v[208:211], v[96:99]
	v_mfma_f32_16x16x32_bf16 v[84:87], v[72:75], v[216:219], v[84:87]
	v_mfma_f32_16x16x32_bf16 v[80:83], v[136:139], v[216:219], v[80:83]
	v_mfma_f32_16x16x32_bf16 v[132:135], v[76:79], v[186:189], v[132:135]
	v_mfma_f32_16x16x32_bf16 v[128:131], v[140:143], v[186:189], v[128:131]
	v_mfma_f32_16x16x32_bf16 v[116:119], v[76:79], v[194:197], v[116:119]
	v_mfma_f32_16x16x32_bf16 v[112:115], v[140:143], v[194:197], v[112:115]
	v_mfma_f32_16x16x32_bf16 v[100:103], v[76:79], v[212:215], v[100:103]
	v_mfma_f32_16x16x32_bf16 v[96:99], v[140:143], v[212:215], v[96:99]
	v_mfma_f32_16x16x32_bf16 v[84:87], v[76:79], v[220:223], v[84:87]
	v_mfma_f32_16x16x32_bf16 v[80:83], v[140:143], v[220:223], v[80:83]
	s_setprio 0
	s_setprio 1
	v_mfma_f32_16x16x32_bf16 v[124:127], v[144:147], v[182:185], v[124:127]
	v_mfma_f32_16x16x32_bf16 v[120:123], v[152:155], v[182:185], v[120:123]
	v_mfma_f32_16x16x32_bf16 v[108:111], v[144:147], v[190:193], v[108:111]
	v_mfma_f32_16x16x32_bf16 v[104:107], v[152:155], v[190:193], v[104:107]
	v_mfma_f32_16x16x32_bf16 v[92:95], v[144:147], v[208:211], v[92:95]
	v_mfma_f32_16x16x32_bf16 v[88:91], v[152:155], v[208:211], v[88:91]
	v_mfma_f32_16x16x32_bf16 v[68:71], v[144:147], v[216:219], v[68:71]
	v_mfma_f32_16x16x32_bf16 v[64:67], v[152:155], v[216:219], v[64:67]
	v_mfma_f32_16x16x32_bf16 v[124:127], v[148:151], v[186:189], v[124:127]
	v_mfma_f32_16x16x32_bf16 v[120:123], v[178:181], v[186:189], v[120:123]
	v_mfma_f32_16x16x32_bf16 v[108:111], v[148:151], v[194:197], v[108:111]
	v_mfma_f32_16x16x32_bf16 v[104:107], v[178:181], v[194:197], v[104:107]
	v_mfma_f32_16x16x32_bf16 v[92:95], v[148:151], v[212:215], v[92:95]
	v_mfma_f32_16x16x32_bf16 v[88:91], v[178:181], v[212:215], v[88:91]
	v_mfma_f32_16x16x32_bf16 v[68:71], v[148:151], v[220:223], v[68:71]
	v_mfma_f32_16x16x32_bf16 v[64:67], v[178:181], v[220:223], v[64:67]
	s_setprio 0
	s_barrier
	s_add_u32 s64, s62, 0x8000
	s_addc_u32 s65, s63, 0
	s_add_i32 s38, s38, s3
	s_mov_b32 m0, s38
	ds_read_b128 v[182:185], v204 offset:49152
	ds_read_b128 v[186:189], v204 offset:50176
	ds_read_b128 v[190:193], v204 offset:51200
	ds_read_b128 v[194:197], v204 offset:52224
	ds_read_b128 v[208:211], v204 offset:53248
	ds_read_b128 v[212:215], v204 offset:54272
	ds_read_b128 v[216:219], v204 offset:55296
	ds_read_b128 v[220:223], v204 offset:56320
	global_load_lds_dwordx4 v158, s[64:65]
	s_add_i32 m0, s38, 0x2000
	s_add_u32 s62, s62, 0x9000
	s_addc_u32 s63, s63, 0
	s_add_i32 s38, s79, s3
	global_load_lds_dwordx4 v162, s[64:65]
	s_mov_b32 m0, s38
	s_nop 0
	global_load_lds_dwordx4 v158, s[62:63]
	s_add_i32 m0, s38, 0x2000
	s_nop 0
	global_load_lds_dwordx4 v162, s[62:63]
	s_mov_b32 m0, s69
	s_nop 0
	global_load_lds_dwordx4 v156, s[60:61]
	s_mov_b32 m0, s70
	s_nop 0
	global_load_lds_dwordx4 v160, s[60:61]
	s_waitcnt vmcnt(8)
	s_waitcnt lgkmcnt(0)
	s_barrier
	s_setprio 1
	s_waitcnt lgkmcnt(0)
	v_mfma_f32_16x16x32_bf16 v[60:63], v[72:75], v[182:185], v[60:63]
	v_mfma_f32_16x16x32_bf16 v[56:59], v[136:139], v[182:185], v[56:59]
	v_mfma_f32_16x16x32_bf16 v[44:47], v[72:75], v[190:193], v[44:47]
	v_mfma_f32_16x16x32_bf16 v[40:43], v[136:139], v[190:193], v[40:43]
	v_mfma_f32_16x16x32_bf16 v[28:31], v[72:75], v[208:211], v[28:31]
	v_mfma_f32_16x16x32_bf16 v[24:27], v[136:139], v[208:211], v[24:27]
	v_mfma_f32_16x16x32_bf16 v[12:15], v[72:75], v[216:219], v[12:15]
	v_mfma_f32_16x16x32_bf16 v[8:11], v[136:139], v[216:219], v[8:11]
	v_mfma_f32_16x16x32_bf16 v[60:63], v[76:79], v[186:189], v[60:63]
	v_mfma_f32_16x16x32_bf16 v[56:59], v[140:143], v[186:189], v[56:59]
	v_mfma_f32_16x16x32_bf16 v[44:47], v[76:79], v[194:197], v[44:47]
	v_mfma_f32_16x16x32_bf16 v[40:43], v[140:143], v[194:197], v[40:43]
	v_mfma_f32_16x16x32_bf16 v[28:31], v[76:79], v[212:215], v[28:31]
	v_mfma_f32_16x16x32_bf16 v[24:27], v[140:143], v[212:215], v[24:27]
	v_mfma_f32_16x16x32_bf16 v[12:15], v[76:79], v[220:223], v[12:15]
	v_mfma_f32_16x16x32_bf16 v[8:11], v[140:143], v[220:223], v[8:11]
	s_setprio 0
	s_setprio 1
	v_mfma_f32_16x16x32_bf16 v[52:55], v[144:147], v[182:185], v[52:55]
	v_mfma_f32_16x16x32_bf16 v[48:51], v[152:155], v[182:185], v[48:51]
	v_mfma_f32_16x16x32_bf16 v[36:39], v[144:147], v[190:193], v[36:39]
	v_mfma_f32_16x16x32_bf16 v[32:35], v[152:155], v[190:193], v[32:35]
	v_mfma_f32_16x16x32_bf16 v[20:23], v[144:147], v[208:211], v[20:23]
	v_mfma_f32_16x16x32_bf16 v[16:19], v[152:155], v[208:211], v[16:19]
	v_mfma_f32_16x16x32_bf16 v[4:7], v[144:147], v[216:219], v[4:7]
	v_mfma_f32_16x16x32_bf16 v[0:3], v[152:155], v[216:219], v[0:3]
	v_mfma_f32_16x16x32_bf16 v[52:55], v[148:151], v[186:189], v[52:55]
	v_mfma_f32_16x16x32_bf16 v[48:51], v[178:181], v[186:189], v[48:51]
	v_mfma_f32_16x16x32_bf16 v[36:39], v[148:151], v[194:197], v[36:39]
	v_mfma_f32_16x16x32_bf16 v[32:35], v[178:181], v[194:197], v[32:35]
	v_mfma_f32_16x16x32_bf16 v[20:23], v[148:151], v[212:215], v[20:23]
	v_mfma_f32_16x16x32_bf16 v[16:19], v[178:181], v[212:215], v[16:19]
	v_mfma_f32_16x16x32_bf16 v[4:7], v[148:151], v[220:223], v[4:7]
	v_mfma_f32_16x16x32_bf16 v[0:3], v[178:181], v[220:223], v[0:3]
	s_setprio 0
	s_barrier
	s_add_i32 s78, s78, 2
	s_add_u32 s59, s59, 0x10000
	s_addc_u32 s77, s77, 0
	s_add_u32 s16, s16, 0x10000
	s_addc_u32 s17, s17, 0
	s_cmpk_gt_u32 s78, 0xfd
	s_cbranch_scc0 .LBB0_1672
	s_and_b64 vcc, exec, s[28:29]
	s_cbranch_vccz .LBB0_1675
	s_barrier
